# static s_setprio 1 for waves 4-7 only, all per-block setprio flips deleted (on top of stagger0+S1+PTfill)
# baseline (speedup 1.0000x reference)
.LBB0_8:
	s_or_b64 exec, exec, s[2:3]
	s_load_dwordx16 s[72:87], s[0:1], 0x0
	s_load_dwordx16 s[12:27], s[0:1], 0x40
	s_lshr_b32 s0, s8, 6
	s_cmp_ge_u32 s0, 4
	s_cbranch_scc0 .Lprio_done
	s_setprio 1
.Lprio_done:
	s_add_u32 s96, s70, 0x2e000000
	s_addc_u32 s97, s71, 0
	v_and_b32_e32 v232, 63, v0
	s_waitcnt lgkmcnt(0)
	v_writelane_b32 v252, s12, 10
	s_nop 1
	v_writelane_b32 v252, s13, 11
	v_writelane_b32 v252, s14, 12
	v_writelane_b32 v252, s15, 13
	v_writelane_b32 v252, s16, 14
	v_writelane_b32 v252, s17, 15
	v_writelane_b32 v252, s18, 16
	v_writelane_b32 v252, s19, 17
	v_writelane_b32 v252, s20, 18
	v_writelane_b32 v252, s21, 19
	v_writelane_b32 v252, s22, 20
	v_writelane_b32 v252, s23, 21
	v_writelane_b32 v252, s24, 22
	v_writelane_b32 v252, s25, 23
	v_writelane_b32 v252, s26, 24
	v_writelane_b32 v252, s27, 25
	v_writelane_b32 v252, s0, 26
	s_add_u32 s0, s70, 0x808000
	s_addc_u32 s1, s71, 0
	v_writelane_b32 v252, s0, 27
	s_nop 1
	v_writelane_b32 v252, s1, 28
	s_nop 0
	v_readlane_b32 s2, v252, 3
	v_readlane_b32 s3, v252, 4
	s_cmp_lt_i32 s2, 1
	s_cselect_b64 s[0:1], -1, 0
	s_cmp_gt_i32 s3, 0
	s_cselect_b64 s[2:3], -1, 0
	s_and_b64 s[0:1], s[0:1], s[2:3]
	v_writelane_b32 v252, s0, 29
	s_andn2_b64 vcc, exec, s[0:1]
	s_nop 0
	v_writelane_b32 v252, s1, 30
	s_cbranch_vccnz .LBB0_137
	v_writelane_b32 v252, s96, 31
	s_cmpk_gt_i32 s95, 0xff
	s_nop 0
	v_writelane_b32 v252, s97, 32
	s_cbranch_scc1 .LBB0_58
	v_mov_b32_e32 v19, 0
	v_lshlrev_b32_e32 v4, 4, v0
	v_and_b32_e32 v1, 15, v0
	v_mov_b32_e32 v2, 16
	s_add_u32 s50, s70, 0x2a00000
	v_cmp_lt_u32_sdwa s[0:1], v0, v2 src0_sel:BYTE_0 src1_sel:DWORD
	v_and_b32_e32 v2, 0x1f0, v4
	v_mov_b32_e32 v3, v19
	v_cmp_eq_u32_e32 vcc, 0, v1
	s_addc_u32 s51, s71, 0
	v_lshl_add_u64 v[2:3], s[70:71], 0, v[2:3]
	s_mov_b64 s[2:3], 0x3000000
	s_and_b64 s[16:17], s[0:1], vcc
	v_cmp_eq_u32_e32 vcc, 1, v1
	v_lshl_add_u64 v[20:21], v[2:3], 0, s[2:3]
	s_and_b64 s[2:3], s[0:1], vcc
	v_writelane_b32 v252, s2, 33
	v_cmp_eq_u32_e32 vcc, 2, v1
	v_lshrrev_b32_e32 v5, 8, v0
	v_writelane_b32 v252, s3, 34
	s_and_b64 s[2:3], s[0:1], vcc
	v_writelane_b32 v252, s2, 35
	v_cmp_eq_u32_e32 vcc, 3, v1
	v_lshlrev_b32_e32 v2, 7, v5
	v_writelane_b32 v252, s3, 36
	s_and_b64 s[2:3], s[0:1], vcc
	v_writelane_b32 v252, s2, 37
	v_cmp_eq_u32_e32 vcc, 4, v1
	v_lshrrev_b32_e32 v7, 4, v0
	v_writelane_b32 v252, s3, 38
	s_and_b64 s[2:3], s[0:1], vcc
	v_writelane_b32 v252, s2, 39
	v_cmp_eq_u32_e32 vcc, 5, v1
	v_and_b32_e32 v7, 28, v7
	v_writelane_b32 v252, s3, 40
	s_and_b64 s[2:3], s[0:1], vcc
	v_writelane_b32 v252, s2, 41
	v_cmp_eq_u32_e32 vcc, 6, v1
	v_lshlrev_b32_e32 v18, 2, v0
	v_writelane_b32 v252, s3, 42
	s_and_b64 s[2:3], s[0:1], vcc
	v_writelane_b32 v252, s2, 43
	v_cmp_eq_u32_e32 vcc, 7, v1
	v_lshl_or_b32 v7, v232, 6, v7
	v_writelane_b32 v252, s3, 44
	s_and_b64 s[2:3], s[0:1], vcc
	v_writelane_b32 v252, s2, 45
	v_cmp_eq_u32_e32 vcc, 8, v1
	v_add_u32_e32 v7, 0, v7
	v_writelane_b32 v252, s3, 46
	s_and_b64 s[2:3], s[0:1], vcc
	v_cmp_eq_u32_e32 vcc, 9, v1
	s_and_b64 s[20:21], s[0:1], vcc
	v_cmp_eq_u32_e32 vcc, 10, v1
	s_and_b64 s[22:23], s[0:1], vcc
	v_cmp_eq_u32_e32 vcc, 11, v1
	s_and_b64 s[24:25], s[0:1], vcc
	v_cmp_eq_u32_e32 vcc, 12, v1
	s_and_b64 s[26:27], s[0:1], vcc
	v_cmp_eq_u32_e32 vcc, 13, v1
	s_and_b64 s[28:29], s[0:1], vcc
	v_cmp_eq_u32_e32 vcc, 14, v1
	v_writelane_b32 v252, s2, 47
	s_and_b64 s[30:31], s[0:1], vcc
	v_cmp_eq_u32_e32 vcc, 15, v1
	v_writelane_b32 v252, s3, 48
	s_and_b64 s[34:35], s[0:1], vcc
	s_movk_i32 s0, 0xf00
	v_and_or_b32 v4, v4, s0, v2
	v_readlane_b32 s0, v252, 31
	v_readlane_b32 s1, v252, 32
	v_lshlrev_b32_e32 v2, 6, v0
	v_mov_b32_e32 v3, v19
	v_lshl_add_u64 v[26:27], s[0:1], 0, v[18:19]
	v_readlane_b32 s0, v252, 10
	v_readlane_b32 s1, v252, 11
	v_not_b32_e32 v6, v0
	v_add_u32_e32 v44, 0x4200, v7
	v_lshlrev_b32_e32 v7, 11, v5
	v_lshl_add_u64 v[28:29], s[86:87], 0, v[2:3]
	v_lshl_add_u64 v[30:31], s[0:1], 0, v[2:3]
	v_add_u32_e32 v40, 0, v2
	v_mov_b32_e32 v2, 6
	v_lshlrev_b32_e32 v3, 3, v0
	v_lshlrev_b32_e32 v6, 5, v6
	v_add_u32_e32 v8, 0, v7
	v_lshl_or_b32 v7, v1, 2, v7
	v_readlane_b32 s2, v252, 12
	v_readlane_b32 s3, v252, 13
	v_readlane_b32 s4, v252, 14
	v_readlane_b32 s5, v252, 15
	v_lshlrev_b32_sdwa v2, v2, v0 dst_sel:DWORD dst_unused:UNUSED_PAD src0_sel:DWORD src1_sel:BYTE_0
	v_and_b32_e32 v3, 8, v3
	v_and_b32_e32 v42, 0x3c0, v6
	v_mul_i32_i24_e32 v6, 0xffffffc4, v0
	v_add_u32_e32 v7, 0, v7
	s_movk_i32 s0, 0x100
	v_lshl_add_u64 v[22:23], s[80:81], 0, v[18:19]
	v_lshl_add_u64 v[24:25], s[82:83], 0, v[18:19]
	v_lshrrev_b32_e32 v41, 5, v0
	v_or_b32_e32 v43, 0xfffffe00, v0
	v_lshl_add_u64 v[32:33], s[2:3], 0, v[18:19]
	s_mov_b64 s[2:3], s[16:17]
	v_lshl_add_u64 v[34:35], s[4:5], 0, v[18:19]
	v_add_u32_e32 v45, 0x2200, v8
	v_add_u32_e32 v46, 0x4200, v7
	v_add_u32_e32 v47, 0, v4
	v_mov_b32_e32 v48, 0x3c0881c4
	v_mov_b32_e32 v49, 0xbab64f3b
	v_mov_b32_e32 v50, 1.0
	v_add_u32_e32 v51, v40, v6
	v_mov_b32_e32 v52, 0x3ab69700
	v_add_u32_e32 v53, 0, v2
	v_lshlrev_b32_e32 v54, 2, v3
	v_mov_b32_e32 v55, 0x7f800000
	v_not_b32_e32 v56, 63
	v_not_b32_e32 v57, 31
	v_mov_b32_e32 v58, 0x7fc00000
	v_mov_b32_e32 v59, 0xa00
	v_mov_b32_e32 v60, 0x7f000000
	v_not_b32_e32 v61, 39
	v_cmp_gt_u32_e64 s[36:37], s0, v0
	s_mov_b32 s89, 0x3fb8aa3b
	s_mov_b32 s90, 0xc2ce8ed0
	s_mov_b32 s91, 0x42b17218
	s_brev_b32 s92, 18
	s_mov_b32 s97, 0xa2f9836e
	s_mov_b32 s93, 0x3fc90fda
	s_mov_b32 s88, 0x3f22f983
	s_mov_b32 s48, 0xbfc90fda
	s_movk_i32 s49, 0x1f8
	s_mov_b32 s33, s95
	v_cmp_gt_u32_e64 s[38:39], 64, v0
	v_cmp_eq_u32_e64 s[40:41], 1, v5
	s_mov_b64 s[52:53], 0x800
	v_readlane_b32 s6, v252, 16
	v_readlane_b32 s7, v252, 17
	v_readlane_b32 s8, v252, 18
	v_readlane_b32 s9, v252, 19
	v_readlane_b32 s10, v252, 20
	v_readlane_b32 s11, v252, 21
	v_readlane_b32 s12, v252, 22
	v_readlane_b32 s13, v252, 23
	v_readlane_b32 s14, v252, 24
	v_readlane_b32 s15, v252, 25
	s_branch .LBB0_12

.LBB0_221:
	s_waitcnt lgkmcnt(0)
	s_add_i32 s2, s58, 0x100
	s_add_i32 s3, s57, 0x100
	s_barrier
	s_waitcnt lgkmcnt(7)
	v_mfma_f32_16x16x32_bf16 v[114:117], v[158:161], v[186:189], 0
	v_mfma_f32_16x16x32_bf16 v[110:113], v[150:153], v[186:189], 0
	s_waitcnt lgkmcnt(6)
	v_mfma_f32_16x16x32_bf16 v[106:109], v[158:161], v[178:181], 0
	v_mfma_f32_16x16x32_bf16 v[102:105], v[150:153], v[178:181], 0
	s_waitcnt lgkmcnt(3)
	v_mfma_f32_16x16x32_bf16 v[98:101], v[158:161], v[170:173], 0
	v_mfma_f32_16x16x32_bf16 v[94:97], v[150:153], v[170:173], 0
	s_waitcnt lgkmcnt(2)
	v_mfma_f32_16x16x32_bf16 v[90:93], v[158:161], v[162:165], 0
	v_mfma_f32_16x16x32_bf16 v[86:89], v[150:153], v[162:165], 0
	v_mfma_f32_16x16x32_bf16 v[114:117], v[154:157], v[190:193], v[114:117]
	v_mfma_f32_16x16x32_bf16 v[110:113], v[146:149], v[190:193], v[110:113]
	v_mfma_f32_16x16x32_bf16 v[106:109], v[154:157], v[182:185], v[106:109]
	v_mfma_f32_16x16x32_bf16 v[102:105], v[146:149], v[182:185], v[102:105]
	s_waitcnt lgkmcnt(1)
	v_mfma_f32_16x16x32_bf16 v[98:101], v[154:157], v[174:177], v[98:101]
	v_mfma_f32_16x16x32_bf16 v[94:97], v[146:149], v[174:177], v[94:97]
	s_waitcnt lgkmcnt(0)
	v_mfma_f32_16x16x32_bf16 v[90:93], v[154:157], v[166:169], v[90:93]
	v_mfma_f32_16x16x32_bf16 v[86:89], v[146:149], v[166:169], v[86:89]
	v_mfma_f32_16x16x32_bf16 v[82:85], v[142:145], v[186:189], 0
	v_mfma_f32_16x16x32_bf16 v[74:77], v[134:137], v[186:189], 0
	v_mfma_f32_16x16x32_bf16 v[70:73], v[142:145], v[178:181], 0
	v_mfma_f32_16x16x32_bf16 v[66:69], v[134:137], v[178:181], 0
	v_mfma_f32_16x16x32_bf16 v[62:65], v[142:145], v[170:173], 0
	v_mfma_f32_16x16x32_bf16 v[58:61], v[134:137], v[170:173], 0
	v_mfma_f32_16x16x32_bf16 v[54:57], v[142:145], v[162:165], 0
	v_mfma_f32_16x16x32_bf16 v[50:53], v[134:137], v[162:165], 0
	s_nop 0
	v_mfma_f32_16x16x32_bf16 v[82:85], v[138:141], v[190:193], v[82:85]
	v_mfma_f32_16x16x32_bf16 v[74:77], v[130:133], v[190:193], v[74:77]
	v_mfma_f32_16x16x32_bf16 v[70:73], v[138:141], v[182:185], v[70:73]
	v_mfma_f32_16x16x32_bf16 v[66:69], v[130:133], v[182:185], v[66:69]
	v_mfma_f32_16x16x32_bf16 v[62:65], v[138:141], v[174:177], v[62:65]
	v_mfma_f32_16x16x32_bf16 v[58:61], v[130:133], v[174:177], v[58:61]
	v_mfma_f32_16x16x32_bf16 v[54:57], v[138:141], v[166:169], v[54:57]
	v_mfma_f32_16x16x32_bf16 v[50:53], v[130:133], v[166:169], v[50:53]
	s_barrier
	s_mov_b32 m0, s21
	ds_read_b128 v[186:189], v221 offset:16384
	ds_read_b128 v[178:181], v221 offset:18432
	ds_read_b128 v[190:193], v222 offset:16384
	ds_read_b128 v[182:185], v222 offset:18432
	ds_read_b128 v[170:173], v221 offset:20480
	ds_read_b128 v[162:165], v221 offset:22528
	ds_read_b128 v[174:177], v222 offset:20480
	ds_read_b128 v[166:169], v222 offset:22528
	buffer_load_dwordx4 v208, s[8:11], s3 offen lds
	s_mov_b32 m0, s22
	v_cndmask_b32_e64 v194, 0, 1, s[18:19]
	buffer_load_dwordx4 v210, s[8:11], s3 offen lds
	s_add_i32 s3, s57, 0x40100
	s_mov_b32 m0, s23
	s_andn2_b64 vcc, exec, s[18:19]
	buffer_load_dwordx4 v208, s[8:11], s3 offen lds
	s_mov_b32 m0, s24
	s_nop 0
	buffer_load_dwordx4 v210, s[8:11], s3 offen lds
	s_mov_b32 m0, s20
	s_nop 0
	buffer_load_dwordx4 v207, s[8:11], s2 offen lds
	s_mov_b32 m0, s25
	s_nop 0
	buffer_load_dwordx4 v209, s[8:11], s2 offen lds
	v_cmp_ne_u32_e64 s[2:3], 1, v194
	s_cbranch_vccnz .LBB0_250
	s_waitcnt vmcnt(14)
	s_cbranch_execnz .LBB0_224

.LBB0_224:
	s_waitcnt lgkmcnt(0)
	s_barrier
	s_waitcnt lgkmcnt(7)
	v_mfma_f32_16x16x32_bf16 v[78:81], v[158:161], v[186:189], 0
	v_mfma_f32_16x16x32_bf16 v[46:49], v[150:153], v[186:189], 0
	s_waitcnt lgkmcnt(6)
	v_mfma_f32_16x16x32_bf16 v[42:45], v[158:161], v[178:181], 0
	v_mfma_f32_16x16x32_bf16 v[38:41], v[150:153], v[178:181], 0
	s_waitcnt lgkmcnt(3)
	v_mfma_f32_16x16x32_bf16 v[34:37], v[158:161], v[170:173], 0
	v_mfma_f32_16x16x32_bf16 v[30:33], v[150:153], v[170:173], 0
	s_waitcnt lgkmcnt(2)
	v_mfma_f32_16x16x32_bf16 v[26:29], v[158:161], v[162:165], 0
	v_mfma_f32_16x16x32_bf16 v[22:25], v[150:153], v[162:165], 0
	v_mfma_f32_16x16x32_bf16 v[78:81], v[154:157], v[190:193], v[78:81]
	v_mfma_f32_16x16x32_bf16 v[46:49], v[146:149], v[190:193], v[46:49]
	v_mfma_f32_16x16x32_bf16 v[42:45], v[154:157], v[182:185], v[42:45]
	v_mfma_f32_16x16x32_bf16 v[38:41], v[146:149], v[182:185], v[38:41]
	s_waitcnt lgkmcnt(1)
	v_mfma_f32_16x16x32_bf16 v[34:37], v[154:157], v[174:177], v[34:37]
	v_mfma_f32_16x16x32_bf16 v[30:33], v[146:149], v[174:177], v[30:33]
	s_waitcnt lgkmcnt(0)
	v_mfma_f32_16x16x32_bf16 v[26:29], v[154:157], v[166:169], v[26:29]
	v_mfma_f32_16x16x32_bf16 v[22:25], v[146:149], v[166:169], v[22:25]
	v_mfma_f32_16x16x32_bf16 v[18:21], v[142:145], v[186:189], 0
	v_mfma_f32_16x16x32_bf16 v[14:17], v[134:137], v[186:189], 0
	v_mfma_f32_16x16x32_bf16 v[10:13], v[142:145], v[178:181], 0
	v_mfma_f32_16x16x32_bf16 v[6:9], v[134:137], v[178:181], 0
	v_mfma_f32_16x16x32_bf16 v[2:5], v[142:145], v[170:173], 0
	v_mfma_f32_16x16x32_bf16 v[126:129], v[134:137], v[170:173], 0
	v_mfma_f32_16x16x32_bf16 v[122:125], v[142:145], v[162:165], 0
	v_mfma_f32_16x16x32_bf16 v[118:121], v[134:137], v[162:165], 0
	s_nop 0
	v_mfma_f32_16x16x32_bf16 v[18:21], v[138:141], v[190:193], v[18:21]
	v_mfma_f32_16x16x32_bf16 v[14:17], v[130:133], v[190:193], v[14:17]
	v_mfma_f32_16x16x32_bf16 v[10:13], v[138:141], v[182:185], v[10:13]
	v_mfma_f32_16x16x32_bf16 v[6:9], v[130:133], v[182:185], v[6:9]
	v_mfma_f32_16x16x32_bf16 v[2:5], v[138:141], v[174:177], v[2:5]
	v_mfma_f32_16x16x32_bf16 v[126:129], v[130:133], v[174:177], v[126:129]
	v_mfma_f32_16x16x32_bf16 v[122:125], v[138:141], v[166:169], v[122:125]
	v_mfma_f32_16x16x32_bf16 v[118:121], v[130:133], v[166:169], v[118:121]
	s_barrier
	v_add_u32_e32 v194, s45, v211
	v_add_u32_e32 v225, s46, v211
	v_add_u32_e32 v229, s47, v211
	v_add_u32_e32 v231, s48, v211
	v_add_u32_e32 v224, s45, v212
	ds_read_b128 v[146:149], v194
	ds_read_b128 v[150:153], v224
	v_add_u32_e32 v228, s46, v212
	ds_read_b128 v[154:157], v225
	ds_read_b128 v[158:161], v228
	v_add_u32_e32 v230, s47, v212
	ds_read_b128 v[130:133], v229
	ds_read_b128 v[134:137], v230
	v_add_u32_e32 v233, s48, v212
	ds_read_b128 v[138:141], v231
	ds_read_b128 v[142:145], v233
	s_mov_b32 m0, s26
	s_add_i32 s4, s58, 0x2100
	ds_read_b128 v[186:189], v221 offset:32768
	ds_read_b128 v[174:177], v221 offset:34816
	ds_read_b128 v[190:193], v222 offset:32768
	ds_read_b128 v[178:181], v222 offset:34816
	ds_read_b128 v[170:173], v221 offset:36864
	ds_read_b128 v[162:165], v221 offset:38912
	ds_read_b128 v[182:185], v222 offset:36864
	ds_read_b128 v[166:169], v222 offset:38912
	buffer_load_dwordx4 v207, s[8:11], s4 offen lds
	s_mov_b32 m0, s27
	s_and_b64 vcc, exec, s[2:3]
	buffer_load_dwordx4 v209, s[8:11], s4 offen lds
	s_cbranch_vccnz .LBB0_251
	s_waitcnt vmcnt(16)
	s_cbranch_execnz .LBB0_227

.LBB0_227:
	s_waitcnt lgkmcnt(0)
	s_add_i32 s18, s58, 0x180
	s_add_i32 s19, s57, 0x180
	s_barrier
	s_waitcnt lgkmcnt(7)
	v_mfma_f32_16x16x32_bf16 v[114:117], v[146:149], v[186:189], v[114:117]
	v_mfma_f32_16x16x32_bf16 v[110:113], v[154:157], v[186:189], v[110:113]
	s_waitcnt lgkmcnt(6)
	v_mfma_f32_16x16x32_bf16 v[106:109], v[146:149], v[174:177], v[106:109]
	v_mfma_f32_16x16x32_bf16 v[102:105], v[154:157], v[174:177], v[102:105]
	s_waitcnt lgkmcnt(3)
	v_mfma_f32_16x16x32_bf16 v[98:101], v[146:149], v[170:173], v[98:101]
	v_mfma_f32_16x16x32_bf16 v[94:97], v[154:157], v[170:173], v[94:97]
	s_waitcnt lgkmcnt(2)
	v_mfma_f32_16x16x32_bf16 v[90:93], v[146:149], v[162:165], v[90:93]
	v_mfma_f32_16x16x32_bf16 v[86:89], v[154:157], v[162:165], v[86:89]
	v_mfma_f32_16x16x32_bf16 v[114:117], v[150:153], v[190:193], v[114:117]
	v_mfma_f32_16x16x32_bf16 v[110:113], v[158:161], v[190:193], v[110:113]
	v_mfma_f32_16x16x32_bf16 v[106:109], v[150:153], v[178:181], v[106:109]
	v_mfma_f32_16x16x32_bf16 v[102:105], v[158:161], v[178:181], v[102:105]
	s_waitcnt lgkmcnt(1)
	v_mfma_f32_16x16x32_bf16 v[98:101], v[150:153], v[182:185], v[98:101]
	v_mfma_f32_16x16x32_bf16 v[94:97], v[158:161], v[182:185], v[94:97]
	s_waitcnt lgkmcnt(0)
	v_mfma_f32_16x16x32_bf16 v[90:93], v[150:153], v[166:169], v[90:93]
	v_mfma_f32_16x16x32_bf16 v[86:89], v[158:161], v[166:169], v[86:89]
	v_mfma_f32_16x16x32_bf16 v[82:85], v[130:133], v[186:189], v[82:85]
	v_mfma_f32_16x16x32_bf16 v[74:77], v[138:141], v[186:189], v[74:77]
	v_mfma_f32_16x16x32_bf16 v[70:73], v[130:133], v[174:177], v[70:73]
	v_mfma_f32_16x16x32_bf16 v[66:69], v[138:141], v[174:177], v[66:69]
	v_mfma_f32_16x16x32_bf16 v[62:65], v[130:133], v[170:173], v[62:65]
	v_mfma_f32_16x16x32_bf16 v[58:61], v[138:141], v[170:173], v[58:61]
	v_mfma_f32_16x16x32_bf16 v[54:57], v[130:133], v[162:165], v[54:57]
	v_mfma_f32_16x16x32_bf16 v[50:53], v[138:141], v[162:165], v[50:53]
	v_mfma_f32_16x16x32_bf16 v[82:85], v[134:137], v[190:193], v[82:85]
	v_mfma_f32_16x16x32_bf16 v[74:77], v[142:145], v[190:193], v[74:77]
	v_mfma_f32_16x16x32_bf16 v[70:73], v[134:137], v[178:181], v[70:73]
	v_mfma_f32_16x16x32_bf16 v[66:69], v[142:145], v[178:181], v[66:69]
	v_mfma_f32_16x16x32_bf16 v[62:65], v[134:137], v[182:185], v[62:65]
	v_mfma_f32_16x16x32_bf16 v[58:61], v[142:145], v[182:185], v[58:61]
	v_mfma_f32_16x16x32_bf16 v[54:57], v[134:137], v[166:169], v[54:57]
	v_mfma_f32_16x16x32_bf16 v[50:53], v[142:145], v[166:169], v[50:53]
	s_barrier
	s_mov_b32 m0, s29
	s_mov_b32 s4, s70
	ds_read_b128 v[186:189], v221 offset:49152
	ds_read_b128 v[174:177], v221 offset:51200
	ds_read_b128 v[190:193], v222 offset:49152
	ds_read_b128 v[178:181], v222 offset:51200
	ds_read_b128 v[170:173], v221 offset:53248
	ds_read_b128 v[162:165], v221 offset:55296
	ds_read_b128 v[182:185], v222 offset:53248
	ds_read_b128 v[166:169], v222 offset:55296
	buffer_load_dwordx4 v208, s[4:7], s19 offen lds
	s_mov_b32 m0, s30
	s_and_b64 vcc, exec, s[2:3]
	buffer_load_dwordx4 v210, s[4:7], s19 offen lds
	s_add_i32 s19, s57, 0x40180
	s_mov_b32 m0, s35
	s_nop 0
	buffer_load_dwordx4 v208, s[4:7], s19 offen lds
	s_mov_b32 m0, s36
	s_nop 0
	buffer_load_dwordx4 v210, s[4:7], s19 offen lds
	s_mov_b32 m0, s31
	s_nop 0
	buffer_load_dwordx4 v207, s[4:7], s18 offen lds
	s_mov_b32 m0, s34
	s_nop 0
	buffer_load_dwordx4 v209, s[4:7], s18 offen lds
	s_cbranch_vccnz .LBB0_252
	s_waitcnt vmcnt(22)
	s_cbranch_execnz .LBB0_230

.LBB0_230:
	s_waitcnt lgkmcnt(0)
	s_barrier
	s_waitcnt lgkmcnt(7)
	v_mfma_f32_16x16x32_bf16 v[78:81], v[146:149], v[186:189], v[78:81]
	v_mfma_f32_16x16x32_bf16 v[46:49], v[154:157], v[186:189], v[46:49]
	s_waitcnt lgkmcnt(6)
	v_mfma_f32_16x16x32_bf16 v[42:45], v[146:149], v[174:177], v[42:45]
	v_mfma_f32_16x16x32_bf16 v[38:41], v[154:157], v[174:177], v[38:41]
	s_waitcnt lgkmcnt(3)
	v_mfma_f32_16x16x32_bf16 v[34:37], v[146:149], v[170:173], v[34:37]
	v_mfma_f32_16x16x32_bf16 v[30:33], v[154:157], v[170:173], v[30:33]
	s_waitcnt lgkmcnt(2)
	v_mfma_f32_16x16x32_bf16 v[26:29], v[146:149], v[162:165], v[26:29]
	v_mfma_f32_16x16x32_bf16 v[22:25], v[154:157], v[162:165], v[22:25]
	v_mfma_f32_16x16x32_bf16 v[78:81], v[150:153], v[190:193], v[78:81]
	v_mfma_f32_16x16x32_bf16 v[46:49], v[158:161], v[190:193], v[46:49]
	v_mfma_f32_16x16x32_bf16 v[42:45], v[150:153], v[178:181], v[42:45]
	v_mfma_f32_16x16x32_bf16 v[38:41], v[158:161], v[178:181], v[38:41]
	s_waitcnt lgkmcnt(1)
	v_mfma_f32_16x16x32_bf16 v[34:37], v[150:153], v[182:185], v[34:37]
	v_mfma_f32_16x16x32_bf16 v[30:33], v[158:161], v[182:185], v[30:33]
	s_waitcnt lgkmcnt(0)
	v_mfma_f32_16x16x32_bf16 v[26:29], v[150:153], v[166:169], v[26:29]
	v_mfma_f32_16x16x32_bf16 v[22:25], v[158:161], v[166:169], v[22:25]
	v_mfma_f32_16x16x32_bf16 v[18:21], v[130:133], v[186:189], v[18:21]
	v_mfma_f32_16x16x32_bf16 v[14:17], v[138:141], v[186:189], v[14:17]
	v_mfma_f32_16x16x32_bf16 v[10:13], v[130:133], v[174:177], v[10:13]
	v_mfma_f32_16x16x32_bf16 v[6:9], v[138:141], v[174:177], v[6:9]
	v_mfma_f32_16x16x32_bf16 v[2:5], v[130:133], v[170:173], v[2:5]
	v_mfma_f32_16x16x32_bf16 v[126:129], v[138:141], v[170:173], v[126:129]
	v_mfma_f32_16x16x32_bf16 v[122:125], v[130:133], v[162:165], v[122:125]
	v_mfma_f32_16x16x32_bf16 v[118:121], v[138:141], v[162:165], v[118:121]
	v_mfma_f32_16x16x32_bf16 v[18:21], v[134:137], v[190:193], v[18:21]
	v_mfma_f32_16x16x32_bf16 v[14:17], v[142:145], v[190:193], v[14:17]
	v_mfma_f32_16x16x32_bf16 v[10:13], v[134:137], v[178:181], v[10:13]
	v_mfma_f32_16x16x32_bf16 v[6:9], v[142:145], v[178:181], v[6:9]
	v_mfma_f32_16x16x32_bf16 v[2:5], v[134:137], v[182:185], v[2:5]
	v_mfma_f32_16x16x32_bf16 v[126:129], v[142:145], v[182:185], v[126:129]
	v_mfma_f32_16x16x32_bf16 v[122:125], v[134:137], v[166:169], v[122:125]
	v_mfma_f32_16x16x32_bf16 v[118:121], v[142:145], v[166:169], v[118:121]
	s_barrier
	s_add_i32 s28, s28, 1
	s_mul_i32 s2, s28, s43
	s_mul_hi_u32 s3, s28, s94
	s_add_i32 s3, s3, s2
	s_mul_i32 s2, s28, s94
	s_add_u32 s18, s2, s95
	s_addc_u32 s19, s3, s44
	v_cmp_gt_i64_e32 vcc, s[18:19], v[198:199]
	v_cmp_lt_i64_e64 s[2:3], s[18:19], v[196:197]
	s_cbranch_vccnz .LBB0_232
	s_ashr_i32 s4, s18, 31
	s_lshr_b32 s4, s4, 29
	s_add_i32 s4, s18, s4
	s_ashr_i32 s19, s4, 3
	s_and_b32 s4, s4, -8
	s_sub_i32 s4, s18, s4
	s_cmp_lt_i32 s4, 0
	s_cselect_b32 s18, s49, 0x240
	s_mul_i32 s4, s4, s18
	s_add_i32 s4, s4, s19
	s_mul_hi_i32 s18, s4, 0x38e38e39
	s_lshr_b32 s19, s18, 31
	s_ashr_i32 s18, s18, 5
	s_add_i32 s18, s18, s19
	s_lshl_b32 s19, s18, 3
	s_sub_i32 s33, 0x100, s19
	s_min_i32 s33, s33, 8
	s_abs_i32 s51, s33
	v_cvt_f32_u32_e32 v130, s51
	s_sub_i32 s53, 0, s51
	s_mulk_i32 s18, 0x90
	s_sub_i32 s4, s4, s18
	v_rcp_iflag_f32_e32 v130, v130
	s_abs_i32 s18, s4
	s_xor_b32 s52, s4, s33
	s_ashr_i32 s52, s52, 31
	v_mul_f32_e32 v130, 0x4f7ffffe, v130
	v_cvt_u32_f32_e32 v130, v130
	s_nop 0
	v_readfirstlane_b32 s54, v130
	s_mul_i32 s53, s53, s54
	s_mul_hi_u32 s53, s54, s53
	s_add_i32 s54, s54, s53
	s_mul_hi_u32 s53, s18, s54
	s_mul_i32 s54, s53, s51
	s_sub_i32 s18, s18, s54
	s_add_i32 s59, s53, 1
	s_sub_i32 s54, s18, s51
	s_cmp_ge_u32 s18, s51
	s_cselect_b32 s53, s59, s53
	s_cselect_b32 s18, s54, s18
	s_add_i32 s54, s53, 1
	s_cmp_ge_u32 s18, s51
	s_cselect_b32 s18, s54, s53
	s_xor_b32 s18, s18, s52
	s_sub_i32 s51, s18, s52
	s_mul_i32 s18, s51, s33
	s_sub_i32 s4, s4, s18
	s_add_i32 s52, s19, s4

.LBB0_233:
	ds_read_b128 v[130:133], v213
	ds_read_b128 v[134:137], v214
	ds_read_b128 v[138:141], v215
	ds_read_b128 v[142:145], v216
	ds_read_b128 v[146:149], v217
	ds_read_b128 v[150:153], v218
	ds_read_b128 v[154:157], v219
	ds_read_b128 v[158:161], v220
	s_add_i32 s4, s33, 0xffffe080
	s_cmp_eq_u32 s58, 12
	s_cselect_b32 s61, s18, s4
	s_cselect_b32 s60, s19, s57
	s_add_i32 s59, s61, 0x80
	s_mov_b32 s4, s70
	s_mov_b32 m0, s38
	ds_read_b128 v[162:165], v221
	ds_read_b128 v[166:169], v221 offset:2048
	ds_read_b128 v[170:173], v222
	ds_read_b128 v[174:177], v222 offset:2048
	ds_read_b128 v[178:181], v221 offset:4096
	ds_read_b128 v[182:185], v221 offset:6144
	ds_read_b128 v[186:189], v222 offset:4096
	ds_read_b128 v[190:193], v222 offset:6144
	buffer_load_dwordx4 v207, s[4:7], s33 offen lds
	s_mov_b32 m0, s41
	s_nop 0
	buffer_load_dwordx4 v209, s[4:7], s33 offen lds
	s_waitcnt vmcnt(8)
	s_waitcnt lgkmcnt(0)
	s_barrier
	s_waitcnt lgkmcnt(7)
	v_mfma_f32_16x16x32_bf16 v[114:117], v[130:133], v[162:165], v[114:117]
	v_mfma_f32_16x16x32_bf16 v[110:113], v[138:141], v[162:165], v[110:113]
	s_waitcnt lgkmcnt(6)
	v_mfma_f32_16x16x32_bf16 v[106:109], v[130:133], v[166:169], v[106:109]
	v_mfma_f32_16x16x32_bf16 v[102:105], v[138:141], v[166:169], v[102:105]
	s_waitcnt lgkmcnt(3)
	v_mfma_f32_16x16x32_bf16 v[98:101], v[130:133], v[178:181], v[98:101]
	v_mfma_f32_16x16x32_bf16 v[94:97], v[138:141], v[178:181], v[94:97]
	s_waitcnt lgkmcnt(2)
	v_mfma_f32_16x16x32_bf16 v[90:93], v[130:133], v[182:185], v[90:93]
	v_mfma_f32_16x16x32_bf16 v[86:89], v[138:141], v[182:185], v[86:89]
	v_mfma_f32_16x16x32_bf16 v[114:117], v[134:137], v[170:173], v[114:117]
	v_mfma_f32_16x16x32_bf16 v[110:113], v[142:145], v[170:173], v[110:113]
	v_mfma_f32_16x16x32_bf16 v[106:109], v[134:137], v[174:177], v[106:109]
	v_mfma_f32_16x16x32_bf16 v[102:105], v[142:145], v[174:177], v[102:105]
	s_waitcnt lgkmcnt(1)
	v_mfma_f32_16x16x32_bf16 v[98:101], v[134:137], v[186:189], v[98:101]
	v_mfma_f32_16x16x32_bf16 v[94:97], v[142:145], v[186:189], v[94:97]
	s_waitcnt lgkmcnt(0)
	v_mfma_f32_16x16x32_bf16 v[90:93], v[134:137], v[190:193], v[90:93]
	v_mfma_f32_16x16x32_bf16 v[86:89], v[142:145], v[190:193], v[86:89]
	v_mfma_f32_16x16x32_bf16 v[82:85], v[146:149], v[162:165], v[82:85]
	v_mfma_f32_16x16x32_bf16 v[74:77], v[154:157], v[162:165], v[74:77]
	v_mfma_f32_16x16x32_bf16 v[70:73], v[146:149], v[166:169], v[70:73]
	v_mfma_f32_16x16x32_bf16 v[66:69], v[154:157], v[166:169], v[66:69]
	v_mfma_f32_16x16x32_bf16 v[62:65], v[146:149], v[178:181], v[62:65]
	v_mfma_f32_16x16x32_bf16 v[58:61], v[154:157], v[178:181], v[58:61]
	v_mfma_f32_16x16x32_bf16 v[54:57], v[146:149], v[182:185], v[54:57]
	v_mfma_f32_16x16x32_bf16 v[50:53], v[154:157], v[182:185], v[50:53]
	v_mfma_f32_16x16x32_bf16 v[82:85], v[150:153], v[170:173], v[82:85]
	v_mfma_f32_16x16x32_bf16 v[74:77], v[158:161], v[170:173], v[74:77]
	v_mfma_f32_16x16x32_bf16 v[70:73], v[150:153], v[174:177], v[70:73]
	v_mfma_f32_16x16x32_bf16 v[66:69], v[158:161], v[174:177], v[66:69]
	v_mfma_f32_16x16x32_bf16 v[62:65], v[150:153], v[186:189], v[62:65]
	v_mfma_f32_16x16x32_bf16 v[58:61], v[158:161], v[186:189], v[58:61]
	v_mfma_f32_16x16x32_bf16 v[54:57], v[150:153], v[190:193], v[54:57]
	v_mfma_f32_16x16x32_bf16 v[50:53], v[158:161], v[190:193], v[50:53]
	s_barrier
	s_mov_b32 m0, s21
	ds_read_b128 v[162:165], v221 offset:16384
	ds_read_b128 v[166:169], v221 offset:18432
	ds_read_b128 v[170:173], v222 offset:16384
	ds_read_b128 v[174:177], v222 offset:18432
	ds_read_b128 v[178:181], v221 offset:20480
	ds_read_b128 v[182:185], v221 offset:22528
	ds_read_b128 v[186:189], v222 offset:20480
	ds_read_b128 v[190:193], v222 offset:22528
	buffer_load_dwordx4 v208, s[4:7], s60 offen lds
	s_mov_b32 m0, s22
	s_add_i32 s62, s60, 0x40000
	buffer_load_dwordx4 v210, s[4:7], s60 offen lds
	s_mov_b32 m0, s23
	s_nop 0
	buffer_load_dwordx4 v208, s[4:7], s62 offen lds
	s_mov_b32 m0, s24
	s_nop 0
	buffer_load_dwordx4 v210, s[4:7], s62 offen lds
	s_mov_b32 m0, s20
	s_nop 0
	buffer_load_dwordx4 v207, s[4:7], s61 offen lds
	s_mov_b32 m0, s25
	s_nop 0
	buffer_load_dwordx4 v209, s[4:7], s61 offen lds
	s_waitcnt vmcnt(8)
	s_waitcnt lgkmcnt(0)
	s_barrier
	s_waitcnt lgkmcnt(7)
	v_mfma_f32_16x16x32_bf16 v[78:81], v[130:133], v[162:165], v[78:81]
	v_mfma_f32_16x16x32_bf16 v[46:49], v[138:141], v[162:165], v[46:49]
	s_waitcnt lgkmcnt(6)
	v_mfma_f32_16x16x32_bf16 v[42:45], v[130:133], v[166:169], v[42:45]
	v_mfma_f32_16x16x32_bf16 v[38:41], v[138:141], v[166:169], v[38:41]
	s_waitcnt lgkmcnt(3)
	v_mfma_f32_16x16x32_bf16 v[34:37], v[130:133], v[178:181], v[34:37]
	v_mfma_f32_16x16x32_bf16 v[30:33], v[138:141], v[178:181], v[30:33]
	s_waitcnt lgkmcnt(2)
	v_mfma_f32_16x16x32_bf16 v[26:29], v[130:133], v[182:185], v[26:29]
	v_mfma_f32_16x16x32_bf16 v[22:25], v[138:141], v[182:185], v[22:25]
	v_mfma_f32_16x16x32_bf16 v[78:81], v[134:137], v[170:173], v[78:81]
	v_mfma_f32_16x16x32_bf16 v[46:49], v[142:145], v[170:173], v[46:49]
	v_mfma_f32_16x16x32_bf16 v[42:45], v[134:137], v[174:177], v[42:45]
	v_mfma_f32_16x16x32_bf16 v[38:41], v[142:145], v[174:177], v[38:41]
	s_waitcnt lgkmcnt(1)
	v_mfma_f32_16x16x32_bf16 v[34:37], v[134:137], v[186:189], v[34:37]
	v_mfma_f32_16x16x32_bf16 v[30:33], v[142:145], v[186:189], v[30:33]
	s_waitcnt lgkmcnt(0)
	v_mfma_f32_16x16x32_bf16 v[26:29], v[134:137], v[190:193], v[26:29]
	v_mfma_f32_16x16x32_bf16 v[22:25], v[142:145], v[190:193], v[22:25]
	v_mfma_f32_16x16x32_bf16 v[18:21], v[146:149], v[162:165], v[18:21]
	v_mfma_f32_16x16x32_bf16 v[14:17], v[154:157], v[162:165], v[14:17]
	v_mfma_f32_16x16x32_bf16 v[10:13], v[146:149], v[166:169], v[10:13]
	v_mfma_f32_16x16x32_bf16 v[6:9], v[154:157], v[166:169], v[6:9]
	v_mfma_f32_16x16x32_bf16 v[2:5], v[146:149], v[178:181], v[2:5]
	v_mfma_f32_16x16x32_bf16 v[126:129], v[154:157], v[178:181], v[126:129]
	v_mfma_f32_16x16x32_bf16 v[122:125], v[146:149], v[182:185], v[122:125]
	v_mfma_f32_16x16x32_bf16 v[118:121], v[154:157], v[182:185], v[118:121]
	v_mfma_f32_16x16x32_bf16 v[18:21], v[150:153], v[170:173], v[18:21]
	v_mfma_f32_16x16x32_bf16 v[14:17], v[158:161], v[170:173], v[14:17]
	v_mfma_f32_16x16x32_bf16 v[10:13], v[150:153], v[174:177], v[10:13]
	v_mfma_f32_16x16x32_bf16 v[6:9], v[158:161], v[174:177], v[6:9]
	v_mfma_f32_16x16x32_bf16 v[2:5], v[150:153], v[186:189], v[2:5]
	v_mfma_f32_16x16x32_bf16 v[126:129], v[158:161], v[186:189], v[126:129]
	v_mfma_f32_16x16x32_bf16 v[122:125], v[150:153], v[190:193], v[122:125]
	v_mfma_f32_16x16x32_bf16 v[118:121], v[158:161], v[190:193], v[118:121]
	s_barrier
	ds_read_b128 v[130:133], v194
	ds_read_b128 v[134:137], v224
	ds_read_b128 v[138:141], v225
	ds_read_b128 v[142:145], v228
	ds_read_b128 v[146:149], v229
	ds_read_b128 v[150:153], v230
	ds_read_b128 v[154:157], v231
	ds_read_b128 v[158:161], v233
	s_addk_i32 s61, 0x2000
	s_mov_b32 m0, s26
	ds_read_b128 v[162:165], v221 offset:32768
	ds_read_b128 v[166:169], v221 offset:34816
	ds_read_b128 v[170:173], v222 offset:32768
	ds_read_b128 v[174:177], v222 offset:34816
	ds_read_b128 v[178:181], v221 offset:36864
	ds_read_b128 v[182:185], v221 offset:38912
	ds_read_b128 v[186:189], v222 offset:36864
	ds_read_b128 v[190:193], v222 offset:38912
	buffer_load_dwordx4 v207, s[4:7], s61 offen lds
	s_mov_b32 m0, s27
	s_nop 0
	buffer_load_dwordx4 v209, s[4:7], s61 offen lds
	s_waitcnt vmcnt(8)
	s_waitcnt lgkmcnt(0)
	s_barrier
	s_waitcnt lgkmcnt(7)
	v_mfma_f32_16x16x32_bf16 v[114:117], v[130:133], v[162:165], v[114:117]
	v_mfma_f32_16x16x32_bf16 v[110:113], v[138:141], v[162:165], v[110:113]
	s_waitcnt lgkmcnt(6)
	v_mfma_f32_16x16x32_bf16 v[106:109], v[130:133], v[166:169], v[106:109]
	v_mfma_f32_16x16x32_bf16 v[102:105], v[138:141], v[166:169], v[102:105]
	s_waitcnt lgkmcnt(3)
	v_mfma_f32_16x16x32_bf16 v[98:101], v[130:133], v[178:181], v[98:101]
	v_mfma_f32_16x16x32_bf16 v[94:97], v[138:141], v[178:181], v[94:97]
	s_waitcnt lgkmcnt(2)
	v_mfma_f32_16x16x32_bf16 v[90:93], v[130:133], v[182:185], v[90:93]
	v_mfma_f32_16x16x32_bf16 v[86:89], v[138:141], v[182:185], v[86:89]
	v_mfma_f32_16x16x32_bf16 v[114:117], v[134:137], v[170:173], v[114:117]
	v_mfma_f32_16x16x32_bf16 v[110:113], v[142:145], v[170:173], v[110:113]
	v_mfma_f32_16x16x32_bf16 v[106:109], v[134:137], v[174:177], v[106:109]
	v_mfma_f32_16x16x32_bf16 v[102:105], v[142:145], v[174:177], v[102:105]
	s_waitcnt lgkmcnt(1)
	v_mfma_f32_16x16x32_bf16 v[98:101], v[134:137], v[186:189], v[98:101]
	v_mfma_f32_16x16x32_bf16 v[94:97], v[142:145], v[186:189], v[94:97]
	s_waitcnt lgkmcnt(0)
	v_mfma_f32_16x16x32_bf16 v[90:93], v[134:137], v[190:193], v[90:93]
	v_mfma_f32_16x16x32_bf16 v[86:89], v[142:145], v[190:193], v[86:89]
	v_mfma_f32_16x16x32_bf16 v[82:85], v[146:149], v[162:165], v[82:85]
	v_mfma_f32_16x16x32_bf16 v[74:77], v[154:157], v[162:165], v[74:77]
	v_mfma_f32_16x16x32_bf16 v[70:73], v[146:149], v[166:169], v[70:73]
	v_mfma_f32_16x16x32_bf16 v[66:69], v[154:157], v[166:169], v[66:69]
	v_mfma_f32_16x16x32_bf16 v[62:65], v[146:149], v[178:181], v[62:65]
	v_mfma_f32_16x16x32_bf16 v[58:61], v[154:157], v[178:181], v[58:61]
	v_mfma_f32_16x16x32_bf16 v[54:57], v[146:149], v[182:185], v[54:57]
	v_mfma_f32_16x16x32_bf16 v[50:53], v[154:157], v[182:185], v[50:53]
	v_mfma_f32_16x16x32_bf16 v[82:85], v[150:153], v[170:173], v[82:85]
	v_mfma_f32_16x16x32_bf16 v[74:77], v[158:161], v[170:173], v[74:77]
	v_mfma_f32_16x16x32_bf16 v[70:73], v[150:153], v[174:177], v[70:73]
	v_mfma_f32_16x16x32_bf16 v[66:69], v[158:161], v[174:177], v[66:69]
	v_mfma_f32_16x16x32_bf16 v[62:65], v[150:153], v[186:189], v[62:65]
	v_mfma_f32_16x16x32_bf16 v[58:61], v[158:161], v[186:189], v[58:61]
	v_mfma_f32_16x16x32_bf16 v[54:57], v[150:153], v[190:193], v[54:57]
	v_mfma_f32_16x16x32_bf16 v[50:53], v[158:161], v[190:193], v[50:53]
	s_barrier
	s_mov_b32 m0, s29
	s_add_i32 s61, s60, 0x80
	ds_read_b128 v[162:165], v221 offset:49152
	ds_read_b128 v[166:169], v221 offset:51200
	ds_read_b128 v[170:173], v222 offset:49152
	ds_read_b128 v[174:177], v222 offset:51200
	ds_read_b128 v[178:181], v221 offset:53248
	ds_read_b128 v[182:185], v221 offset:55296
	ds_read_b128 v[186:189], v222 offset:53248
	ds_read_b128 v[190:193], v222 offset:55296
	buffer_load_dwordx4 v208, s[4:7], s61 offen lds
	s_mov_b32 m0, s30
	s_add_i32 s60, s60, 0x40080
	buffer_load_dwordx4 v210, s[4:7], s61 offen lds
	s_mov_b32 m0, s35
	s_nop 0
	buffer_load_dwordx4 v208, s[4:7], s60 offen lds
	s_mov_b32 m0, s36
	s_nop 0
	buffer_load_dwordx4 v210, s[4:7], s60 offen lds
	s_mov_b32 m0, s31
	s_nop 0
	buffer_load_dwordx4 v207, s[4:7], s59 offen lds
	s_mov_b32 m0, s34
	s_nop 0
	buffer_load_dwordx4 v209, s[4:7], s59 offen lds
	s_waitcnt vmcnt(8)
	s_waitcnt lgkmcnt(0)
	s_barrier
	s_waitcnt lgkmcnt(7)
	v_mfma_f32_16x16x32_bf16 v[78:81], v[130:133], v[162:165], v[78:81]
	v_mfma_f32_16x16x32_bf16 v[46:49], v[138:141], v[162:165], v[46:49]
	s_waitcnt lgkmcnt(6)
	v_mfma_f32_16x16x32_bf16 v[42:45], v[130:133], v[166:169], v[42:45]
	v_mfma_f32_16x16x32_bf16 v[38:41], v[138:141], v[166:169], v[38:41]
	s_waitcnt lgkmcnt(3)
	v_mfma_f32_16x16x32_bf16 v[34:37], v[130:133], v[178:181], v[34:37]
	v_mfma_f32_16x16x32_bf16 v[30:33], v[138:141], v[178:181], v[30:33]
	s_waitcnt lgkmcnt(2)
	v_mfma_f32_16x16x32_bf16 v[26:29], v[130:133], v[182:185], v[26:29]
	v_mfma_f32_16x16x32_bf16 v[22:25], v[138:141], v[182:185], v[22:25]
	v_mfma_f32_16x16x32_bf16 v[78:81], v[134:137], v[170:173], v[78:81]
	v_mfma_f32_16x16x32_bf16 v[46:49], v[142:145], v[170:173], v[46:49]
	v_mfma_f32_16x16x32_bf16 v[42:45], v[134:137], v[174:177], v[42:45]
	v_mfma_f32_16x16x32_bf16 v[38:41], v[142:145], v[174:177], v[38:41]
	s_waitcnt lgkmcnt(1)
	v_mfma_f32_16x16x32_bf16 v[34:37], v[134:137], v[186:189], v[34:37]
	v_mfma_f32_16x16x32_bf16 v[30:33], v[142:145], v[186:189], v[30:33]
	s_waitcnt lgkmcnt(0)
	v_mfma_f32_16x16x32_bf16 v[26:29], v[134:137], v[190:193], v[26:29]
	v_mfma_f32_16x16x32_bf16 v[22:25], v[142:145], v[190:193], v[22:25]
	v_mfma_f32_16x16x32_bf16 v[18:21], v[146:149], v[162:165], v[18:21]
	v_mfma_f32_16x16x32_bf16 v[14:17], v[154:157], v[162:165], v[14:17]
	v_mfma_f32_16x16x32_bf16 v[10:13], v[146:149], v[166:169], v[10:13]
	v_mfma_f32_16x16x32_bf16 v[6:9], v[154:157], v[166:169], v[6:9]
	v_mfma_f32_16x16x32_bf16 v[2:5], v[146:149], v[178:181], v[2:5]
	v_mfma_f32_16x16x32_bf16 v[126:129], v[154:157], v[178:181], v[126:129]
	v_mfma_f32_16x16x32_bf16 v[122:125], v[146:149], v[182:185], v[122:125]
	v_mfma_f32_16x16x32_bf16 v[118:121], v[154:157], v[182:185], v[118:121]
	v_mfma_f32_16x16x32_bf16 v[18:21], v[150:153], v[170:173], v[18:21]
	v_mfma_f32_16x16x32_bf16 v[14:17], v[158:161], v[170:173], v[14:17]
	v_mfma_f32_16x16x32_bf16 v[10:13], v[150:153], v[174:177], v[10:13]
	v_mfma_f32_16x16x32_bf16 v[6:9], v[158:161], v[174:177], v[6:9]
	v_mfma_f32_16x16x32_bf16 v[2:5], v[150:153], v[186:189], v[2:5]
	v_mfma_f32_16x16x32_bf16 v[126:129], v[158:161], v[186:189], v[126:129]
	v_mfma_f32_16x16x32_bf16 v[122:125], v[150:153], v[190:193], v[122:125]
	v_mfma_f32_16x16x32_bf16 v[118:121], v[158:161], v[190:193], v[118:121]
	s_barrier
	s_add_i32 s58, s58, 2
	s_addk_i32 s33, 0x100
	s_addk_i32 s57, 0x100
	s_cmp_gt_u32 s58, 13
	s_cbranch_scc0 .LBB0_233
	s_and_b64 vcc, exec, s[16:17]
	s_cbranch_vccz .LBB0_236
	s_barrier

.LBB0_271:
	s_waitcnt lgkmcnt(13)
	v_mfma_scale_f32_16x16x128_f8f6f4 v[222:225], v[18:25], v[82:89], v[222:225], v250, v249 op_sel_hi:[0,0,0]
	s_waitcnt lgkmcnt(0)
	s_add_i32 s16, s56, 0x80
	s_add_i32 s17, s33, 0x80
	s_barrier
	v_mfma_scale_f32_16x16x128_f8f6f4 v[218:221], v[26:33], v[82:89], v[218:221], v250, v249 op_sel_hi:[0,0,0]
	s_waitcnt lgkmcnt(12)
	v_mfma_scale_f32_16x16x128_f8f6f4 v[214:217], v[18:25], v[74:81], v[214:217], v250, v249 op_sel_hi:[0,0,0]
	v_mfma_scale_f32_16x16x128_f8f6f4 v[210:213], v[26:33], v[74:81], v[210:213], v250, v249 op_sel_hi:[0,0,0]
	s_waitcnt lgkmcnt(9)
	v_mfma_scale_f32_16x16x128_f8f6f4 v[206:209], v[18:25], v[90:97], v[206:209], v250, v249 op_sel_hi:[0,0,0]
	v_mfma_scale_f32_16x16x128_f8f6f4 v[202:205], v[26:33], v[90:97], v[202:205], v250, v249 op_sel_hi:[0,0,0]
	s_waitcnt lgkmcnt(8)
	v_mfma_scale_f32_16x16x128_f8f6f4 v[198:201], v[18:25], v[34:41], v[198:201], v250, v249 op_sel_hi:[0,0,0]
	v_mfma_scale_f32_16x16x128_f8f6f4 v[194:197], v[26:33], v[34:41], v[194:197], v250, v249 op_sel_hi:[0,0,0]
	v_mfma_scale_f32_16x16x128_f8f6f4 v[166:169], v[2:9], v[82:89], v[166:169], v250, v249 op_sel_hi:[0,0,0]
	v_mfma_scale_f32_16x16x128_f8f6f4 v[130:133], v[10:17], v[34:41], v[130:133], v250, v249 op_sel_hi:[0,0,0]
	v_mfma_scale_f32_16x16x128_f8f6f4 v[82:85], v[10:17], v[82:89], v[154:157], v250, v249 op_sel_hi:[0,0,0]
	v_mfma_scale_f32_16x16x128_f8f6f4 v[86:89], v[2:9], v[74:81], v[150:153], v250, v249 op_sel_hi:[0,0,0]
	v_mfma_scale_f32_16x16x128_f8f6f4 v[74:77], v[10:17], v[74:81], v[146:149], v250, v249 op_sel_hi:[0,0,0]
	v_mfma_scale_f32_16x16x128_f8f6f4 v[78:81], v[2:9], v[90:97], v[142:145], v250, v249 op_sel_hi:[0,0,0]
	v_mfma_scale_f32_16x16x128_f8f6f4 v[90:93], v[10:17], v[90:97], v[138:141], v250, v249 op_sel_hi:[0,0,0]
	v_mfma_scale_f32_16x16x128_f8f6f4 v[94:97], v[2:9], v[34:41], v[134:137], v250, v249 op_sel_hi:[0,0,0]
	s_waitcnt lgkmcnt(5)
	v_mfma_scale_f32_16x16x128_f8f6f4 v[190:193], v[18:25], v[50:57], v[190:193], v250, v249 op_sel_hi:[0,0,0]
	v_mfma_scale_f32_16x16x128_f8f6f4 v[186:189], v[26:33], v[50:57], v[186:189], v250, v249 op_sel_hi:[0,0,0]
	s_waitcnt lgkmcnt(4)
	v_mfma_scale_f32_16x16x128_f8f6f4 v[182:185], v[18:25], v[42:49], v[182:185], v250, v249 op_sel_hi:[0,0,0]
	v_mfma_scale_f32_16x16x128_f8f6f4 v[178:181], v[26:33], v[42:49], v[178:181], v250, v249 op_sel_hi:[0,0,0]
	s_waitcnt lgkmcnt(1)
	v_mfma_scale_f32_16x16x128_f8f6f4 v[174:177], v[18:25], v[66:73], v[174:177], v250, v249 op_sel_hi:[0,0,0]
	v_mfma_scale_f32_16x16x128_f8f6f4 v[170:173], v[26:33], v[66:73], v[170:173], v250, v249 op_sel_hi:[0,0,0]
	s_waitcnt lgkmcnt(0)
	v_mfma_scale_f32_16x16x128_f8f6f4 v[162:165], v[18:25], v[58:65], v[162:165], v250, v249 op_sel_hi:[0,0,0]
	v_mfma_scale_f32_16x16x128_f8f6f4 v[158:161], v[26:33], v[58:65], v[158:161], v250, v249 op_sel_hi:[0,0,0]
	v_mfma_scale_f32_16x16x128_f8f6f4 v[126:129], v[2:9], v[50:57], v[126:129], v250, v249 op_sel_hi:[0,0,0]
	v_mfma_scale_f32_16x16x128_f8f6f4 v[122:125], v[10:17], v[50:57], v[122:125], v250, v249 op_sel_hi:[0,0,0]
	v_mfma_scale_f32_16x16x128_f8f6f4 v[118:121], v[2:9], v[42:49], v[118:121], v250, v249 op_sel_hi:[0,0,0]
	v_mfma_scale_f32_16x16x128_f8f6f4 v[114:117], v[10:17], v[42:49], v[114:117], v250, v249 op_sel_hi:[0,0,0]
	v_mfma_scale_f32_16x16x128_f8f6f4 v[110:113], v[2:9], v[66:73], v[110:113], v250, v249 op_sel_hi:[0,0,0]
	v_mfma_scale_f32_16x16x128_f8f6f4 v[98:101], v[10:17], v[58:65], v[98:101], v250, v249 op_sel_hi:[0,0,0]
	v_mfma_scale_f32_16x16x128_f8f6f4 v[66:69], v[10:17], v[66:73], v[106:109], v250, v249 op_sel_hi:[0,0,0]
	v_mfma_scale_f32_16x16x128_f8f6f4 v[70:73], v[2:9], v[58:65], v[102:105], v250, v249 op_sel_hi:[0,0,0]
	s_barrier
	s_add_i32 s4, 0, 0x18000
	v_add_u32_e32 v2, s4, v237
	v_add_u32_e32 v6, s4, v238
	s_add_i32 s4, 0, 0x1c000
	v_add_u32_e32 v10, s42, v237
	v_add_u32_e32 v14, s42, v238
	v_add_u32_e32 v18, s4, v237
	v_add_u32_e32 v22, s4, v238
	v_add_u32_e32 v26, s43, v237
	v_add_u32_e32 v30, s43, v238
	ds_read_b128 v[2:5], v2
	ds_read_b128 v[6:9], v6
	ds_read_b128 v[10:13], v10
	ds_read_b128 v[14:17], v14
	ds_read_b128 v[18:21], v18
	ds_read_b128 v[22:25], v22
	ds_read_b128 v[26:29], v26
	ds_read_b128 v[30:33], v30
	s_add_i32 s56, s56, 0x20000
	s_mov_b32 s4, s70
	s_mov_b32 m0, s27
	ds_read_b128 v[34:37], v247 offset:32768
	ds_read_b128 v[42:45], v247 offset:34816
	ds_read_b128 v[38:41], v248 offset:32768
	ds_read_b128 v[46:49], v248 offset:34816
	ds_read_b128 v[50:53], v247 offset:36864
	ds_read_b128 v[58:61], v247 offset:38912
	ds_read_b128 v[54:57], v248 offset:36864
	ds_read_b128 v[62:65], v248 offset:38912
	buffer_load_dwordx4 v233, s[4:7], s56 offen lds
	s_mov_b32 m0, s28
	s_nop 0
	buffer_load_dwordx4 v235, s[4:7], s56 offen lds
	s_waitcnt vmcnt(8)
	s_waitcnt lgkmcnt(0)
	s_barrier
	s_waitcnt lgkmcnt(5)
	v_mfma_scale_f32_16x16x128_f8f6f4 v[222:225], v[2:9], v[34:41], v[222:225], v250, v249 op_sel_hi:[0,0,0]
	v_mfma_scale_f32_16x16x128_f8f6f4 v[218:221], v[10:17], v[34:41], v[218:221], v250, v249 op_sel_hi:[0,0,0]
	s_waitcnt lgkmcnt(4)
	v_mfma_scale_f32_16x16x128_f8f6f4 v[214:217], v[2:9], v[42:49], v[214:217], v250, v249 op_sel_hi:[0,0,0]
	v_mfma_scale_f32_16x16x128_f8f6f4 v[210:213], v[10:17], v[42:49], v[210:213], v250, v249 op_sel_hi:[0,0,0]
	s_waitcnt lgkmcnt(1)
	v_mfma_scale_f32_16x16x128_f8f6f4 v[206:209], v[2:9], v[50:57], v[206:209], v250, v249 op_sel_hi:[0,0,0]
	v_mfma_scale_f32_16x16x128_f8f6f4 v[202:205], v[10:17], v[50:57], v[202:205], v250, v249 op_sel_hi:[0,0,0]
	s_waitcnt lgkmcnt(0)
	v_mfma_scale_f32_16x16x128_f8f6f4 v[198:201], v[2:9], v[58:65], v[198:201], v250, v249 op_sel_hi:[0,0,0]
	v_mfma_scale_f32_16x16x128_f8f6f4 v[194:197], v[10:17], v[58:65], v[194:197], v250, v249 op_sel_hi:[0,0,0]
	v_mfma_scale_f32_16x16x128_f8f6f4 v[166:169], v[18:25], v[34:41], v[166:169], v250, v249 op_sel_hi:[0,0,0]
	v_mfma_scale_f32_16x16x128_f8f6f4 v[154:157], v[26:33], v[34:41], v[82:85], v250, v249 op_sel_hi:[0,0,0]
	v_mfma_scale_f32_16x16x128_f8f6f4 v[150:153], v[18:25], v[42:49], v[86:89], v250, v249 op_sel_hi:[0,0,0]
	v_mfma_scale_f32_16x16x128_f8f6f4 v[146:149], v[26:33], v[42:49], v[74:77], v250, v249 op_sel_hi:[0,0,0]
	v_mfma_scale_f32_16x16x128_f8f6f4 v[142:145], v[18:25], v[50:57], v[78:81], v250, v249 op_sel_hi:[0,0,0]
	v_mfma_scale_f32_16x16x128_f8f6f4 v[138:141], v[26:33], v[50:57], v[90:93], v250, v249 op_sel_hi:[0,0,0]
	v_mfma_scale_f32_16x16x128_f8f6f4 v[134:137], v[18:25], v[58:65], v[94:97], v250, v249 op_sel_hi:[0,0,0]
	v_mfma_scale_f32_16x16x128_f8f6f4 v[130:133], v[26:33], v[58:65], v[130:133], v250, v249 op_sel_hi:[0,0,0]
	s_barrier
	s_mov_b32 m0, s29
	ds_read_b128 v[34:37], v247 offset:49152
	ds_read_b128 v[42:45], v247 offset:51200
	ds_read_b128 v[38:41], v248 offset:49152
	ds_read_b128 v[46:49], v248 offset:51200
	ds_read_b128 v[50:53], v247 offset:53248
	ds_read_b128 v[58:61], v247 offset:55296
	ds_read_b128 v[54:57], v248 offset:53248
	ds_read_b128 v[62:65], v248 offset:55296
	buffer_load_dwordx4 v234, s[4:7], s17 offen lds
	s_mov_b32 m0, s30
	s_add_i32 s33, s33, 0x20080
	buffer_load_dwordx4 v236, s[4:7], s17 offen lds
	s_mov_b32 m0, s35
	s_nop 0
	buffer_load_dwordx4 v234, s[4:7], s33 offen lds
	s_mov_b32 m0, s36
	s_nop 0
	buffer_load_dwordx4 v236, s[4:7], s33 offen lds
	s_mov_b32 m0, s31
	s_nop 0
	buffer_load_dwordx4 v233, s[4:7], s16 offen lds
	s_mov_b32 m0, s34
	s_nop 0
	buffer_load_dwordx4 v235, s[4:7], s16 offen lds
	s_waitcnt vmcnt(8)
	s_waitcnt lgkmcnt(0)
	s_barrier
	s_waitcnt lgkmcnt(5)
	v_mfma_scale_f32_16x16x128_f8f6f4 v[190:193], v[2:9], v[34:41], v[190:193], v250, v249 op_sel_hi:[0,0,0]
	v_mfma_scale_f32_16x16x128_f8f6f4 v[186:189], v[10:17], v[34:41], v[186:189], v250, v249 op_sel_hi:[0,0,0]
	s_waitcnt lgkmcnt(4)
	v_mfma_scale_f32_16x16x128_f8f6f4 v[182:185], v[2:9], v[42:49], v[182:185], v250, v249 op_sel_hi:[0,0,0]
	v_mfma_scale_f32_16x16x128_f8f6f4 v[178:181], v[10:17], v[42:49], v[178:181], v250, v249 op_sel_hi:[0,0,0]
	s_waitcnt lgkmcnt(1)
	v_mfma_scale_f32_16x16x128_f8f6f4 v[174:177], v[2:9], v[50:57], v[174:177], v250, v249 op_sel_hi:[0,0,0]
	v_mfma_scale_f32_16x16x128_f8f6f4 v[170:173], v[10:17], v[50:57], v[170:173], v250, v249 op_sel_hi:[0,0,0]
	s_waitcnt lgkmcnt(0)
	v_mfma_scale_f32_16x16x128_f8f6f4 v[162:165], v[2:9], v[58:65], v[162:165], v250, v249 op_sel_hi:[0,0,0]
	v_mfma_scale_f32_16x16x128_f8f6f4 v[158:161], v[10:17], v[58:65], v[158:161], v250, v249 op_sel_hi:[0,0,0]
	v_mfma_scale_f32_16x16x128_f8f6f4 v[126:129], v[18:25], v[34:41], v[126:129], v250, v249 op_sel_hi:[0,0,0]
	v_mfma_scale_f32_16x16x128_f8f6f4 v[122:125], v[26:33], v[34:41], v[122:125], v250, v249 op_sel_hi:[0,0,0]
	v_mfma_scale_f32_16x16x128_f8f6f4 v[118:121], v[18:25], v[42:49], v[118:121], v250, v249 op_sel_hi:[0,0,0]
	v_mfma_scale_f32_16x16x128_f8f6f4 v[114:117], v[26:33], v[42:49], v[114:117], v250, v249 op_sel_hi:[0,0,0]
	v_mfma_scale_f32_16x16x128_f8f6f4 v[110:113], v[18:25], v[50:57], v[110:113], v250, v249 op_sel_hi:[0,0,0]
	v_mfma_scale_f32_16x16x128_f8f6f4 v[106:109], v[26:33], v[50:57], v[66:69], v250, v249 op_sel_hi:[0,0,0]
	v_mfma_scale_f32_16x16x128_f8f6f4 v[102:105], v[18:25], v[58:65], v[70:73], v250, v249 op_sel_hi:[0,0,0]
	v_mfma_scale_f32_16x16x128_f8f6f4 v[98:101], v[26:33], v[58:65], v[98:101], v250, v249 op_sel_hi:[0,0,0]
	s_barrier
	s_add_i32 s55, s55, 2
	s_addk_i32 s53, 0x100
	s_addk_i32 s54, 0x100
	s_cmp_gt_u32 s55, 5
	s_cbranch_scc1 .LBB0_280

.LBB0_276:
	s_add_i32 s4, s53, 0xfffe0080
	s_waitcnt lgkmcnt(0)
	s_cmp_eq_u32 s55, 4
	s_cselect_b32 s56, s51, s4
	s_cselect_b32 s33, s52, s54
	s_barrier
	s_barrier
	s_mov_b32 m0, s22
	s_mov_b32 s4, s70
	ds_read_b128 v[50:53], v247 offset:16384
	ds_read_b128 v[42:45], v247 offset:18432
	ds_read_b128 v[54:57], v248 offset:16384
	ds_read_b128 v[46:49], v248 offset:18432
	ds_read_b128 v[66:69], v247 offset:20480
	ds_read_b128 v[58:61], v247 offset:22528
	ds_read_b128 v[70:73], v248 offset:20480
	ds_read_b128 v[62:65], v248 offset:22528
	buffer_load_dwordx4 v234, s[4:7], s33 offen lds
	s_mov_b32 m0, s23
	s_add_i32 s18, s33, 0x20000
	buffer_load_dwordx4 v236, s[4:7], s33 offen lds
	s_mov_b32 m0, s24
	s_and_b64 vcc, exec, s[16:17]
	buffer_load_dwordx4 v234, s[4:7], s18 offen lds
	s_mov_b32 m0, s25
	s_nop 0
	buffer_load_dwordx4 v236, s[4:7], s18 offen lds
	s_mov_b32 m0, s21
	s_mov_b64 s[18:19], -1
	buffer_load_dwordx4 v233, s[4:7], s56 offen lds
	s_mov_b32 m0, s26
	s_nop 0
	buffer_load_dwordx4 v235, s[4:7], s56 offen lds
	s_cbranch_vccz .LBB0_278
	s_waitcnt vmcnt(8)
	s_mov_b64 s[18:19], 0

.LBB0_379:
	s_waitcnt lgkmcnt(0)
	s_add_i32 s2, s23, 0x100
	s_add_i32 s3, s4, 0x100
	s_barrier
	s_waitcnt lgkmcnt(7)
	v_mfma_f32_16x16x32_bf16 v[126:129], v[158:161], v[186:189], 0
	v_mfma_f32_16x16x32_bf16 v[122:125], v[150:153], v[186:189], 0
	s_waitcnt lgkmcnt(6)
	v_mfma_f32_16x16x32_bf16 v[118:121], v[158:161], v[178:181], 0
	v_mfma_f32_16x16x32_bf16 v[114:117], v[150:153], v[178:181], 0
	s_waitcnt lgkmcnt(3)
	v_mfma_f32_16x16x32_bf16 v[110:113], v[158:161], v[170:173], 0
	v_mfma_f32_16x16x32_bf16 v[106:109], v[150:153], v[170:173], 0
	s_waitcnt lgkmcnt(2)
	v_mfma_f32_16x16x32_bf16 v[102:105], v[158:161], v[162:165], 0
	v_mfma_f32_16x16x32_bf16 v[98:101], v[150:153], v[162:165], 0
	v_mfma_f32_16x16x32_bf16 v[126:129], v[154:157], v[190:193], v[126:129]
	v_mfma_f32_16x16x32_bf16 v[122:125], v[146:149], v[190:193], v[122:125]
	v_mfma_f32_16x16x32_bf16 v[118:121], v[154:157], v[182:185], v[118:121]
	v_mfma_f32_16x16x32_bf16 v[114:117], v[146:149], v[182:185], v[114:117]
	s_waitcnt lgkmcnt(1)
	v_mfma_f32_16x16x32_bf16 v[110:113], v[154:157], v[174:177], v[110:113]
	v_mfma_f32_16x16x32_bf16 v[106:109], v[146:149], v[174:177], v[106:109]
	s_waitcnt lgkmcnt(0)
	v_mfma_f32_16x16x32_bf16 v[102:105], v[154:157], v[166:169], v[102:105]
	v_mfma_f32_16x16x32_bf16 v[98:101], v[146:149], v[166:169], v[98:101]
	s_nop 0
	s_barrier
	s_mov_b32 m0, s28
	ds_read_b128 v[186:189], v216 offset:16384
	ds_read_b128 v[178:181], v216 offset:18432
	ds_read_b128 v[190:193], v217 offset:16384
	ds_read_b128 v[182:185], v217 offset:18432
	ds_read_b128 v[170:173], v216 offset:20480
	ds_read_b128 v[162:165], v216 offset:22528
	ds_read_b128 v[174:177], v217 offset:20480
	ds_read_b128 v[166:169], v217 offset:22528
	buffer_load_dwordx4 v203, s[8:11], s3 offen lds
	s_mov_b32 m0, s29
	v_cndmask_b32_e64 v218, 0, 1, s[24:25]
	buffer_load_dwordx4 v205, s[8:11], s3 offen lds
	s_add_i32 s3, s4, 0x10100
	s_mov_b32 m0, s30
	s_andn2_b64 vcc, exec, s[24:25]
	buffer_load_dwordx4 v203, s[8:11], s3 offen lds
	s_mov_b32 m0, s31
	s_mov_b64 s[24:25], -1
	buffer_load_dwordx4 v205, s[8:11], s3 offen lds
	s_mov_b32 m0, s27
	s_nop 0
	buffer_load_dwordx4 v198, s[8:11], s2 offen lds
	s_mov_b32 m0, s34
	s_nop 0
	buffer_load_dwordx4 v204, s[8:11], s2 offen lds
	v_cmp_ne_u32_e64 s[2:3], 1, v218
	s_cbranch_vccnz .LBB0_381
	s_waitcnt vmcnt(22)
	s_mov_b64 s[24:25], 0

.LBB0_383:
	s_waitcnt lgkmcnt(0)
	s_barrier
	s_waitcnt lgkmcnt(7)
	v_mfma_f32_16x16x32_bf16 v[62:65], v[158:161], v[186:189], 0
	v_mfma_f32_16x16x32_bf16 v[58:61], v[150:153], v[186:189], 0
	s_waitcnt lgkmcnt(6)
	v_mfma_f32_16x16x32_bf16 v[54:57], v[158:161], v[178:181], 0
	v_mfma_f32_16x16x32_bf16 v[50:53], v[150:153], v[178:181], 0
	s_waitcnt lgkmcnt(3)
	v_mfma_f32_16x16x32_bf16 v[46:49], v[158:161], v[170:173], 0
	v_mfma_f32_16x16x32_bf16 v[42:45], v[150:153], v[170:173], 0
	s_waitcnt lgkmcnt(2)
	v_mfma_f32_16x16x32_bf16 v[38:41], v[158:161], v[162:165], 0
	v_mfma_f32_16x16x32_bf16 v[34:37], v[150:153], v[162:165], 0
	v_mfma_f32_16x16x32_bf16 v[62:65], v[154:157], v[190:193], v[62:65]
	v_mfma_f32_16x16x32_bf16 v[58:61], v[146:149], v[190:193], v[58:61]
	v_mfma_f32_16x16x32_bf16 v[54:57], v[154:157], v[182:185], v[54:57]
	v_mfma_f32_16x16x32_bf16 v[50:53], v[146:149], v[182:185], v[50:53]
	s_waitcnt lgkmcnt(1)
	v_mfma_f32_16x16x32_bf16 v[46:49], v[154:157], v[174:177], v[46:49]
	v_mfma_f32_16x16x32_bf16 v[42:45], v[146:149], v[174:177], v[42:45]
	s_waitcnt lgkmcnt(0)
	v_mfma_f32_16x16x32_bf16 v[38:41], v[154:157], v[166:169], v[38:41]
	v_mfma_f32_16x16x32_bf16 v[34:37], v[146:149], v[166:169], v[34:37]
	s_nop 0
	s_barrier
	v_add_u32_e32 v218, s48, v206
	v_add_u32_e32 v220, s49, v206
	v_add_u32_e32 v222, s50, v206
	v_add_u32_e32 v224, s51, v206
	v_add_u32_e32 v219, s48, v207
	ds_read_b128 v[146:149], v218
	ds_read_b128 v[150:153], v219
	v_add_u32_e32 v221, s49, v207
	ds_read_b128 v[154:157], v220
	ds_read_b128 v[158:161], v221
	v_add_u32_e32 v223, s50, v207
	ds_read_b128 v[130:133], v222
	ds_read_b128 v[134:137], v223
	v_add_u32_e32 v225, s51, v207
	ds_read_b128 v[138:141], v224
	ds_read_b128 v[142:145], v225
	s_mov_b32 m0, s35
	s_add_i32 s24, s23, 0xd00
	ds_read_b128 v[186:189], v216 offset:32768
	ds_read_b128 v[174:177], v216 offset:34816
	ds_read_b128 v[190:193], v217 offset:32768
	ds_read_b128 v[178:181], v217 offset:34816
	ds_read_b128 v[170:173], v216 offset:36864
	ds_read_b128 v[162:165], v216 offset:38912
	ds_read_b128 v[182:185], v217 offset:36864
	ds_read_b128 v[166:169], v217 offset:38912
	buffer_load_dwordx4 v198, s[8:11], s24 offen lds
	s_mov_b32 m0, s36
	s_and_b64 vcc, exec, s[2:3]
	buffer_load_dwordx4 v204, s[8:11], s24 offen lds
	s_mov_b64 s[24:25], -1
	s_cbranch_vccnz .LBB0_385
	s_waitcnt vmcnt(24)
	s_mov_b64 s[24:25], 0

.LBB0_387:
	s_waitcnt lgkmcnt(0)
	s_add_i32 s24, s23, 0x180
	s_add_i32 s25, s4, 0x180
	s_barrier
	s_waitcnt lgkmcnt(7)
	v_mfma_f32_16x16x32_bf16 v[126:129], v[146:149], v[186:189], v[126:129]
	v_mfma_f32_16x16x32_bf16 v[122:125], v[154:157], v[186:189], v[122:125]
	s_waitcnt lgkmcnt(6)
	v_mfma_f32_16x16x32_bf16 v[118:121], v[146:149], v[174:177], v[118:121]
	v_mfma_f32_16x16x32_bf16 v[114:117], v[154:157], v[174:177], v[114:117]
	s_waitcnt lgkmcnt(3)
	v_mfma_f32_16x16x32_bf16 v[110:113], v[146:149], v[170:173], v[110:113]
	v_mfma_f32_16x16x32_bf16 v[106:109], v[154:157], v[170:173], v[106:109]
	s_waitcnt lgkmcnt(2)
	v_mfma_f32_16x16x32_bf16 v[102:105], v[146:149], v[162:165], v[102:105]
	v_mfma_f32_16x16x32_bf16 v[98:101], v[154:157], v[162:165], v[98:101]
	v_mfma_f32_16x16x32_bf16 v[126:129], v[150:153], v[190:193], v[126:129]
	v_mfma_f32_16x16x32_bf16 v[122:125], v[158:161], v[190:193], v[122:125]
	v_mfma_f32_16x16x32_bf16 v[118:121], v[150:153], v[178:181], v[118:121]
	v_mfma_f32_16x16x32_bf16 v[114:117], v[158:161], v[178:181], v[114:117]
	s_waitcnt lgkmcnt(1)
	v_mfma_f32_16x16x32_bf16 v[110:113], v[150:153], v[182:185], v[110:113]
	v_mfma_f32_16x16x32_bf16 v[106:109], v[158:161], v[182:185], v[106:109]
	s_waitcnt lgkmcnt(0)
	v_mfma_f32_16x16x32_bf16 v[102:105], v[150:153], v[166:169], v[102:105]
	v_mfma_f32_16x16x32_bf16 v[98:101], v[158:161], v[166:169], v[98:101]
	s_barrier
	s_mov_b32 m0, s37
	ds_read_b128 v[186:189], v216 offset:49152
	ds_read_b128 v[174:177], v216 offset:51200
	ds_read_b128 v[190:193], v217 offset:49152
	ds_read_b128 v[178:181], v217 offset:51200
	ds_read_b128 v[170:173], v216 offset:53248
	ds_read_b128 v[162:165], v216 offset:55296
	ds_read_b128 v[182:185], v217 offset:53248
	ds_read_b128 v[166:169], v217 offset:55296
	buffer_load_dwordx4 v203, s[8:11], s25 offen lds
	s_mov_b32 m0, s38
	s_and_b64 vcc, exec, s[2:3]
	buffer_load_dwordx4 v205, s[8:11], s25 offen lds
	s_add_i32 s25, s4, 0x10180
	s_mov_b32 m0, s42
	s_mov_b64 s[2:3], -1
	buffer_load_dwordx4 v203, s[8:11], s25 offen lds
	s_mov_b32 m0, s43
	s_nop 0
	buffer_load_dwordx4 v205, s[8:11], s25 offen lds
	s_mov_b32 m0, s40
	s_nop 0
	buffer_load_dwordx4 v198, s[8:11], s24 offen lds
	s_mov_b32 m0, s41
	s_nop 0
	buffer_load_dwordx4 v204, s[8:11], s24 offen lds
	s_cbranch_vccnz .LBB0_389
	s_waitcnt vmcnt(30)
	s_mov_b64 s[2:3], 0

.LBB0_391:
	s_waitcnt lgkmcnt(0)
	s_barrier
	s_waitcnt lgkmcnt(7)
	v_mfma_f32_16x16x32_bf16 v[62:65], v[146:149], v[186:189], v[62:65]
	v_mfma_f32_16x16x32_bf16 v[58:61], v[154:157], v[186:189], v[58:61]
	s_waitcnt lgkmcnt(6)
	v_mfma_f32_16x16x32_bf16 v[54:57], v[146:149], v[174:177], v[54:57]
	v_mfma_f32_16x16x32_bf16 v[50:53], v[154:157], v[174:177], v[50:53]
	s_waitcnt lgkmcnt(3)
	v_mfma_f32_16x16x32_bf16 v[46:49], v[146:149], v[170:173], v[46:49]
	v_mfma_f32_16x16x32_bf16 v[42:45], v[154:157], v[170:173], v[42:45]
	s_waitcnt lgkmcnt(2)
	v_mfma_f32_16x16x32_bf16 v[38:41], v[146:149], v[162:165], v[38:41]
	v_mfma_f32_16x16x32_bf16 v[34:37], v[154:157], v[162:165], v[34:37]
	v_mfma_f32_16x16x32_bf16 v[62:65], v[150:153], v[190:193], v[62:65]
	v_mfma_f32_16x16x32_bf16 v[58:61], v[158:161], v[190:193], v[58:61]
	v_mfma_f32_16x16x32_bf16 v[54:57], v[150:153], v[178:181], v[54:57]
	v_mfma_f32_16x16x32_bf16 v[50:53], v[158:161], v[178:181], v[50:53]
	s_waitcnt lgkmcnt(1)
	v_mfma_f32_16x16x32_bf16 v[46:49], v[150:153], v[182:185], v[46:49]
	v_mfma_f32_16x16x32_bf16 v[42:45], v[158:161], v[182:185], v[42:45]
	s_waitcnt lgkmcnt(0)
	v_mfma_f32_16x16x32_bf16 v[38:41], v[150:153], v[166:169], v[38:41]
	v_mfma_f32_16x16x32_bf16 v[34:37], v[158:161], v[166:169], v[34:37]
	s_barrier
	ds_read_b128 v[130:133], v208
	ds_read_b128 v[134:137], v209
	ds_read_b128 v[138:141], v210
	ds_read_b128 v[142:145], v211
	ds_read_b128 v[146:149], v212
	ds_read_b128 v[150:153], v213
	ds_read_b128 v[154:157], v214
	ds_read_b128 v[158:161], v215
	s_add_i32 s24, s55, s26
	s_and_b64 s[2:3], s[18:19], exec
	s_cselect_b32 s2, s24, s33
	s_mul_i32 s25, s2, 0x30000
	s_add_i32 s25, s25, 0xc000000
	s_and_b64 s[2:3], s[18:19], exec
	s_cselect_b32 s2, s25, s23
	s_lshl_b32 s3, s24, 12
	s_and_b32 s54, s3, 0xffff0000
	s_add_i32 s54, s54, 0x3000000
	s_and_b64 s[56:57], s[18:19], exec
	s_cselect_b32 s33, s54, s4
	s_add_i32 s3, s2, 0x80
	s_addk_i32 s23, 0xd80
	s_mov_b32 s4, s70
	s_mov_b32 m0, s44
	ds_read_b128 v[162:165], v216
	ds_read_b128 v[166:169], v216 offset:2048
	ds_read_b128 v[170:173], v217
	ds_read_b128 v[174:177], v217 offset:2048
	ds_read_b128 v[178:181], v216 offset:4096
	ds_read_b128 v[182:185], v216 offset:6144
	ds_read_b128 v[186:189], v217 offset:4096
	ds_read_b128 v[190:193], v217 offset:6144
	buffer_load_dwordx4 v198, s[4:7], s23 offen lds
	s_mov_b32 m0, s47
	s_nop 0
	buffer_load_dwordx4 v204, s[4:7], s23 offen lds
	s_waitcnt vmcnt(8)
	s_waitcnt lgkmcnt(0)
	s_barrier
	s_waitcnt lgkmcnt(7)
	v_mfma_f32_16x16x32_bf16 v[126:129], v[130:133], v[162:165], v[126:129]
	v_mfma_f32_16x16x32_bf16 v[122:125], v[138:141], v[162:165], v[122:125]
	s_waitcnt lgkmcnt(6)
	v_mfma_f32_16x16x32_bf16 v[118:121], v[130:133], v[166:169], v[118:121]
	v_mfma_f32_16x16x32_bf16 v[114:117], v[138:141], v[166:169], v[114:117]
	s_waitcnt lgkmcnt(3)
	v_mfma_f32_16x16x32_bf16 v[110:113], v[130:133], v[178:181], v[110:113]
	v_mfma_f32_16x16x32_bf16 v[106:109], v[138:141], v[178:181], v[106:109]
	s_waitcnt lgkmcnt(2)
	v_mfma_f32_16x16x32_bf16 v[102:105], v[130:133], v[182:185], v[102:105]
	v_mfma_f32_16x16x32_bf16 v[98:101], v[138:141], v[182:185], v[98:101]
	v_mfma_f32_16x16x32_bf16 v[126:129], v[134:137], v[170:173], v[126:129]
	v_mfma_f32_16x16x32_bf16 v[122:125], v[142:145], v[170:173], v[122:125]
	v_mfma_f32_16x16x32_bf16 v[118:121], v[134:137], v[174:177], v[118:121]
	v_mfma_f32_16x16x32_bf16 v[114:117], v[142:145], v[174:177], v[114:117]
	s_waitcnt lgkmcnt(1)
	v_mfma_f32_16x16x32_bf16 v[110:113], v[134:137], v[186:189], v[110:113]
	v_mfma_f32_16x16x32_bf16 v[106:109], v[142:145], v[186:189], v[106:109]
	s_waitcnt lgkmcnt(0)
	v_mfma_f32_16x16x32_bf16 v[102:105], v[134:137], v[190:193], v[102:105]
	v_mfma_f32_16x16x32_bf16 v[98:101], v[142:145], v[190:193], v[98:101]
	s_barrier
	s_mov_b32 m0, s28
	ds_read_b128 v[162:165], v216 offset:16384
	ds_read_b128 v[166:169], v216 offset:18432
	ds_read_b128 v[170:173], v217 offset:16384
	ds_read_b128 v[174:177], v217 offset:18432
	ds_read_b128 v[178:181], v216 offset:20480
	ds_read_b128 v[182:185], v216 offset:22528
	ds_read_b128 v[186:189], v217 offset:20480
	ds_read_b128 v[190:193], v217 offset:22528
	buffer_load_dwordx4 v203, s[4:7], s33 offen lds
	s_mov_b32 m0, s29
	s_add_i32 s23, s33, 0x10000
	buffer_load_dwordx4 v205, s[4:7], s33 offen lds
	s_mov_b32 m0, s30
	s_nop 0
	buffer_load_dwordx4 v203, s[4:7], s23 offen lds
	s_mov_b32 m0, s31
	s_nop 0
	buffer_load_dwordx4 v205, s[4:7], s23 offen lds
	s_mov_b32 m0, s27
	s_nop 0
	buffer_load_dwordx4 v198, s[4:7], s2 offen lds
	s_mov_b32 m0, s34
	s_nop 0
	buffer_load_dwordx4 v204, s[4:7], s2 offen lds
	s_waitcnt vmcnt(8)
	s_waitcnt lgkmcnt(0)
	s_barrier
	s_waitcnt lgkmcnt(7)
	v_mfma_f32_16x16x32_bf16 v[62:65], v[130:133], v[162:165], v[62:65]
	v_mfma_f32_16x16x32_bf16 v[58:61], v[138:141], v[162:165], v[58:61]
	s_waitcnt lgkmcnt(6)
	v_mfma_f32_16x16x32_bf16 v[54:57], v[130:133], v[166:169], v[54:57]
	v_mfma_f32_16x16x32_bf16 v[50:53], v[138:141], v[166:169], v[50:53]
	s_waitcnt lgkmcnt(3)
	v_mfma_f32_16x16x32_bf16 v[46:49], v[130:133], v[178:181], v[46:49]
	v_mfma_f32_16x16x32_bf16 v[42:45], v[138:141], v[178:181], v[42:45]
	s_waitcnt lgkmcnt(2)
	v_mfma_f32_16x16x32_bf16 v[38:41], v[130:133], v[182:185], v[38:41]
	v_mfma_f32_16x16x32_bf16 v[34:37], v[138:141], v[182:185], v[34:37]
	v_mfma_f32_16x16x32_bf16 v[62:65], v[134:137], v[170:173], v[62:65]
	v_mfma_f32_16x16x32_bf16 v[58:61], v[142:145], v[170:173], v[58:61]
	v_mfma_f32_16x16x32_bf16 v[54:57], v[134:137], v[174:177], v[54:57]
	v_mfma_f32_16x16x32_bf16 v[50:53], v[142:145], v[174:177], v[50:53]
	s_waitcnt lgkmcnt(1)
	v_mfma_f32_16x16x32_bf16 v[46:49], v[134:137], v[186:189], v[46:49]
	v_mfma_f32_16x16x32_bf16 v[42:45], v[142:145], v[186:189], v[42:45]
	s_waitcnt lgkmcnt(0)
	v_mfma_f32_16x16x32_bf16 v[38:41], v[134:137], v[190:193], v[38:41]
	v_mfma_f32_16x16x32_bf16 v[34:37], v[142:145], v[190:193], v[34:37]
	s_barrier
	ds_read_b128 v[130:133], v218
	ds_read_b128 v[134:137], v219
	ds_read_b128 v[138:141], v220
	ds_read_b128 v[142:145], v221
	ds_read_b128 v[146:149], v222
	ds_read_b128 v[150:153], v223
	ds_read_b128 v[154:157], v224
	ds_read_b128 v[158:161], v225
	s_add_i32 s23, s2, 0xc00
	s_mov_b32 m0, s35
	ds_read_b128 v[162:165], v216 offset:32768
	ds_read_b128 v[166:169], v216 offset:34816
	ds_read_b128 v[170:173], v217 offset:32768
	ds_read_b128 v[174:177], v217 offset:34816
	ds_read_b128 v[178:181], v216 offset:36864
	ds_read_b128 v[182:185], v216 offset:38912
	ds_read_b128 v[186:189], v217 offset:36864
	ds_read_b128 v[190:193], v217 offset:38912
	buffer_load_dwordx4 v198, s[4:7], s23 offen lds
	s_mov_b32 m0, s36
	s_nop 0
	buffer_load_dwordx4 v204, s[4:7], s23 offen lds
	s_waitcnt vmcnt(8)
	s_waitcnt lgkmcnt(0)
	s_barrier
	s_waitcnt lgkmcnt(7)
	v_mfma_f32_16x16x32_bf16 v[126:129], v[130:133], v[162:165], v[126:129]
	v_mfma_f32_16x16x32_bf16 v[122:125], v[138:141], v[162:165], v[122:125]
	s_waitcnt lgkmcnt(6)
	v_mfma_f32_16x16x32_bf16 v[118:121], v[130:133], v[166:169], v[118:121]
	v_mfma_f32_16x16x32_bf16 v[114:117], v[138:141], v[166:169], v[114:117]
	s_waitcnt lgkmcnt(3)
	v_mfma_f32_16x16x32_bf16 v[110:113], v[130:133], v[178:181], v[110:113]
	v_mfma_f32_16x16x32_bf16 v[106:109], v[138:141], v[178:181], v[106:109]
	s_waitcnt lgkmcnt(2)
	v_mfma_f32_16x16x32_bf16 v[102:105], v[130:133], v[182:185], v[102:105]
	v_mfma_f32_16x16x32_bf16 v[98:101], v[138:141], v[182:185], v[98:101]
	v_mfma_f32_16x16x32_bf16 v[126:129], v[134:137], v[170:173], v[126:129]
	v_mfma_f32_16x16x32_bf16 v[122:125], v[142:145], v[170:173], v[122:125]
	v_mfma_f32_16x16x32_bf16 v[118:121], v[134:137], v[174:177], v[118:121]
	v_mfma_f32_16x16x32_bf16 v[114:117], v[142:145], v[174:177], v[114:117]
	s_waitcnt lgkmcnt(1)
	v_mfma_f32_16x16x32_bf16 v[110:113], v[134:137], v[186:189], v[110:113]
	v_mfma_f32_16x16x32_bf16 v[106:109], v[142:145], v[186:189], v[106:109]
	s_waitcnt lgkmcnt(0)
	v_mfma_f32_16x16x32_bf16 v[102:105], v[134:137], v[190:193], v[102:105]
	v_mfma_f32_16x16x32_bf16 v[98:101], v[142:145], v[190:193], v[98:101]
	s_barrier
	s_mov_b32 m0, s37
	s_add_i32 s23, s33, 0x80
	ds_read_b128 v[162:165], v216 offset:49152
	ds_read_b128 v[166:169], v216 offset:51200
	ds_read_b128 v[170:173], v217 offset:49152
	ds_read_b128 v[174:177], v217 offset:51200
	ds_read_b128 v[178:181], v216 offset:53248
	ds_read_b128 v[182:185], v216 offset:55296
	ds_read_b128 v[186:189], v217 offset:53248
	ds_read_b128 v[190:193], v217 offset:55296
	buffer_load_dwordx4 v203, s[4:7], s23 offen lds
	s_mov_b32 m0, s38
	s_add_i32 s33, s33, 0x10080
	buffer_load_dwordx4 v205, s[4:7], s23 offen lds
	s_mov_b32 m0, s42
	s_nop 0
	buffer_load_dwordx4 v203, s[4:7], s33 offen lds
	s_mov_b32 m0, s43
	s_nop 0
	buffer_load_dwordx4 v205, s[4:7], s33 offen lds
	s_mov_b32 m0, s40
	s_nop 0
	buffer_load_dwordx4 v198, s[4:7], s3 offen lds
	s_mov_b32 m0, s41
	s_nop 0
	buffer_load_dwordx4 v204, s[4:7], s3 offen lds
	s_waitcnt vmcnt(8)
	s_waitcnt lgkmcnt(0)
	s_barrier
	s_waitcnt lgkmcnt(7)
	v_mfma_f32_16x16x32_bf16 v[62:65], v[130:133], v[162:165], v[62:65]
	v_mfma_f32_16x16x32_bf16 v[58:61], v[138:141], v[162:165], v[58:61]
	s_waitcnt lgkmcnt(6)
	v_mfma_f32_16x16x32_bf16 v[54:57], v[130:133], v[166:169], v[54:57]
	v_mfma_f32_16x16x32_bf16 v[50:53], v[138:141], v[166:169], v[50:53]
	s_waitcnt lgkmcnt(3)
	v_mfma_f32_16x16x32_bf16 v[46:49], v[130:133], v[178:181], v[46:49]
	v_mfma_f32_16x16x32_bf16 v[42:45], v[138:141], v[178:181], v[42:45]
	s_waitcnt lgkmcnt(2)
	v_mfma_f32_16x16x32_bf16 v[38:41], v[130:133], v[182:185], v[38:41]
	v_mfma_f32_16x16x32_bf16 v[34:37], v[138:141], v[182:185], v[34:37]
	v_mfma_f32_16x16x32_bf16 v[62:65], v[134:137], v[170:173], v[62:65]
	v_mfma_f32_16x16x32_bf16 v[58:61], v[142:145], v[170:173], v[58:61]
	v_mfma_f32_16x16x32_bf16 v[54:57], v[134:137], v[174:177], v[54:57]
	v_mfma_f32_16x16x32_bf16 v[50:53], v[142:145], v[174:177], v[50:53]
	s_waitcnt lgkmcnt(1)
	v_mfma_f32_16x16x32_bf16 v[46:49], v[134:137], v[186:189], v[46:49]
	v_mfma_f32_16x16x32_bf16 v[42:45], v[142:145], v[186:189], v[42:45]
	s_waitcnt lgkmcnt(0)
	v_mfma_f32_16x16x32_bf16 v[38:41], v[134:137], v[190:193], v[38:41]
	v_mfma_f32_16x16x32_bf16 v[34:37], v[142:145], v[190:193], v[34:37]
	s_barrier
	s_andn2_b64 vcc, exec, s[16:17]
	s_cbranch_vccnz .LBB0_393
	s_barrier

.LBB0_407:
	s_waitcnt lgkmcnt(0)
	s_add_i32 s2, s52, 0x100
	s_add_i32 s3, s51, 0x100
	s_barrier
	s_waitcnt lgkmcnt(7)
	v_mfma_f32_16x16x32_bf16 v[126:129], v[158:161], v[186:189], 0
	v_mfma_f32_16x16x32_bf16 v[122:125], v[150:153], v[186:189], 0
	s_waitcnt lgkmcnt(6)
	v_mfma_f32_16x16x32_bf16 v[118:121], v[158:161], v[178:181], 0
	v_mfma_f32_16x16x32_bf16 v[114:117], v[150:153], v[178:181], 0
	s_waitcnt lgkmcnt(3)
	v_mfma_f32_16x16x32_bf16 v[110:113], v[158:161], v[170:173], 0
	v_mfma_f32_16x16x32_bf16 v[106:109], v[150:153], v[170:173], 0
	s_waitcnt lgkmcnt(2)
	v_mfma_f32_16x16x32_bf16 v[102:105], v[158:161], v[162:165], 0
	v_mfma_f32_16x16x32_bf16 v[98:101], v[150:153], v[162:165], 0
	v_mfma_f32_16x16x32_bf16 v[126:129], v[154:157], v[190:193], v[126:129]
	v_mfma_f32_16x16x32_bf16 v[122:125], v[146:149], v[190:193], v[122:125]
	v_mfma_f32_16x16x32_bf16 v[118:121], v[154:157], v[182:185], v[118:121]
	v_mfma_f32_16x16x32_bf16 v[114:117], v[146:149], v[182:185], v[114:117]
	s_waitcnt lgkmcnt(1)
	v_mfma_f32_16x16x32_bf16 v[110:113], v[154:157], v[174:177], v[110:113]
	v_mfma_f32_16x16x32_bf16 v[106:109], v[146:149], v[174:177], v[106:109]
	s_waitcnt lgkmcnt(0)
	v_mfma_f32_16x16x32_bf16 v[102:105], v[154:157], v[166:169], v[102:105]
	v_mfma_f32_16x16x32_bf16 v[98:101], v[146:149], v[166:169], v[98:101]
	v_mfma_f32_16x16x32_bf16 v[94:97], v[142:145], v[186:189], 0
	v_mfma_f32_16x16x32_bf16 v[86:89], v[134:137], v[186:189], 0
	v_mfma_f32_16x16x32_bf16 v[82:85], v[142:145], v[178:181], 0
	v_mfma_f32_16x16x32_bf16 v[78:81], v[134:137], v[178:181], 0
	v_mfma_f32_16x16x32_bf16 v[74:77], v[142:145], v[170:173], 0
	v_mfma_f32_16x16x32_bf16 v[70:73], v[134:137], v[170:173], 0
	v_mfma_f32_16x16x32_bf16 v[66:69], v[142:145], v[162:165], 0
	v_mfma_f32_16x16x32_bf16 v[62:65], v[134:137], v[162:165], 0
	s_nop 0
	v_mfma_f32_16x16x32_bf16 v[94:97], v[138:141], v[190:193], v[94:97]
	v_mfma_f32_16x16x32_bf16 v[86:89], v[130:133], v[190:193], v[86:89]
	v_mfma_f32_16x16x32_bf16 v[82:85], v[138:141], v[182:185], v[82:85]
	v_mfma_f32_16x16x32_bf16 v[78:81], v[130:133], v[182:185], v[78:81]
	v_mfma_f32_16x16x32_bf16 v[74:77], v[138:141], v[174:177], v[74:77]
	v_mfma_f32_16x16x32_bf16 v[70:73], v[130:133], v[174:177], v[70:73]
	v_mfma_f32_16x16x32_bf16 v[66:69], v[138:141], v[166:169], v[66:69]
	v_mfma_f32_16x16x32_bf16 v[62:65], v[130:133], v[166:169], v[62:65]
	s_barrier
	s_mov_b32 m0, s25
	ds_read_b128 v[186:189], v211 offset:16384
	ds_read_b128 v[178:181], v211 offset:18432
	ds_read_b128 v[190:193], v212 offset:16384
	ds_read_b128 v[182:185], v212 offset:18432
	ds_read_b128 v[170:173], v211 offset:20480
	ds_read_b128 v[162:165], v211 offset:22528
	ds_read_b128 v[174:177], v212 offset:20480
	ds_read_b128 v[166:169], v212 offset:22528
	buffer_load_dwordx4 v198, s[8:11], s3 offen lds
	s_mov_b32 m0, s27
	v_cndmask_b32_e64 v194, 0, 1, s[22:23]
	buffer_load_dwordx4 v200, s[8:11], s3 offen lds
	s_add_i32 s3, s51, 0x18100
	s_mov_b32 m0, s28
	s_andn2_b64 vcc, exec, s[22:23]
	buffer_load_dwordx4 v198, s[8:11], s3 offen lds
	s_mov_b32 m0, s29
	s_mov_b64 s[22:23], -1
	buffer_load_dwordx4 v200, s[8:11], s3 offen lds
	s_mov_b32 m0, s24
	s_nop 0
	buffer_load_dwordx4 v197, s[8:11], s2 offen lds
	s_mov_b32 m0, s30
	s_nop 0
	buffer_load_dwordx4 v199, s[8:11], s2 offen lds
	v_cmp_ne_u32_e64 s[2:3], 1, v194
	s_cbranch_vccnz .LBB0_409
	s_waitcnt vmcnt(22)
	s_mov_b64 s[22:23], 0

.LBB0_411:
	s_waitcnt lgkmcnt(0)
	s_barrier
	s_waitcnt lgkmcnt(7)
	v_mfma_f32_16x16x32_bf16 v[90:93], v[158:161], v[186:189], 0
	v_mfma_f32_16x16x32_bf16 v[58:61], v[150:153], v[186:189], 0
	s_waitcnt lgkmcnt(6)
	v_mfma_f32_16x16x32_bf16 v[54:57], v[158:161], v[178:181], 0
	v_mfma_f32_16x16x32_bf16 v[50:53], v[150:153], v[178:181], 0
	s_waitcnt lgkmcnt(3)
	v_mfma_f32_16x16x32_bf16 v[46:49], v[158:161], v[170:173], 0
	v_mfma_f32_16x16x32_bf16 v[42:45], v[150:153], v[170:173], 0
	s_waitcnt lgkmcnt(2)
	v_mfma_f32_16x16x32_bf16 v[38:41], v[158:161], v[162:165], 0
	v_mfma_f32_16x16x32_bf16 v[34:37], v[150:153], v[162:165], 0
	v_mfma_f32_16x16x32_bf16 v[90:93], v[154:157], v[190:193], v[90:93]
	v_mfma_f32_16x16x32_bf16 v[58:61], v[146:149], v[190:193], v[58:61]
	v_mfma_f32_16x16x32_bf16 v[54:57], v[154:157], v[182:185], v[54:57]
	v_mfma_f32_16x16x32_bf16 v[50:53], v[146:149], v[182:185], v[50:53]
	s_waitcnt lgkmcnt(1)
	v_mfma_f32_16x16x32_bf16 v[46:49], v[154:157], v[174:177], v[46:49]
	v_mfma_f32_16x16x32_bf16 v[42:45], v[146:149], v[174:177], v[42:45]
	s_waitcnt lgkmcnt(0)
	v_mfma_f32_16x16x32_bf16 v[38:41], v[154:157], v[166:169], v[38:41]
	v_mfma_f32_16x16x32_bf16 v[34:37], v[146:149], v[166:169], v[34:37]
	v_mfma_f32_16x16x32_bf16 v[30:33], v[142:145], v[186:189], 0
	v_mfma_f32_16x16x32_bf16 v[26:29], v[134:137], v[186:189], 0
	v_mfma_f32_16x16x32_bf16 v[22:25], v[142:145], v[178:181], 0
	v_mfma_f32_16x16x32_bf16 v[18:21], v[134:137], v[178:181], 0
	v_mfma_f32_16x16x32_bf16 v[14:17], v[142:145], v[170:173], 0
	v_mfma_f32_16x16x32_bf16 v[10:13], v[134:137], v[170:173], 0
	v_mfma_f32_16x16x32_bf16 v[6:9], v[142:145], v[162:165], 0
	v_mfma_f32_16x16x32_bf16 v[2:5], v[134:137], v[162:165], 0
	s_nop 0
	v_mfma_f32_16x16x32_bf16 v[30:33], v[138:141], v[190:193], v[30:33]
	v_mfma_f32_16x16x32_bf16 v[26:29], v[130:133], v[190:193], v[26:29]
	v_mfma_f32_16x16x32_bf16 v[22:25], v[138:141], v[182:185], v[22:25]
	v_mfma_f32_16x16x32_bf16 v[18:21], v[130:133], v[182:185], v[18:21]
	v_mfma_f32_16x16x32_bf16 v[14:17], v[138:141], v[174:177], v[14:17]
	v_mfma_f32_16x16x32_bf16 v[10:13], v[130:133], v[174:177], v[10:13]
	v_mfma_f32_16x16x32_bf16 v[6:9], v[138:141], v[166:169], v[6:9]
	v_mfma_f32_16x16x32_bf16 v[2:5], v[130:133], v[166:169], v[2:5]
	s_barrier
	v_add_u32_e32 v194, s45, v201
	v_add_u32_e32 v214, s46, v201
	v_add_u32_e32 v216, s47, v201
	v_add_u32_e32 v218, s48, v201
	v_add_u32_e32 v213, s45, v202
	ds_read_b128 v[146:149], v194
	ds_read_b128 v[150:153], v213
	v_add_u32_e32 v215, s46, v202
	ds_read_b128 v[154:157], v214
	ds_read_b128 v[158:161], v215
	v_add_u32_e32 v217, s47, v202
	ds_read_b128 v[130:133], v216
	ds_read_b128 v[134:137], v217
	v_add_u32_e32 v219, s48, v202
	ds_read_b128 v[138:141], v218
	ds_read_b128 v[142:145], v219
	s_mov_b32 m0, s31
	s_add_i32 s4, s52, 0x18100
	ds_read_b128 v[186:189], v211 offset:32768
	ds_read_b128 v[174:177], v211 offset:34816
	ds_read_b128 v[190:193], v212 offset:32768
	ds_read_b128 v[178:181], v212 offset:34816
	ds_read_b128 v[170:173], v211 offset:36864
	ds_read_b128 v[162:165], v211 offset:38912
	ds_read_b128 v[182:185], v212 offset:36864
	ds_read_b128 v[166:169], v212 offset:38912
	buffer_load_dwordx4 v197, s[8:11], s4 offen lds
	s_mov_b32 m0, s34
	s_and_b64 vcc, exec, s[2:3]
	buffer_load_dwordx4 v199, s[8:11], s4 offen lds
	s_mov_b64 s[22:23], -1
	s_cbranch_vccnz .LBB0_413
	s_waitcnt vmcnt(24)
	s_mov_b64 s[22:23], 0

.LBB0_415:
	s_waitcnt lgkmcnt(0)
	s_add_i32 s22, s52, 0x180
	s_add_i32 s23, s51, 0x180
	s_barrier
	s_waitcnt lgkmcnt(7)
	v_mfma_f32_16x16x32_bf16 v[126:129], v[146:149], v[186:189], v[126:129]
	v_mfma_f32_16x16x32_bf16 v[122:125], v[154:157], v[186:189], v[122:125]
	s_waitcnt lgkmcnt(6)
	v_mfma_f32_16x16x32_bf16 v[118:121], v[146:149], v[174:177], v[118:121]
	v_mfma_f32_16x16x32_bf16 v[114:117], v[154:157], v[174:177], v[114:117]
	s_waitcnt lgkmcnt(3)
	v_mfma_f32_16x16x32_bf16 v[110:113], v[146:149], v[170:173], v[110:113]
	v_mfma_f32_16x16x32_bf16 v[106:109], v[154:157], v[170:173], v[106:109]
	s_waitcnt lgkmcnt(2)
	v_mfma_f32_16x16x32_bf16 v[102:105], v[146:149], v[162:165], v[102:105]
	v_mfma_f32_16x16x32_bf16 v[98:101], v[154:157], v[162:165], v[98:101]
	v_mfma_f32_16x16x32_bf16 v[126:129], v[150:153], v[190:193], v[126:129]
	v_mfma_f32_16x16x32_bf16 v[122:125], v[158:161], v[190:193], v[122:125]
	v_mfma_f32_16x16x32_bf16 v[118:121], v[150:153], v[178:181], v[118:121]
	v_mfma_f32_16x16x32_bf16 v[114:117], v[158:161], v[178:181], v[114:117]
	s_waitcnt lgkmcnt(1)
	v_mfma_f32_16x16x32_bf16 v[110:113], v[150:153], v[182:185], v[110:113]
	v_mfma_f32_16x16x32_bf16 v[106:109], v[158:161], v[182:185], v[106:109]
	s_waitcnt lgkmcnt(0)
	v_mfma_f32_16x16x32_bf16 v[102:105], v[150:153], v[166:169], v[102:105]
	v_mfma_f32_16x16x32_bf16 v[98:101], v[158:161], v[166:169], v[98:101]
	v_mfma_f32_16x16x32_bf16 v[94:97], v[130:133], v[186:189], v[94:97]
	v_mfma_f32_16x16x32_bf16 v[86:89], v[138:141], v[186:189], v[86:89]
	v_mfma_f32_16x16x32_bf16 v[82:85], v[130:133], v[174:177], v[82:85]
	v_mfma_f32_16x16x32_bf16 v[78:81], v[138:141], v[174:177], v[78:81]
	v_mfma_f32_16x16x32_bf16 v[74:77], v[130:133], v[170:173], v[74:77]
	v_mfma_f32_16x16x32_bf16 v[70:73], v[138:141], v[170:173], v[70:73]
	v_mfma_f32_16x16x32_bf16 v[66:69], v[130:133], v[162:165], v[66:69]
	v_mfma_f32_16x16x32_bf16 v[62:65], v[138:141], v[162:165], v[62:65]
	v_mfma_f32_16x16x32_bf16 v[94:97], v[134:137], v[190:193], v[94:97]
	v_mfma_f32_16x16x32_bf16 v[86:89], v[142:145], v[190:193], v[86:89]
	v_mfma_f32_16x16x32_bf16 v[82:85], v[134:137], v[178:181], v[82:85]
	v_mfma_f32_16x16x32_bf16 v[78:81], v[142:145], v[178:181], v[78:81]
	v_mfma_f32_16x16x32_bf16 v[74:77], v[134:137], v[182:185], v[74:77]
	v_mfma_f32_16x16x32_bf16 v[70:73], v[142:145], v[182:185], v[70:73]
	v_mfma_f32_16x16x32_bf16 v[66:69], v[134:137], v[166:169], v[66:69]
	v_mfma_f32_16x16x32_bf16 v[62:65], v[142:145], v[166:169], v[62:65]
	s_barrier
	s_mov_b32 m0, s36
	s_mov_b32 s4, s70
	ds_read_b128 v[186:189], v211 offset:49152
	ds_read_b128 v[174:177], v211 offset:51200
	ds_read_b128 v[190:193], v212 offset:49152
	ds_read_b128 v[178:181], v212 offset:51200
	ds_read_b128 v[170:173], v211 offset:53248
	ds_read_b128 v[162:165], v211 offset:55296
	ds_read_b128 v[182:185], v212 offset:53248
	ds_read_b128 v[166:169], v212 offset:55296
	buffer_load_dwordx4 v198, s[4:7], s23 offen lds
	s_mov_b32 m0, s37
	s_and_b64 vcc, exec, s[2:3]
	buffer_load_dwordx4 v200, s[4:7], s23 offen lds
	s_add_i32 s23, s51, 0x18180
	s_mov_b32 m0, s40
	s_mov_b64 s[2:3], -1
	buffer_load_dwordx4 v198, s[4:7], s23 offen lds
	s_mov_b32 m0, s41
	s_nop 0
	buffer_load_dwordx4 v200, s[4:7], s23 offen lds
	s_mov_b32 m0, s38
	s_nop 0
	buffer_load_dwordx4 v197, s[4:7], s22 offen lds
	s_mov_b32 m0, s39
	s_nop 0
	buffer_load_dwordx4 v199, s[4:7], s22 offen lds
	s_cbranch_vccnz .LBB0_417
	s_waitcnt vmcnt(30)
	s_mov_b64 s[2:3], 0

.LBB0_419:
	s_waitcnt lgkmcnt(0)
	s_barrier
	s_waitcnt lgkmcnt(7)
	v_mfma_f32_16x16x32_bf16 v[90:93], v[146:149], v[186:189], v[90:93]
	v_mfma_f32_16x16x32_bf16 v[58:61], v[154:157], v[186:189], v[58:61]
	s_waitcnt lgkmcnt(6)
	v_mfma_f32_16x16x32_bf16 v[54:57], v[146:149], v[174:177], v[54:57]
	v_mfma_f32_16x16x32_bf16 v[50:53], v[154:157], v[174:177], v[50:53]
	s_waitcnt lgkmcnt(3)
	v_mfma_f32_16x16x32_bf16 v[46:49], v[146:149], v[170:173], v[46:49]
	v_mfma_f32_16x16x32_bf16 v[42:45], v[154:157], v[170:173], v[42:45]
	s_waitcnt lgkmcnt(2)
	v_mfma_f32_16x16x32_bf16 v[38:41], v[146:149], v[162:165], v[38:41]
	v_mfma_f32_16x16x32_bf16 v[34:37], v[154:157], v[162:165], v[34:37]
	v_mfma_f32_16x16x32_bf16 v[90:93], v[150:153], v[190:193], v[90:93]
	v_mfma_f32_16x16x32_bf16 v[58:61], v[158:161], v[190:193], v[58:61]
	v_mfma_f32_16x16x32_bf16 v[54:57], v[150:153], v[178:181], v[54:57]
	v_mfma_f32_16x16x32_bf16 v[50:53], v[158:161], v[178:181], v[50:53]
	s_waitcnt lgkmcnt(1)
	v_mfma_f32_16x16x32_bf16 v[46:49], v[150:153], v[182:185], v[46:49]
	v_mfma_f32_16x16x32_bf16 v[42:45], v[158:161], v[182:185], v[42:45]
	s_waitcnt lgkmcnt(0)
	v_mfma_f32_16x16x32_bf16 v[38:41], v[150:153], v[166:169], v[38:41]
	v_mfma_f32_16x16x32_bf16 v[34:37], v[158:161], v[166:169], v[34:37]
	v_mfma_f32_16x16x32_bf16 v[30:33], v[130:133], v[186:189], v[30:33]
	v_mfma_f32_16x16x32_bf16 v[26:29], v[138:141], v[186:189], v[26:29]
	v_mfma_f32_16x16x32_bf16 v[22:25], v[130:133], v[174:177], v[22:25]
	v_mfma_f32_16x16x32_bf16 v[18:21], v[138:141], v[174:177], v[18:21]
	v_mfma_f32_16x16x32_bf16 v[14:17], v[130:133], v[170:173], v[14:17]
	v_mfma_f32_16x16x32_bf16 v[10:13], v[138:141], v[170:173], v[10:13]
	v_mfma_f32_16x16x32_bf16 v[6:9], v[130:133], v[162:165], v[6:9]
	v_mfma_f32_16x16x32_bf16 v[2:5], v[138:141], v[162:165], v[2:5]
	v_mfma_f32_16x16x32_bf16 v[30:33], v[134:137], v[190:193], v[30:33]
	v_mfma_f32_16x16x32_bf16 v[26:29], v[142:145], v[190:193], v[26:29]
	v_mfma_f32_16x16x32_bf16 v[22:25], v[134:137], v[178:181], v[22:25]
	v_mfma_f32_16x16x32_bf16 v[18:21], v[142:145], v[178:181], v[18:21]
	v_mfma_f32_16x16x32_bf16 v[14:17], v[134:137], v[182:185], v[14:17]
	v_mfma_f32_16x16x32_bf16 v[10:13], v[142:145], v[182:185], v[10:13]
	v_mfma_f32_16x16x32_bf16 v[6:9], v[134:137], v[166:169], v[6:9]
	v_mfma_f32_16x16x32_bf16 v[2:5], v[142:145], v[166:169], v[2:5]
	s_barrier
	v_cndmask_b32_e64 v130, 0, 1, s[20:21]
	s_add_i32 s22, s53, s26
	v_cmp_ne_u32_e64 s[2:3], 1, v130
	s_andn2_b64 vcc, exec, s[20:21]
	s_mov_b32 s23, s51
	s_cbranch_vccnz .LBB0_421
	s_lshr_b32 s4, s22, 4
	s_mul_i32 s4, s4, 0x30000
	s_add_i32 s23, s4, 0x2a00000

.LBB0_422:
	ds_read_b128 v[130:133], v203
	ds_read_b128 v[134:137], v204
	ds_read_b128 v[138:141], v205
	ds_read_b128 v[142:145], v206
	ds_read_b128 v[146:149], v207
	ds_read_b128 v[150:153], v208
	ds_read_b128 v[154:157], v209
	ds_read_b128 v[158:161], v210
	s_add_i32 s4, s21, 0xfffe8080
	s_cmp_eq_u32 s51, 2
	s_cselect_b32 s54, s20, s4
	s_cselect_b32 s53, s23, s33
	s_add_i32 s52, s54, 0x80
	s_mov_b32 s4, s70
	s_mov_b32 m0, s42
	ds_read_b128 v[162:165], v211
	ds_read_b128 v[166:169], v211 offset:2048
	ds_read_b128 v[170:173], v212
	ds_read_b128 v[174:177], v212 offset:2048
	ds_read_b128 v[178:181], v211 offset:4096
	ds_read_b128 v[182:185], v211 offset:6144
	ds_read_b128 v[186:189], v212 offset:4096
	ds_read_b128 v[190:193], v212 offset:6144
	buffer_load_dwordx4 v197, s[4:7], s21 offen lds
	s_mov_b32 m0, s44
	s_nop 0
	buffer_load_dwordx4 v199, s[4:7], s21 offen lds
	s_waitcnt vmcnt(8)
	s_waitcnt lgkmcnt(0)
	s_barrier
	s_waitcnt lgkmcnt(7)
	v_mfma_f32_16x16x32_bf16 v[126:129], v[130:133], v[162:165], v[126:129]
	v_mfma_f32_16x16x32_bf16 v[122:125], v[138:141], v[162:165], v[122:125]
	s_waitcnt lgkmcnt(6)
	v_mfma_f32_16x16x32_bf16 v[118:121], v[130:133], v[166:169], v[118:121]
	v_mfma_f32_16x16x32_bf16 v[114:117], v[138:141], v[166:169], v[114:117]
	s_waitcnt lgkmcnt(3)
	v_mfma_f32_16x16x32_bf16 v[110:113], v[130:133], v[178:181], v[110:113]
	v_mfma_f32_16x16x32_bf16 v[106:109], v[138:141], v[178:181], v[106:109]
	s_waitcnt lgkmcnt(2)
	v_mfma_f32_16x16x32_bf16 v[102:105], v[130:133], v[182:185], v[102:105]
	v_mfma_f32_16x16x32_bf16 v[98:101], v[138:141], v[182:185], v[98:101]
	v_mfma_f32_16x16x32_bf16 v[126:129], v[134:137], v[170:173], v[126:129]
	v_mfma_f32_16x16x32_bf16 v[122:125], v[142:145], v[170:173], v[122:125]
	v_mfma_f32_16x16x32_bf16 v[118:121], v[134:137], v[174:177], v[118:121]
	v_mfma_f32_16x16x32_bf16 v[114:117], v[142:145], v[174:177], v[114:117]
	s_waitcnt lgkmcnt(1)
	v_mfma_f32_16x16x32_bf16 v[110:113], v[134:137], v[186:189], v[110:113]
	v_mfma_f32_16x16x32_bf16 v[106:109], v[142:145], v[186:189], v[106:109]
	s_waitcnt lgkmcnt(0)
	v_mfma_f32_16x16x32_bf16 v[102:105], v[134:137], v[190:193], v[102:105]
	v_mfma_f32_16x16x32_bf16 v[98:101], v[142:145], v[190:193], v[98:101]
	v_mfma_f32_16x16x32_bf16 v[94:97], v[146:149], v[162:165], v[94:97]
	v_mfma_f32_16x16x32_bf16 v[86:89], v[154:157], v[162:165], v[86:89]
	v_mfma_f32_16x16x32_bf16 v[82:85], v[146:149], v[166:169], v[82:85]
	v_mfma_f32_16x16x32_bf16 v[78:81], v[154:157], v[166:169], v[78:81]
	v_mfma_f32_16x16x32_bf16 v[74:77], v[146:149], v[178:181], v[74:77]
	v_mfma_f32_16x16x32_bf16 v[70:73], v[154:157], v[178:181], v[70:73]
	v_mfma_f32_16x16x32_bf16 v[66:69], v[146:149], v[182:185], v[66:69]
	v_mfma_f32_16x16x32_bf16 v[62:65], v[154:157], v[182:185], v[62:65]
	v_mfma_f32_16x16x32_bf16 v[94:97], v[150:153], v[170:173], v[94:97]
	v_mfma_f32_16x16x32_bf16 v[86:89], v[158:161], v[170:173], v[86:89]
	v_mfma_f32_16x16x32_bf16 v[82:85], v[150:153], v[174:177], v[82:85]
	v_mfma_f32_16x16x32_bf16 v[78:81], v[158:161], v[174:177], v[78:81]
	v_mfma_f32_16x16x32_bf16 v[74:77], v[150:153], v[186:189], v[74:77]
	v_mfma_f32_16x16x32_bf16 v[70:73], v[158:161], v[186:189], v[70:73]
	v_mfma_f32_16x16x32_bf16 v[66:69], v[150:153], v[190:193], v[66:69]
	v_mfma_f32_16x16x32_bf16 v[62:65], v[158:161], v[190:193], v[62:65]
	s_barrier
	s_mov_b32 m0, s25
	ds_read_b128 v[162:165], v211 offset:16384
	ds_read_b128 v[166:169], v211 offset:18432
	ds_read_b128 v[170:173], v212 offset:16384
	ds_read_b128 v[174:177], v212 offset:18432
	ds_read_b128 v[178:181], v211 offset:20480
	ds_read_b128 v[182:185], v211 offset:22528
	ds_read_b128 v[186:189], v212 offset:20480
	ds_read_b128 v[190:193], v212 offset:22528
	buffer_load_dwordx4 v198, s[4:7], s53 offen lds
	s_mov_b32 m0, s27
	s_add_i32 s55, s53, 0x18000
	buffer_load_dwordx4 v200, s[4:7], s53 offen lds
	s_mov_b32 m0, s28
	s_nop 0
	buffer_load_dwordx4 v198, s[4:7], s55 offen lds
	s_mov_b32 m0, s29
	s_nop 0
	buffer_load_dwordx4 v200, s[4:7], s55 offen lds
	s_mov_b32 m0, s24
	s_nop 0
	buffer_load_dwordx4 v197, s[4:7], s54 offen lds
	s_mov_b32 m0, s30
	s_nop 0
	buffer_load_dwordx4 v199, s[4:7], s54 offen lds
	s_waitcnt vmcnt(8)
	s_waitcnt lgkmcnt(0)
	s_barrier
	s_waitcnt lgkmcnt(7)
	v_mfma_f32_16x16x32_bf16 v[90:93], v[130:133], v[162:165], v[90:93]
	v_mfma_f32_16x16x32_bf16 v[58:61], v[138:141], v[162:165], v[58:61]
	s_waitcnt lgkmcnt(6)
	v_mfma_f32_16x16x32_bf16 v[54:57], v[130:133], v[166:169], v[54:57]
	v_mfma_f32_16x16x32_bf16 v[50:53], v[138:141], v[166:169], v[50:53]
	s_waitcnt lgkmcnt(3)
	v_mfma_f32_16x16x32_bf16 v[46:49], v[130:133], v[178:181], v[46:49]
	v_mfma_f32_16x16x32_bf16 v[42:45], v[138:141], v[178:181], v[42:45]
	s_waitcnt lgkmcnt(2)
	v_mfma_f32_16x16x32_bf16 v[38:41], v[130:133], v[182:185], v[38:41]
	v_mfma_f32_16x16x32_bf16 v[34:37], v[138:141], v[182:185], v[34:37]
	v_mfma_f32_16x16x32_bf16 v[90:93], v[134:137], v[170:173], v[90:93]
	v_mfma_f32_16x16x32_bf16 v[58:61], v[142:145], v[170:173], v[58:61]
	v_mfma_f32_16x16x32_bf16 v[54:57], v[134:137], v[174:177], v[54:57]
	v_mfma_f32_16x16x32_bf16 v[50:53], v[142:145], v[174:177], v[50:53]
	s_waitcnt lgkmcnt(1)
	v_mfma_f32_16x16x32_bf16 v[46:49], v[134:137], v[186:189], v[46:49]
	v_mfma_f32_16x16x32_bf16 v[42:45], v[142:145], v[186:189], v[42:45]
	s_waitcnt lgkmcnt(0)
	v_mfma_f32_16x16x32_bf16 v[38:41], v[134:137], v[190:193], v[38:41]
	v_mfma_f32_16x16x32_bf16 v[34:37], v[142:145], v[190:193], v[34:37]
	v_mfma_f32_16x16x32_bf16 v[30:33], v[146:149], v[162:165], v[30:33]
	v_mfma_f32_16x16x32_bf16 v[26:29], v[154:157], v[162:165], v[26:29]
	v_mfma_f32_16x16x32_bf16 v[22:25], v[146:149], v[166:169], v[22:25]
	v_mfma_f32_16x16x32_bf16 v[18:21], v[154:157], v[166:169], v[18:21]
	v_mfma_f32_16x16x32_bf16 v[14:17], v[146:149], v[178:181], v[14:17]
	v_mfma_f32_16x16x32_bf16 v[10:13], v[154:157], v[178:181], v[10:13]
	v_mfma_f32_16x16x32_bf16 v[6:9], v[146:149], v[182:185], v[6:9]
	v_mfma_f32_16x16x32_bf16 v[2:5], v[154:157], v[182:185], v[2:5]
	v_mfma_f32_16x16x32_bf16 v[30:33], v[150:153], v[170:173], v[30:33]
	v_mfma_f32_16x16x32_bf16 v[26:29], v[158:161], v[170:173], v[26:29]
	v_mfma_f32_16x16x32_bf16 v[22:25], v[150:153], v[174:177], v[22:25]
	v_mfma_f32_16x16x32_bf16 v[18:21], v[158:161], v[174:177], v[18:21]
	v_mfma_f32_16x16x32_bf16 v[14:17], v[150:153], v[186:189], v[14:17]
	v_mfma_f32_16x16x32_bf16 v[10:13], v[158:161], v[186:189], v[10:13]
	v_mfma_f32_16x16x32_bf16 v[6:9], v[150:153], v[190:193], v[6:9]
	v_mfma_f32_16x16x32_bf16 v[2:5], v[158:161], v[190:193], v[2:5]
	s_barrier
	ds_read_b128 v[130:133], v194
	ds_read_b128 v[134:137], v213
	ds_read_b128 v[138:141], v214
	ds_read_b128 v[142:145], v215
	ds_read_b128 v[146:149], v216
	ds_read_b128 v[150:153], v217
	ds_read_b128 v[154:157], v218
	ds_read_b128 v[158:161], v219
	s_add_i32 s54, s54, 0x18000
	s_mov_b32 m0, s31
	ds_read_b128 v[162:165], v211 offset:32768
	ds_read_b128 v[166:169], v211 offset:34816
	ds_read_b128 v[170:173], v212 offset:32768
	ds_read_b128 v[174:177], v212 offset:34816
	ds_read_b128 v[178:181], v211 offset:36864
	ds_read_b128 v[182:185], v211 offset:38912
	ds_read_b128 v[186:189], v212 offset:36864
	ds_read_b128 v[190:193], v212 offset:38912
	buffer_load_dwordx4 v197, s[4:7], s54 offen lds
	s_mov_b32 m0, s34
	s_nop 0
	buffer_load_dwordx4 v199, s[4:7], s54 offen lds
	s_waitcnt vmcnt(8)
	s_waitcnt lgkmcnt(0)
	s_barrier
	s_waitcnt lgkmcnt(7)
	v_mfma_f32_16x16x32_bf16 v[126:129], v[130:133], v[162:165], v[126:129]
	v_mfma_f32_16x16x32_bf16 v[122:125], v[138:141], v[162:165], v[122:125]
	s_waitcnt lgkmcnt(6)
	v_mfma_f32_16x16x32_bf16 v[118:121], v[130:133], v[166:169], v[118:121]
	v_mfma_f32_16x16x32_bf16 v[114:117], v[138:141], v[166:169], v[114:117]
	s_waitcnt lgkmcnt(3)
	v_mfma_f32_16x16x32_bf16 v[110:113], v[130:133], v[178:181], v[110:113]
	v_mfma_f32_16x16x32_bf16 v[106:109], v[138:141], v[178:181], v[106:109]
	s_waitcnt lgkmcnt(2)
	v_mfma_f32_16x16x32_bf16 v[102:105], v[130:133], v[182:185], v[102:105]
	v_mfma_f32_16x16x32_bf16 v[98:101], v[138:141], v[182:185], v[98:101]
	v_mfma_f32_16x16x32_bf16 v[126:129], v[134:137], v[170:173], v[126:129]
	v_mfma_f32_16x16x32_bf16 v[122:125], v[142:145], v[170:173], v[122:125]
	v_mfma_f32_16x16x32_bf16 v[118:121], v[134:137], v[174:177], v[118:121]
	v_mfma_f32_16x16x32_bf16 v[114:117], v[142:145], v[174:177], v[114:117]
	s_waitcnt lgkmcnt(1)
	v_mfma_f32_16x16x32_bf16 v[110:113], v[134:137], v[186:189], v[110:113]
	v_mfma_f32_16x16x32_bf16 v[106:109], v[142:145], v[186:189], v[106:109]
	s_waitcnt lgkmcnt(0)
	v_mfma_f32_16x16x32_bf16 v[102:105], v[134:137], v[190:193], v[102:105]
	v_mfma_f32_16x16x32_bf16 v[98:101], v[142:145], v[190:193], v[98:101]
	v_mfma_f32_16x16x32_bf16 v[94:97], v[146:149], v[162:165], v[94:97]
	v_mfma_f32_16x16x32_bf16 v[86:89], v[154:157], v[162:165], v[86:89]
	v_mfma_f32_16x16x32_bf16 v[82:85], v[146:149], v[166:169], v[82:85]
	v_mfma_f32_16x16x32_bf16 v[78:81], v[154:157], v[166:169], v[78:81]
	v_mfma_f32_16x16x32_bf16 v[74:77], v[146:149], v[178:181], v[74:77]
	v_mfma_f32_16x16x32_bf16 v[70:73], v[154:157], v[178:181], v[70:73]
	v_mfma_f32_16x16x32_bf16 v[66:69], v[146:149], v[182:185], v[66:69]
	v_mfma_f32_16x16x32_bf16 v[62:65], v[154:157], v[182:185], v[62:65]
	v_mfma_f32_16x16x32_bf16 v[94:97], v[150:153], v[170:173], v[94:97]
	v_mfma_f32_16x16x32_bf16 v[86:89], v[158:161], v[170:173], v[86:89]
	v_mfma_f32_16x16x32_bf16 v[82:85], v[150:153], v[174:177], v[82:85]
	v_mfma_f32_16x16x32_bf16 v[78:81], v[158:161], v[174:177], v[78:81]
	v_mfma_f32_16x16x32_bf16 v[74:77], v[150:153], v[186:189], v[74:77]
	v_mfma_f32_16x16x32_bf16 v[70:73], v[158:161], v[186:189], v[70:73]
	v_mfma_f32_16x16x32_bf16 v[66:69], v[150:153], v[190:193], v[66:69]
	v_mfma_f32_16x16x32_bf16 v[62:65], v[158:161], v[190:193], v[62:65]
	s_barrier
	s_mov_b32 m0, s36
	s_add_i32 s54, s53, 0x80
	ds_read_b128 v[162:165], v211 offset:49152
	ds_read_b128 v[166:169], v211 offset:51200
	ds_read_b128 v[170:173], v212 offset:49152
	ds_read_b128 v[174:177], v212 offset:51200
	ds_read_b128 v[178:181], v211 offset:53248
	ds_read_b128 v[182:185], v211 offset:55296
	ds_read_b128 v[186:189], v212 offset:53248
	ds_read_b128 v[190:193], v212 offset:55296
	buffer_load_dwordx4 v198, s[4:7], s54 offen lds
	s_mov_b32 m0, s37
	s_add_i32 s53, s53, 0x18080
	buffer_load_dwordx4 v200, s[4:7], s54 offen lds
	s_mov_b32 m0, s40
	s_nop 0
	buffer_load_dwordx4 v198, s[4:7], s53 offen lds
	s_mov_b32 m0, s41
	s_nop 0
	buffer_load_dwordx4 v200, s[4:7], s53 offen lds
	s_mov_b32 m0, s38
	s_nop 0
	buffer_load_dwordx4 v197, s[4:7], s52 offen lds
	s_mov_b32 m0, s39
	s_nop 0
	buffer_load_dwordx4 v199, s[4:7], s52 offen lds
	s_waitcnt vmcnt(8)
	s_waitcnt lgkmcnt(0)
	s_barrier
	s_waitcnt lgkmcnt(7)
	v_mfma_f32_16x16x32_bf16 v[90:93], v[130:133], v[162:165], v[90:93]
	v_mfma_f32_16x16x32_bf16 v[58:61], v[138:141], v[162:165], v[58:61]
	s_waitcnt lgkmcnt(6)
	v_mfma_f32_16x16x32_bf16 v[54:57], v[130:133], v[166:169], v[54:57]
	v_mfma_f32_16x16x32_bf16 v[50:53], v[138:141], v[166:169], v[50:53]
	s_waitcnt lgkmcnt(3)
	v_mfma_f32_16x16x32_bf16 v[46:49], v[130:133], v[178:181], v[46:49]
	v_mfma_f32_16x16x32_bf16 v[42:45], v[138:141], v[178:181], v[42:45]
	s_waitcnt lgkmcnt(2)
	v_mfma_f32_16x16x32_bf16 v[38:41], v[130:133], v[182:185], v[38:41]
	v_mfma_f32_16x16x32_bf16 v[34:37], v[138:141], v[182:185], v[34:37]
	v_mfma_f32_16x16x32_bf16 v[90:93], v[134:137], v[170:173], v[90:93]
	v_mfma_f32_16x16x32_bf16 v[58:61], v[142:145], v[170:173], v[58:61]
	v_mfma_f32_16x16x32_bf16 v[54:57], v[134:137], v[174:177], v[54:57]
	v_mfma_f32_16x16x32_bf16 v[50:53], v[142:145], v[174:177], v[50:53]
	s_waitcnt lgkmcnt(1)
	v_mfma_f32_16x16x32_bf16 v[46:49], v[134:137], v[186:189], v[46:49]
	v_mfma_f32_16x16x32_bf16 v[42:45], v[142:145], v[186:189], v[42:45]
	s_waitcnt lgkmcnt(0)
	v_mfma_f32_16x16x32_bf16 v[38:41], v[134:137], v[190:193], v[38:41]
	v_mfma_f32_16x16x32_bf16 v[34:37], v[142:145], v[190:193], v[34:37]
	v_mfma_f32_16x16x32_bf16 v[30:33], v[146:149], v[162:165], v[30:33]
	v_mfma_f32_16x16x32_bf16 v[26:29], v[154:157], v[162:165], v[26:29]
	v_mfma_f32_16x16x32_bf16 v[22:25], v[146:149], v[166:169], v[22:25]
	v_mfma_f32_16x16x32_bf16 v[18:21], v[154:157], v[166:169], v[18:21]
	v_mfma_f32_16x16x32_bf16 v[14:17], v[146:149], v[178:181], v[14:17]
	v_mfma_f32_16x16x32_bf16 v[10:13], v[154:157], v[178:181], v[10:13]
	v_mfma_f32_16x16x32_bf16 v[6:9], v[146:149], v[182:185], v[6:9]
	v_mfma_f32_16x16x32_bf16 v[2:5], v[154:157], v[182:185], v[2:5]
	v_mfma_f32_16x16x32_bf16 v[30:33], v[150:153], v[170:173], v[30:33]
	v_mfma_f32_16x16x32_bf16 v[26:29], v[158:161], v[170:173], v[26:29]
	v_mfma_f32_16x16x32_bf16 v[22:25], v[150:153], v[174:177], v[22:25]
	v_mfma_f32_16x16x32_bf16 v[18:21], v[158:161], v[174:177], v[18:21]
	v_mfma_f32_16x16x32_bf16 v[14:17], v[150:153], v[186:189], v[14:17]
	v_mfma_f32_16x16x32_bf16 v[10:13], v[158:161], v[186:189], v[10:13]
	v_mfma_f32_16x16x32_bf16 v[6:9], v[150:153], v[190:193], v[6:9]
	v_mfma_f32_16x16x32_bf16 v[2:5], v[158:161], v[190:193], v[2:5]
	s_barrier
	s_add_i32 s51, s51, 2
	s_addk_i32 s21, 0x100
	s_addk_i32 s33, 0x100
	s_cmp_gt_u32 s51, 3
	s_cbranch_scc0 .LBB0_422
	s_and_b64 vcc, exec, s[16:17]
	s_cbranch_vccz .LBB0_425
	s_barrier

.LBB0_530:
	s_waitcnt lgkmcnt(0)
	s_add_i32 s33, s55, 0x100
	s_add_i32 s53, s61, 0x100
	s_barrier
	s_waitcnt lgkmcnt(7)
	v_mfma_f32_16x16x32_bf16 v[126:129], v[158:161], v[186:189], 0
	v_mfma_f32_16x16x32_bf16 v[122:125], v[150:153], v[186:189], 0
	s_waitcnt lgkmcnt(6)
	v_mfma_f32_16x16x32_bf16 v[118:121], v[158:161], v[178:181], 0
	v_mfma_f32_16x16x32_bf16 v[114:117], v[150:153], v[178:181], 0
	s_waitcnt lgkmcnt(3)
	v_mfma_f32_16x16x32_bf16 v[110:113], v[158:161], v[170:173], 0
	v_mfma_f32_16x16x32_bf16 v[106:109], v[150:153], v[170:173], 0
	s_waitcnt lgkmcnt(2)
	v_mfma_f32_16x16x32_bf16 v[102:105], v[158:161], v[162:165], 0
	v_mfma_f32_16x16x32_bf16 v[98:101], v[150:153], v[162:165], 0
	v_mfma_f32_16x16x32_bf16 v[126:129], v[154:157], v[190:193], v[126:129]
	v_mfma_f32_16x16x32_bf16 v[122:125], v[146:149], v[190:193], v[122:125]
	v_mfma_f32_16x16x32_bf16 v[118:121], v[154:157], v[182:185], v[118:121]
	v_mfma_f32_16x16x32_bf16 v[114:117], v[146:149], v[182:185], v[114:117]
	s_waitcnt lgkmcnt(1)
	v_mfma_f32_16x16x32_bf16 v[110:113], v[154:157], v[174:177], v[110:113]
	v_mfma_f32_16x16x32_bf16 v[106:109], v[146:149], v[174:177], v[106:109]
	s_waitcnt lgkmcnt(0)
	v_mfma_f32_16x16x32_bf16 v[102:105], v[154:157], v[166:169], v[102:105]
	v_mfma_f32_16x16x32_bf16 v[98:101], v[146:149], v[166:169], v[98:101]
	v_mfma_f32_16x16x32_bf16 v[94:97], v[142:145], v[186:189], 0
	v_mfma_f32_16x16x32_bf16 v[90:93], v[134:137], v[186:189], 0
	v_mfma_f32_16x16x32_bf16 v[86:89], v[142:145], v[178:181], 0
	v_mfma_f32_16x16x32_bf16 v[82:85], v[134:137], v[178:181], 0
	v_mfma_f32_16x16x32_bf16 v[78:81], v[142:145], v[170:173], 0
	v_mfma_f32_16x16x32_bf16 v[74:77], v[134:137], v[170:173], 0
	v_mfma_f32_16x16x32_bf16 v[70:73], v[142:145], v[162:165], 0
	v_mfma_f32_16x16x32_bf16 v[66:69], v[134:137], v[162:165], 0
	s_nop 0
	v_mfma_f32_16x16x32_bf16 v[94:97], v[138:141], v[190:193], v[94:97]
	v_mfma_f32_16x16x32_bf16 v[90:93], v[130:133], v[190:193], v[90:93]
	v_mfma_f32_16x16x32_bf16 v[86:89], v[138:141], v[182:185], v[86:89]
	v_mfma_f32_16x16x32_bf16 v[82:85], v[130:133], v[182:185], v[82:85]
	v_mfma_f32_16x16x32_bf16 v[78:81], v[138:141], v[174:177], v[78:81]
	v_mfma_f32_16x16x32_bf16 v[74:77], v[130:133], v[174:177], v[74:77]
	v_mfma_f32_16x16x32_bf16 v[70:73], v[138:141], v[166:169], v[70:73]
	v_mfma_f32_16x16x32_bf16 v[66:69], v[130:133], v[166:169], v[66:69]
	s_barrier
	s_cmp_lg_u32 s59, 0
	s_cselect_b64 s[20:21], -1, 0
	s_cmp_eq_u32 s59, 0
	s_cselect_b64 s[2:3], -1, 0
	v_cndmask_b32_e64 v194, v200, 0, s[2:3]
	s_mov_b32 m0, s25
	v_sub_u32_e32 v233, v201, v194
	s_mov_b32 s4, s70
	v_cndmask_b32_e64 v194, v203, 0, s[2:3]
	ds_read_b128 v[186:189], v219 offset:16384
	ds_read_b128 v[178:181], v219 offset:18432
	ds_read_b128 v[190:193], v220 offset:16384
	ds_read_b128 v[182:185], v220 offset:18432
	ds_read_b128 v[170:173], v219 offset:20480
	ds_read_b128 v[162:165], v219 offset:22528
	ds_read_b128 v[174:177], v220 offset:20480
	ds_read_b128 v[166:169], v220 offset:22528
	buffer_load_dwordx4 v233, s[4:7], s53 offen lds
	v_sub_u32_e32 v234, v204, v194
	s_mov_b32 m0, s26
	v_cndmask_b32_e64 v194, v205, 0, s[2:3]
	buffer_load_dwordx4 v234, s[4:7], s53 offen lds
	s_add_i32 s53, s53, s60
	s_mov_b32 m0, s27
	v_sub_u32_e32 v194, v1, v194
	buffer_load_dwordx4 v233, s[4:7], s53 offen lds
	s_mov_b32 m0, s28
	v_cndmask_b32_e64 v222, v206, 0, s[2:3]
	buffer_load_dwordx4 v234, s[4:7], s53 offen lds
	s_mov_b32 m0, s24
	v_sub_u32_e32 v222, v202, v222
	buffer_load_dwordx4 v194, s[4:7], s33 offen lds
	s_mov_b32 m0, s29
	v_cndmask_b32_e64 v223, 0, 1, s[22:23]
	buffer_load_dwordx4 v222, s[4:7], s33 offen lds
	v_cmp_ne_u32_e64 s[2:3], 1, v223
	s_andn2_b64 vcc, exec, s[22:23]
	s_cbranch_vccnz .LBB0_557
	s_waitcnt vmcnt(14)
	s_cbranch_execnz .LBB0_533

.LBB0_533:
	s_waitcnt lgkmcnt(0)
	s_barrier
	s_waitcnt lgkmcnt(7)
	v_mfma_f32_16x16x32_bf16 v[62:65], v[158:161], v[186:189], 0
	v_mfma_f32_16x16x32_bf16 v[58:61], v[150:153], v[186:189], 0
	s_waitcnt lgkmcnt(6)
	v_mfma_f32_16x16x32_bf16 v[54:57], v[158:161], v[178:181], 0
	v_mfma_f32_16x16x32_bf16 v[50:53], v[150:153], v[178:181], 0
	s_waitcnt lgkmcnt(3)
	v_mfma_f32_16x16x32_bf16 v[46:49], v[158:161], v[170:173], 0
	v_mfma_f32_16x16x32_bf16 v[42:45], v[150:153], v[170:173], 0
	s_waitcnt lgkmcnt(2)
	v_mfma_f32_16x16x32_bf16 v[38:41], v[158:161], v[162:165], 0
	v_mfma_f32_16x16x32_bf16 v[34:37], v[150:153], v[162:165], 0
	v_mfma_f32_16x16x32_bf16 v[62:65], v[154:157], v[190:193], v[62:65]
	v_mfma_f32_16x16x32_bf16 v[58:61], v[146:149], v[190:193], v[58:61]
	v_mfma_f32_16x16x32_bf16 v[54:57], v[154:157], v[182:185], v[54:57]
	v_mfma_f32_16x16x32_bf16 v[50:53], v[146:149], v[182:185], v[50:53]
	s_waitcnt lgkmcnt(1)
	v_mfma_f32_16x16x32_bf16 v[46:49], v[154:157], v[174:177], v[46:49]
	v_mfma_f32_16x16x32_bf16 v[42:45], v[146:149], v[174:177], v[42:45]
	s_waitcnt lgkmcnt(0)
	v_mfma_f32_16x16x32_bf16 v[38:41], v[154:157], v[166:169], v[38:41]
	v_mfma_f32_16x16x32_bf16 v[34:37], v[146:149], v[166:169], v[34:37]
	v_mfma_f32_16x16x32_bf16 v[30:33], v[142:145], v[186:189], 0
	v_mfma_f32_16x16x32_bf16 v[26:29], v[134:137], v[186:189], 0
	v_mfma_f32_16x16x32_bf16 v[22:25], v[142:145], v[178:181], 0
	v_mfma_f32_16x16x32_bf16 v[18:21], v[134:137], v[178:181], 0
	v_mfma_f32_16x16x32_bf16 v[14:17], v[142:145], v[170:173], 0
	v_mfma_f32_16x16x32_bf16 v[10:13], v[134:137], v[170:173], 0
	v_mfma_f32_16x16x32_bf16 v[6:9], v[142:145], v[162:165], 0
	v_mfma_f32_16x16x32_bf16 v[2:5], v[134:137], v[162:165], 0
	s_nop 0
	v_mfma_f32_16x16x32_bf16 v[30:33], v[138:141], v[190:193], v[30:33]
	v_mfma_f32_16x16x32_bf16 v[26:29], v[130:133], v[190:193], v[26:29]
	v_mfma_f32_16x16x32_bf16 v[22:25], v[138:141], v[182:185], v[22:25]
	v_mfma_f32_16x16x32_bf16 v[18:21], v[130:133], v[182:185], v[18:21]
	v_mfma_f32_16x16x32_bf16 v[14:17], v[138:141], v[174:177], v[14:17]
	v_mfma_f32_16x16x32_bf16 v[10:13], v[130:133], v[174:177], v[10:13]
	v_mfma_f32_16x16x32_bf16 v[6:9], v[138:141], v[166:169], v[6:9]
	v_mfma_f32_16x16x32_bf16 v[2:5], v[130:133], v[166:169], v[2:5]
	s_barrier
	s_add_i32 s4, 0, 0x18000
	v_add_u32_e32 v223, s4, v209
	v_add_u32_e32 v224, s4, v210
	s_add_i32 s4, 0, 0x1c000
	v_add_u32_e32 v225, s46, v209
	v_add_u32_e32 v228, s4, v209
	v_add_u32_e32 v230, s47, v209
	ds_read_b128 v[146:149], v223
	ds_read_b128 v[150:153], v224
	v_add_u32_e32 v227, s46, v210
	ds_read_b128 v[154:157], v225
	ds_read_b128 v[158:161], v227
	v_add_u32_e32 v229, s4, v210
	ds_read_b128 v[130:133], v228
	ds_read_b128 v[134:137], v229
	v_add_u32_e32 v231, s47, v210
	ds_read_b128 v[138:141], v230
	ds_read_b128 v[142:145], v231
	s_mov_b32 m0, s30
	s_add_i32 s33, s33, s60
	s_mov_b32 s4, s70
	ds_read_b128 v[186:189], v219 offset:32768
	ds_read_b128 v[174:177], v219 offset:34816
	ds_read_b128 v[190:193], v220 offset:32768
	ds_read_b128 v[178:181], v220 offset:34816
	ds_read_b128 v[170:173], v219 offset:36864
	ds_read_b128 v[162:165], v219 offset:38912
	ds_read_b128 v[182:185], v220 offset:36864
	ds_read_b128 v[166:169], v220 offset:38912
	buffer_load_dwordx4 v194, s[4:7], s33 offen lds
	s_mov_b32 m0, s31
	s_and_b64 vcc, exec, s[2:3]
	buffer_load_dwordx4 v222, s[4:7], s33 offen lds
	s_cbranch_vccnz .LBB0_558
	s_waitcnt vmcnt(16)
	s_cbranch_execnz .LBB0_536

.LBB0_536:
	s_waitcnt lgkmcnt(0)
	s_add_i32 s62, s55, 0x180
	s_add_i32 s22, s61, 0x180
	s_barrier
	s_waitcnt lgkmcnt(7)
	v_mfma_f32_16x16x32_bf16 v[126:129], v[146:149], v[186:189], v[126:129]
	v_mfma_f32_16x16x32_bf16 v[122:125], v[154:157], v[186:189], v[122:125]
	s_waitcnt lgkmcnt(6)
	v_mfma_f32_16x16x32_bf16 v[118:121], v[146:149], v[174:177], v[118:121]
	v_mfma_f32_16x16x32_bf16 v[114:117], v[154:157], v[174:177], v[114:117]
	s_waitcnt lgkmcnt(3)
	v_mfma_f32_16x16x32_bf16 v[110:113], v[146:149], v[170:173], v[110:113]
	v_mfma_f32_16x16x32_bf16 v[106:109], v[154:157], v[170:173], v[106:109]
	s_waitcnt lgkmcnt(2)
	v_mfma_f32_16x16x32_bf16 v[102:105], v[146:149], v[162:165], v[102:105]
	v_mfma_f32_16x16x32_bf16 v[98:101], v[154:157], v[162:165], v[98:101]
	v_mfma_f32_16x16x32_bf16 v[126:129], v[150:153], v[190:193], v[126:129]
	v_mfma_f32_16x16x32_bf16 v[122:125], v[158:161], v[190:193], v[122:125]
	v_mfma_f32_16x16x32_bf16 v[118:121], v[150:153], v[178:181], v[118:121]
	v_mfma_f32_16x16x32_bf16 v[114:117], v[158:161], v[178:181], v[114:117]
	s_waitcnt lgkmcnt(1)
	v_mfma_f32_16x16x32_bf16 v[110:113], v[150:153], v[182:185], v[110:113]
	v_mfma_f32_16x16x32_bf16 v[106:109], v[158:161], v[182:185], v[106:109]
	s_waitcnt lgkmcnt(0)
	v_mfma_f32_16x16x32_bf16 v[102:105], v[150:153], v[166:169], v[102:105]
	v_mfma_f32_16x16x32_bf16 v[98:101], v[158:161], v[166:169], v[98:101]
	v_mfma_f32_16x16x32_bf16 v[94:97], v[130:133], v[186:189], v[94:97]
	v_mfma_f32_16x16x32_bf16 v[90:93], v[138:141], v[186:189], v[90:93]
	v_mfma_f32_16x16x32_bf16 v[86:89], v[130:133], v[174:177], v[86:89]
	v_mfma_f32_16x16x32_bf16 v[82:85], v[138:141], v[174:177], v[82:85]
	v_mfma_f32_16x16x32_bf16 v[78:81], v[130:133], v[170:173], v[78:81]
	v_mfma_f32_16x16x32_bf16 v[74:77], v[138:141], v[170:173], v[74:77]
	v_mfma_f32_16x16x32_bf16 v[70:73], v[130:133], v[162:165], v[70:73]
	v_mfma_f32_16x16x32_bf16 v[66:69], v[138:141], v[162:165], v[66:69]
	v_mfma_f32_16x16x32_bf16 v[94:97], v[134:137], v[190:193], v[94:97]
	v_mfma_f32_16x16x32_bf16 v[90:93], v[142:145], v[190:193], v[90:93]
	v_mfma_f32_16x16x32_bf16 v[86:89], v[134:137], v[178:181], v[86:89]
	v_mfma_f32_16x16x32_bf16 v[82:85], v[142:145], v[178:181], v[82:85]
	v_mfma_f32_16x16x32_bf16 v[78:81], v[134:137], v[182:185], v[78:81]
	v_mfma_f32_16x16x32_bf16 v[74:77], v[142:145], v[182:185], v[74:77]
	v_mfma_f32_16x16x32_bf16 v[70:73], v[134:137], v[166:169], v[70:73]
	v_mfma_f32_16x16x32_bf16 v[66:69], v[142:145], v[166:169], v[66:69]
	s_barrier
	s_mov_b32 m0, s36
	s_mov_b32 s4, s70
	ds_read_b128 v[186:189], v219 offset:49152
	ds_read_b128 v[174:177], v219 offset:51200
	ds_read_b128 v[190:193], v220 offset:49152
	ds_read_b128 v[178:181], v220 offset:51200
	ds_read_b128 v[170:173], v219 offset:53248
	ds_read_b128 v[162:165], v219 offset:55296
	ds_read_b128 v[182:185], v220 offset:53248
	ds_read_b128 v[166:169], v220 offset:55296
	buffer_load_dwordx4 v233, s[4:7], s22 offen lds
	s_mov_b32 m0, s37
	s_and_b64 vcc, exec, s[2:3]
	buffer_load_dwordx4 v234, s[4:7], s22 offen lds
	s_add_i32 s22, s22, s60
	s_mov_b32 m0, s40
	s_nop 0
	buffer_load_dwordx4 v233, s[4:7], s22 offen lds
	s_mov_b32 m0, s41
	s_nop 0
	buffer_load_dwordx4 v234, s[4:7], s22 offen lds
	s_mov_b32 m0, s38
	s_nop 0
	buffer_load_dwordx4 v194, s[4:7], s62 offen lds
	s_mov_b32 m0, s39
	s_nop 0
	buffer_load_dwordx4 v222, s[4:7], s62 offen lds
	s_cbranch_vccnz .LBB0_559
	s_waitcnt vmcnt(22)
	s_cbranch_execnz .LBB0_539

.LBB0_539:
	s_waitcnt lgkmcnt(0)
	s_barrier
	s_waitcnt lgkmcnt(7)
	v_mfma_f32_16x16x32_bf16 v[62:65], v[146:149], v[186:189], v[62:65]
	v_mfma_f32_16x16x32_bf16 v[58:61], v[154:157], v[186:189], v[58:61]
	s_waitcnt lgkmcnt(6)
	v_mfma_f32_16x16x32_bf16 v[54:57], v[146:149], v[174:177], v[54:57]
	v_mfma_f32_16x16x32_bf16 v[50:53], v[154:157], v[174:177], v[50:53]
	s_waitcnt lgkmcnt(3)
	v_mfma_f32_16x16x32_bf16 v[46:49], v[146:149], v[170:173], v[46:49]
	v_mfma_f32_16x16x32_bf16 v[42:45], v[154:157], v[170:173], v[42:45]
	s_waitcnt lgkmcnt(2)
	v_mfma_f32_16x16x32_bf16 v[38:41], v[146:149], v[162:165], v[38:41]
	v_mfma_f32_16x16x32_bf16 v[34:37], v[154:157], v[162:165], v[34:37]
	v_mfma_f32_16x16x32_bf16 v[62:65], v[150:153], v[190:193], v[62:65]
	v_mfma_f32_16x16x32_bf16 v[58:61], v[158:161], v[190:193], v[58:61]
	v_mfma_f32_16x16x32_bf16 v[54:57], v[150:153], v[178:181], v[54:57]
	v_mfma_f32_16x16x32_bf16 v[50:53], v[158:161], v[178:181], v[50:53]
	s_waitcnt lgkmcnt(1)
	v_mfma_f32_16x16x32_bf16 v[46:49], v[150:153], v[182:185], v[46:49]
	v_mfma_f32_16x16x32_bf16 v[42:45], v[158:161], v[182:185], v[42:45]
	s_waitcnt lgkmcnt(0)
	v_mfma_f32_16x16x32_bf16 v[38:41], v[150:153], v[166:169], v[38:41]
	v_mfma_f32_16x16x32_bf16 v[34:37], v[158:161], v[166:169], v[34:37]
	v_mfma_f32_16x16x32_bf16 v[30:33], v[130:133], v[186:189], v[30:33]
	v_mfma_f32_16x16x32_bf16 v[26:29], v[138:141], v[186:189], v[26:29]
	v_mfma_f32_16x16x32_bf16 v[22:25], v[130:133], v[174:177], v[22:25]
	v_mfma_f32_16x16x32_bf16 v[18:21], v[138:141], v[174:177], v[18:21]
	v_mfma_f32_16x16x32_bf16 v[14:17], v[130:133], v[170:173], v[14:17]
	v_mfma_f32_16x16x32_bf16 v[10:13], v[138:141], v[170:173], v[10:13]
	v_mfma_f32_16x16x32_bf16 v[6:9], v[130:133], v[162:165], v[6:9]
	v_mfma_f32_16x16x32_bf16 v[2:5], v[138:141], v[162:165], v[2:5]
	v_mfma_f32_16x16x32_bf16 v[30:33], v[134:137], v[190:193], v[30:33]
	v_mfma_f32_16x16x32_bf16 v[26:29], v[142:145], v[190:193], v[26:29]
	v_mfma_f32_16x16x32_bf16 v[22:25], v[134:137], v[178:181], v[22:25]
	v_mfma_f32_16x16x32_bf16 v[18:21], v[142:145], v[178:181], v[18:21]
	v_mfma_f32_16x16x32_bf16 v[14:17], v[134:137], v[182:185], v[14:17]
	v_mfma_f32_16x16x32_bf16 v[10:13], v[142:145], v[182:185], v[10:13]
	v_mfma_f32_16x16x32_bf16 v[6:9], v[134:137], v[166:169], v[6:9]
	v_mfma_f32_16x16x32_bf16 v[2:5], v[142:145], v[166:169], v[2:5]
	s_barrier
	s_add_i32 s53, s54, 1
	s_mul_hi_u32 s2, s53, 0xaaaaaaab
	s_lshr_b32 s4, s2, 1
	s_mul_i32 s3, s4, s94
	s_mul_hi_i32 s2, s4, s94
	s_add_u32 s22, s3, s95
	s_addc_u32 s23, s2, s45
	v_cmp_gt_i64_e32 vcc, s[22:23], v[198:199]
	v_cmp_lt_i64_e64 s[2:3], s[22:23], v[196:197]
	s_mov_b32 s33, s59
	s_cbranch_vccnz .LBB0_545
	s_ashr_i32 s23, s22, 31
	s_lshr_b32 s23, s23, 29
	s_add_i32 s33, s22, s23
	s_and_b32 s23, s33, -8
	s_sub_i32 s51, s22, s23
	s_cmp_gt_i32 s51, -1
	s_mov_b64 s[22:23], -1
	s_cbranch_scc0 .LBB0_542
	s_lshl_b32 s50, s51, 7
	s_mov_b64 s[22:23], 0

.LBB0_546:
	ds_read_b128 v[130:133], v211
	ds_read_b128 v[134:137], v212
	ds_read_b128 v[138:141], v213
	ds_read_b128 v[142:145], v214
	ds_read_b128 v[146:149], v215
	ds_read_b128 v[150:153], v216
	ds_read_b128 v[154:157], v217
	ds_read_b128 v[158:161], v218
	s_add_i32 s4, s62, 0x80
	s_cmp_eq_u32 s63, s78
	s_cselect_b32 s84, s64, s4
	s_cselect_b32 s82, s33, s59
	s_cselect_b32 s81, s65, s61
	s_cselect_b32 s80, s56, s60
	s_add_i32 s79, s84, 0x80
	s_add_i32 s83, s60, s62
	s_mov_b32 s4, s70
	s_mov_b32 m0, s43
	ds_read_b128 v[162:165], v219
	ds_read_b128 v[166:169], v219 offset:2048
	ds_read_b128 v[170:173], v220
	ds_read_b128 v[174:177], v220 offset:2048
	ds_read_b128 v[178:181], v219 offset:4096
	ds_read_b128 v[182:185], v219 offset:6144
	ds_read_b128 v[186:189], v220 offset:4096
	ds_read_b128 v[190:193], v220 offset:6144
	buffer_load_dwordx4 v194, s[4:7], s83 offen lds
	s_mov_b32 m0, s44
	s_nop 0
	buffer_load_dwordx4 v222, s[4:7], s83 offen lds
	s_waitcnt vmcnt(8)
	s_waitcnt lgkmcnt(0)
	s_barrier
	s_waitcnt lgkmcnt(7)
	v_mfma_f32_16x16x32_bf16 v[126:129], v[130:133], v[162:165], v[126:129]
	v_mfma_f32_16x16x32_bf16 v[122:125], v[138:141], v[162:165], v[122:125]
	s_waitcnt lgkmcnt(6)
	v_mfma_f32_16x16x32_bf16 v[118:121], v[130:133], v[166:169], v[118:121]
	v_mfma_f32_16x16x32_bf16 v[114:117], v[138:141], v[166:169], v[114:117]
	s_waitcnt lgkmcnt(3)
	v_mfma_f32_16x16x32_bf16 v[110:113], v[130:133], v[178:181], v[110:113]
	v_mfma_f32_16x16x32_bf16 v[106:109], v[138:141], v[178:181], v[106:109]
	s_waitcnt lgkmcnt(2)
	v_mfma_f32_16x16x32_bf16 v[102:105], v[130:133], v[182:185], v[102:105]
	v_mfma_f32_16x16x32_bf16 v[98:101], v[138:141], v[182:185], v[98:101]
	v_mfma_f32_16x16x32_bf16 v[126:129], v[134:137], v[170:173], v[126:129]
	v_mfma_f32_16x16x32_bf16 v[122:125], v[142:145], v[170:173], v[122:125]
	v_mfma_f32_16x16x32_bf16 v[118:121], v[134:137], v[174:177], v[118:121]
	v_mfma_f32_16x16x32_bf16 v[114:117], v[142:145], v[174:177], v[114:117]
	s_waitcnt lgkmcnt(1)
	v_mfma_f32_16x16x32_bf16 v[110:113], v[134:137], v[186:189], v[110:113]
	v_mfma_f32_16x16x32_bf16 v[106:109], v[142:145], v[186:189], v[106:109]
	s_waitcnt lgkmcnt(0)
	v_mfma_f32_16x16x32_bf16 v[102:105], v[134:137], v[190:193], v[102:105]
	v_mfma_f32_16x16x32_bf16 v[98:101], v[142:145], v[190:193], v[98:101]
	v_mfma_f32_16x16x32_bf16 v[94:97], v[146:149], v[162:165], v[94:97]
	v_mfma_f32_16x16x32_bf16 v[90:93], v[154:157], v[162:165], v[90:93]
	v_mfma_f32_16x16x32_bf16 v[86:89], v[146:149], v[166:169], v[86:89]
	v_mfma_f32_16x16x32_bf16 v[82:85], v[154:157], v[166:169], v[82:85]
	v_mfma_f32_16x16x32_bf16 v[78:81], v[146:149], v[178:181], v[78:81]
	v_mfma_f32_16x16x32_bf16 v[74:77], v[154:157], v[178:181], v[74:77]
	v_mfma_f32_16x16x32_bf16 v[70:73], v[146:149], v[182:185], v[70:73]
	v_mfma_f32_16x16x32_bf16 v[66:69], v[154:157], v[182:185], v[66:69]
	v_mfma_f32_16x16x32_bf16 v[94:97], v[150:153], v[170:173], v[94:97]
	v_mfma_f32_16x16x32_bf16 v[90:93], v[158:161], v[170:173], v[90:93]
	v_mfma_f32_16x16x32_bf16 v[86:89], v[150:153], v[174:177], v[86:89]
	v_mfma_f32_16x16x32_bf16 v[82:85], v[158:161], v[174:177], v[82:85]
	v_mfma_f32_16x16x32_bf16 v[78:81], v[150:153], v[186:189], v[78:81]
	v_mfma_f32_16x16x32_bf16 v[74:77], v[158:161], v[186:189], v[74:77]
	v_mfma_f32_16x16x32_bf16 v[70:73], v[150:153], v[190:193], v[70:73]
	v_mfma_f32_16x16x32_bf16 v[66:69], v[158:161], v[190:193], v[66:69]
	s_barrier
	s_cmp_eq_u32 s82, 0
	s_cselect_b64 s[82:83], -1, 0
	v_cndmask_b32_e64 v233, v200, 0, s[82:83]
	s_mov_b32 m0, s25
	v_sub_u32_e32 v233, v201, v233
	v_cndmask_b32_e64 v234, v203, 0, s[82:83]
	ds_read_b128 v[162:165], v219 offset:16384
	ds_read_b128 v[166:169], v219 offset:18432
	ds_read_b128 v[170:173], v220 offset:16384
	ds_read_b128 v[174:177], v220 offset:18432
	ds_read_b128 v[178:181], v219 offset:20480
	ds_read_b128 v[182:185], v219 offset:22528
	ds_read_b128 v[186:189], v220 offset:20480
	ds_read_b128 v[190:193], v220 offset:22528
	buffer_load_dwordx4 v233, s[4:7], s81 offen lds
	v_sub_u32_e32 v234, v204, v234
	s_mov_b32 m0, s26
	s_add_i32 s85, s81, s80
	buffer_load_dwordx4 v234, s[4:7], s81 offen lds
	s_mov_b32 m0, s27
	v_cndmask_b32_e64 v235, v205, 0, s[82:83]
	buffer_load_dwordx4 v233, s[4:7], s85 offen lds
	s_mov_b32 m0, s28
	v_sub_u32_e32 v235, v1, v235
	buffer_load_dwordx4 v234, s[4:7], s85 offen lds
	s_mov_b32 m0, s24
	v_cndmask_b32_e64 v236, v206, 0, s[82:83]
	buffer_load_dwordx4 v235, s[4:7], s84 offen lds
	v_sub_u32_e32 v236, v202, v236
	s_mov_b32 m0, s29
	s_nop 0
	buffer_load_dwordx4 v236, s[4:7], s84 offen lds
	s_waitcnt vmcnt(8)
	s_waitcnt lgkmcnt(0)
	s_barrier
	s_waitcnt lgkmcnt(7)
	v_mfma_f32_16x16x32_bf16 v[62:65], v[130:133], v[162:165], v[62:65]
	v_mfma_f32_16x16x32_bf16 v[58:61], v[138:141], v[162:165], v[58:61]
	s_waitcnt lgkmcnt(6)
	v_mfma_f32_16x16x32_bf16 v[54:57], v[130:133], v[166:169], v[54:57]
	v_mfma_f32_16x16x32_bf16 v[50:53], v[138:141], v[166:169], v[50:53]
	s_waitcnt lgkmcnt(3)
	v_mfma_f32_16x16x32_bf16 v[46:49], v[130:133], v[178:181], v[46:49]
	v_mfma_f32_16x16x32_bf16 v[42:45], v[138:141], v[178:181], v[42:45]
	s_waitcnt lgkmcnt(2)
	v_mfma_f32_16x16x32_bf16 v[38:41], v[130:133], v[182:185], v[38:41]
	v_mfma_f32_16x16x32_bf16 v[34:37], v[138:141], v[182:185], v[34:37]
	v_mfma_f32_16x16x32_bf16 v[62:65], v[134:137], v[170:173], v[62:65]
	v_mfma_f32_16x16x32_bf16 v[58:61], v[142:145], v[170:173], v[58:61]
	v_mfma_f32_16x16x32_bf16 v[54:57], v[134:137], v[174:177], v[54:57]
	v_mfma_f32_16x16x32_bf16 v[50:53], v[142:145], v[174:177], v[50:53]
	s_waitcnt lgkmcnt(1)
	v_mfma_f32_16x16x32_bf16 v[46:49], v[134:137], v[186:189], v[46:49]
	v_mfma_f32_16x16x32_bf16 v[42:45], v[142:145], v[186:189], v[42:45]
	s_waitcnt lgkmcnt(0)
	v_mfma_f32_16x16x32_bf16 v[38:41], v[134:137], v[190:193], v[38:41]
	v_mfma_f32_16x16x32_bf16 v[34:37], v[142:145], v[190:193], v[34:37]
	v_mfma_f32_16x16x32_bf16 v[30:33], v[146:149], v[162:165], v[30:33]
	v_mfma_f32_16x16x32_bf16 v[26:29], v[154:157], v[162:165], v[26:29]
	v_mfma_f32_16x16x32_bf16 v[22:25], v[146:149], v[166:169], v[22:25]
	v_mfma_f32_16x16x32_bf16 v[18:21], v[154:157], v[166:169], v[18:21]
	v_mfma_f32_16x16x32_bf16 v[14:17], v[146:149], v[178:181], v[14:17]
	v_mfma_f32_16x16x32_bf16 v[10:13], v[154:157], v[178:181], v[10:13]
	v_mfma_f32_16x16x32_bf16 v[6:9], v[146:149], v[182:185], v[6:9]
	v_mfma_f32_16x16x32_bf16 v[2:5], v[154:157], v[182:185], v[2:5]
	v_mfma_f32_16x16x32_bf16 v[30:33], v[150:153], v[170:173], v[30:33]
	v_mfma_f32_16x16x32_bf16 v[26:29], v[158:161], v[170:173], v[26:29]
	v_mfma_f32_16x16x32_bf16 v[22:25], v[150:153], v[174:177], v[22:25]
	v_mfma_f32_16x16x32_bf16 v[18:21], v[158:161], v[174:177], v[18:21]
	v_mfma_f32_16x16x32_bf16 v[14:17], v[150:153], v[186:189], v[14:17]
	v_mfma_f32_16x16x32_bf16 v[10:13], v[158:161], v[186:189], v[10:13]
	v_mfma_f32_16x16x32_bf16 v[6:9], v[150:153], v[190:193], v[6:9]
	v_mfma_f32_16x16x32_bf16 v[2:5], v[158:161], v[190:193], v[2:5]
	s_barrier
	ds_read_b128 v[130:133], v223
	ds_read_b128 v[134:137], v224
	ds_read_b128 v[138:141], v225
	ds_read_b128 v[142:145], v227
	ds_read_b128 v[146:149], v228
	ds_read_b128 v[150:153], v229
	ds_read_b128 v[154:157], v230
	ds_read_b128 v[158:161], v231
	s_add_i32 s84, s84, s80
	s_mov_b32 m0, s30
	ds_read_b128 v[162:165], v219 offset:32768
	ds_read_b128 v[166:169], v219 offset:34816
	ds_read_b128 v[170:173], v220 offset:32768
	ds_read_b128 v[174:177], v220 offset:34816
	ds_read_b128 v[178:181], v219 offset:36864
	ds_read_b128 v[182:185], v219 offset:38912
	ds_read_b128 v[186:189], v220 offset:36864
	ds_read_b128 v[190:193], v220 offset:38912
	buffer_load_dwordx4 v235, s[4:7], s84 offen lds
	s_mov_b32 m0, s31
	s_nop 0
	buffer_load_dwordx4 v236, s[4:7], s84 offen lds
	s_waitcnt vmcnt(8)
	s_waitcnt lgkmcnt(0)
	s_barrier
	s_waitcnt lgkmcnt(7)
	v_mfma_f32_16x16x32_bf16 v[126:129], v[130:133], v[162:165], v[126:129]
	v_mfma_f32_16x16x32_bf16 v[122:125], v[138:141], v[162:165], v[122:125]
	s_waitcnt lgkmcnt(6)
	v_mfma_f32_16x16x32_bf16 v[118:121], v[130:133], v[166:169], v[118:121]
	v_mfma_f32_16x16x32_bf16 v[114:117], v[138:141], v[166:169], v[114:117]
	s_waitcnt lgkmcnt(3)
	v_mfma_f32_16x16x32_bf16 v[110:113], v[130:133], v[178:181], v[110:113]
	v_mfma_f32_16x16x32_bf16 v[106:109], v[138:141], v[178:181], v[106:109]
	s_waitcnt lgkmcnt(2)
	v_mfma_f32_16x16x32_bf16 v[102:105], v[130:133], v[182:185], v[102:105]
	v_mfma_f32_16x16x32_bf16 v[98:101], v[138:141], v[182:185], v[98:101]
	v_mfma_f32_16x16x32_bf16 v[126:129], v[134:137], v[170:173], v[126:129]
	v_mfma_f32_16x16x32_bf16 v[122:125], v[142:145], v[170:173], v[122:125]
	v_mfma_f32_16x16x32_bf16 v[118:121], v[134:137], v[174:177], v[118:121]
	v_mfma_f32_16x16x32_bf16 v[114:117], v[142:145], v[174:177], v[114:117]
	s_waitcnt lgkmcnt(1)
	v_mfma_f32_16x16x32_bf16 v[110:113], v[134:137], v[186:189], v[110:113]
	v_mfma_f32_16x16x32_bf16 v[106:109], v[142:145], v[186:189], v[106:109]
	s_waitcnt lgkmcnt(0)
	v_mfma_f32_16x16x32_bf16 v[102:105], v[134:137], v[190:193], v[102:105]
	v_mfma_f32_16x16x32_bf16 v[98:101], v[142:145], v[190:193], v[98:101]
	v_mfma_f32_16x16x32_bf16 v[94:97], v[146:149], v[162:165], v[94:97]
	v_mfma_f32_16x16x32_bf16 v[90:93], v[154:157], v[162:165], v[90:93]
	v_mfma_f32_16x16x32_bf16 v[86:89], v[146:149], v[166:169], v[86:89]
	v_mfma_f32_16x16x32_bf16 v[82:85], v[154:157], v[166:169], v[82:85]
	v_mfma_f32_16x16x32_bf16 v[78:81], v[146:149], v[178:181], v[78:81]
	v_mfma_f32_16x16x32_bf16 v[74:77], v[154:157], v[178:181], v[74:77]
	v_mfma_f32_16x16x32_bf16 v[70:73], v[146:149], v[182:185], v[70:73]
	v_mfma_f32_16x16x32_bf16 v[66:69], v[154:157], v[182:185], v[66:69]
	v_mfma_f32_16x16x32_bf16 v[94:97], v[150:153], v[170:173], v[94:97]
	v_mfma_f32_16x16x32_bf16 v[90:93], v[158:161], v[170:173], v[90:93]
	v_mfma_f32_16x16x32_bf16 v[86:89], v[150:153], v[174:177], v[86:89]
	v_mfma_f32_16x16x32_bf16 v[82:85], v[158:161], v[174:177], v[82:85]
	v_mfma_f32_16x16x32_bf16 v[78:81], v[150:153], v[186:189], v[78:81]
	v_mfma_f32_16x16x32_bf16 v[74:77], v[158:161], v[186:189], v[74:77]
	v_mfma_f32_16x16x32_bf16 v[70:73], v[150:153], v[190:193], v[70:73]
	v_mfma_f32_16x16x32_bf16 v[66:69], v[158:161], v[190:193], v[66:69]
	s_barrier
	s_mov_b32 m0, s36
	s_addk_i32 s81, 0x80
	ds_read_b128 v[162:165], v219 offset:49152
	ds_read_b128 v[166:169], v219 offset:51200
	ds_read_b128 v[170:173], v220 offset:49152
	ds_read_b128 v[174:177], v220 offset:51200
	ds_read_b128 v[178:181], v219 offset:53248
	ds_read_b128 v[182:185], v219 offset:55296
	ds_read_b128 v[186:189], v220 offset:53248
	ds_read_b128 v[190:193], v220 offset:55296
	buffer_load_dwordx4 v233, s[4:7], s81 offen lds
	s_mov_b32 m0, s37
	s_nop 0
	buffer_load_dwordx4 v234, s[4:7], s81 offen lds
	s_add_i32 s81, s81, s80
	s_mov_b32 m0, s40
	s_nop 0
	buffer_load_dwordx4 v233, s[4:7], s81 offen lds
	s_mov_b32 m0, s41
	s_nop 0
	buffer_load_dwordx4 v234, s[4:7], s81 offen lds
	s_mov_b32 m0, s38
	s_nop 0
	buffer_load_dwordx4 v235, s[4:7], s79 offen lds
	s_mov_b32 m0, s39
	s_nop 0
	buffer_load_dwordx4 v236, s[4:7], s79 offen lds
	s_waitcnt vmcnt(8)
	s_waitcnt lgkmcnt(0)
	s_barrier
	s_waitcnt lgkmcnt(7)
	v_mfma_f32_16x16x32_bf16 v[62:65], v[130:133], v[162:165], v[62:65]
	v_mfma_f32_16x16x32_bf16 v[58:61], v[138:141], v[162:165], v[58:61]
	s_waitcnt lgkmcnt(6)
	v_mfma_f32_16x16x32_bf16 v[54:57], v[130:133], v[166:169], v[54:57]
	v_mfma_f32_16x16x32_bf16 v[50:53], v[138:141], v[166:169], v[50:53]
	s_waitcnt lgkmcnt(3)
	v_mfma_f32_16x16x32_bf16 v[46:49], v[130:133], v[178:181], v[46:49]
	v_mfma_f32_16x16x32_bf16 v[42:45], v[138:141], v[178:181], v[42:45]
	s_waitcnt lgkmcnt(2)
	v_mfma_f32_16x16x32_bf16 v[38:41], v[130:133], v[182:185], v[38:41]
	v_mfma_f32_16x16x32_bf16 v[34:37], v[138:141], v[182:185], v[34:37]
	v_mfma_f32_16x16x32_bf16 v[62:65], v[134:137], v[170:173], v[62:65]
	v_mfma_f32_16x16x32_bf16 v[58:61], v[142:145], v[170:173], v[58:61]
	v_mfma_f32_16x16x32_bf16 v[54:57], v[134:137], v[174:177], v[54:57]
	v_mfma_f32_16x16x32_bf16 v[50:53], v[142:145], v[174:177], v[50:53]
	s_waitcnt lgkmcnt(1)
	v_mfma_f32_16x16x32_bf16 v[46:49], v[134:137], v[186:189], v[46:49]
	v_mfma_f32_16x16x32_bf16 v[42:45], v[142:145], v[186:189], v[42:45]
	s_waitcnt lgkmcnt(0)
	v_mfma_f32_16x16x32_bf16 v[38:41], v[134:137], v[190:193], v[38:41]
	v_mfma_f32_16x16x32_bf16 v[34:37], v[142:145], v[190:193], v[34:37]
	v_mfma_f32_16x16x32_bf16 v[30:33], v[146:149], v[162:165], v[30:33]
	v_mfma_f32_16x16x32_bf16 v[26:29], v[154:157], v[162:165], v[26:29]
	v_mfma_f32_16x16x32_bf16 v[22:25], v[146:149], v[166:169], v[22:25]
	v_mfma_f32_16x16x32_bf16 v[18:21], v[154:157], v[166:169], v[18:21]
	v_mfma_f32_16x16x32_bf16 v[14:17], v[146:149], v[178:181], v[14:17]
	v_mfma_f32_16x16x32_bf16 v[10:13], v[154:157], v[178:181], v[10:13]
	v_mfma_f32_16x16x32_bf16 v[6:9], v[146:149], v[182:185], v[6:9]
	v_mfma_f32_16x16x32_bf16 v[2:5], v[154:157], v[182:185], v[2:5]
	v_mfma_f32_16x16x32_bf16 v[30:33], v[150:153], v[170:173], v[30:33]
	v_mfma_f32_16x16x32_bf16 v[26:29], v[158:161], v[170:173], v[26:29]
	v_mfma_f32_16x16x32_bf16 v[22:25], v[150:153], v[174:177], v[22:25]
	v_mfma_f32_16x16x32_bf16 v[18:21], v[158:161], v[174:177], v[18:21]
	v_mfma_f32_16x16x32_bf16 v[14:17], v[150:153], v[186:189], v[14:17]
	v_mfma_f32_16x16x32_bf16 v[10:13], v[158:161], v[186:189], v[10:13]
	v_mfma_f32_16x16x32_bf16 v[6:9], v[150:153], v[190:193], v[6:9]
	v_mfma_f32_16x16x32_bf16 v[2:5], v[158:161], v[190:193], v[2:5]
	s_barrier
	s_add_i32 s4, s78, 2
	s_addk_i32 s62, 0x100
	s_addk_i32 s61, 0x100
	s_cmp_ge_u32 s78, s63
	s_mov_b32 s78, s4
	s_cbranch_scc0 .LBB0_546
	s_and_b64 vcc, exec, s[12:13]
	s_cbranch_vccz .LBB0_549
	s_barrier

.LBB0_822:
	s_waitcnt lgkmcnt(0)
	s_add_i32 s2, s42, 0x100
	s_add_i32 s3, s34, 0x100
	s_barrier
	s_waitcnt lgkmcnt(7)
	v_mfma_f32_16x16x32_bf16 v[74:77], v[190:193], v[218:221], 0
	v_mfma_f32_16x16x32_bf16 v[70:73], v[182:185], v[218:221], 0
	s_waitcnt lgkmcnt(6)
	v_mfma_f32_16x16x32_bf16 v[66:69], v[190:193], v[210:213], 0
	v_mfma_f32_16x16x32_bf16 v[82:85], v[182:185], v[210:213], 0
	s_waitcnt lgkmcnt(3)
	v_mfma_f32_16x16x32_bf16 v[78:81], v[190:193], v[202:205], 0
	v_mfma_f32_16x16x32_bf16 v[90:93], v[182:185], v[202:205], 0
	s_waitcnt lgkmcnt(2)
	v_mfma_f32_16x16x32_bf16 v[86:89], v[190:193], v[194:197], 0
	v_mfma_f32_16x16x32_bf16 v[102:105], v[182:185], v[194:197], 0
	v_mfma_f32_16x16x32_bf16 v[74:77], v[186:189], v[222:225], v[74:77]
	v_mfma_f32_16x16x32_bf16 v[70:73], v[178:181], v[222:225], v[70:73]
	v_mfma_f32_16x16x32_bf16 v[66:69], v[186:189], v[214:217], v[66:69]
	v_mfma_f32_16x16x32_bf16 v[82:85], v[178:181], v[214:217], v[82:85]
	s_waitcnt lgkmcnt(1)
	v_mfma_f32_16x16x32_bf16 v[78:81], v[186:189], v[206:209], v[78:81]
	v_mfma_f32_16x16x32_bf16 v[90:93], v[178:181], v[206:209], v[90:93]
	s_waitcnt lgkmcnt(0)
	v_mfma_f32_16x16x32_bf16 v[86:89], v[186:189], v[198:201], v[86:89]
	v_mfma_f32_16x16x32_bf16 v[102:105], v[178:181], v[198:201], v[102:105]
	v_mfma_f32_16x16x32_bf16 v[98:101], v[174:177], v[218:221], 0
	v_mfma_f32_16x16x32_bf16 v[94:97], v[142:145], v[218:221], 0
	v_mfma_f32_16x16x32_bf16 v[106:109], v[174:177], v[210:213], 0
	v_mfma_f32_16x16x32_bf16 v[110:113], v[142:145], v[210:213], 0
	v_mfma_f32_16x16x32_bf16 v[114:117], v[174:177], v[202:205], 0
	v_mfma_f32_16x16x32_bf16 v[118:121], v[142:145], v[202:205], 0
	v_mfma_f32_16x16x32_bf16 v[122:125], v[174:177], v[194:197], 0
	v_mfma_f32_16x16x32_bf16 v[126:129], v[142:145], v[194:197], 0
	s_nop 0
	v_mfma_f32_16x16x32_bf16 v[98:101], v[170:173], v[222:225], v[98:101]
	v_mfma_f32_16x16x32_bf16 v[94:97], v[134:137], v[222:225], v[94:97]
	v_mfma_f32_16x16x32_bf16 v[106:109], v[170:173], v[214:217], v[106:109]
	v_mfma_f32_16x16x32_bf16 v[110:113], v[134:137], v[214:217], v[110:113]
	v_mfma_f32_16x16x32_bf16 v[114:117], v[170:173], v[206:209], v[114:117]
	v_mfma_f32_16x16x32_bf16 v[118:121], v[134:137], v[206:209], v[118:121]
	v_mfma_f32_16x16x32_bf16 v[122:125], v[170:173], v[198:201], v[122:125]
	v_mfma_f32_16x16x32_bf16 v[126:129], v[134:137], v[198:201], v[126:129]
	s_barrier
	s_mov_b32 m0, s29
	ds_read_b128 v[202:205], v248 offset:16384
	ds_read_b128 v[194:197], v248 offset:18432
	ds_read_b128 v[206:209], v249 offset:16384
	ds_read_b128 v[198:201], v249 offset:18432
	ds_read_b128 v[154:157], v248 offset:20480
	ds_read_b128 v[146:149], v248 offset:22528
	ds_read_b128 v[158:161], v249 offset:20480
	ds_read_b128 v[150:153], v249 offset:22528
	buffer_load_dwordx4 v233, s[12:15], s3 offen lds
	s_mov_b32 m0, s30
	s_and_b64 vcc, exec, s[0:1]
	buffer_load_dwordx4 v235, s[12:15], s3 offen lds
	s_add_i32 s3, s34, 0x40100
	s_mov_b32 m0, s31
	s_nop 0
	buffer_load_dwordx4 v233, s[12:15], s3 offen lds
	s_mov_b32 m0, s35
	s_nop 0
	buffer_load_dwordx4 v235, s[12:15], s3 offen lds
	s_mov_b32 m0, s28
	s_nop 0
	buffer_load_dwordx4 v1, s[12:15], s2 offen lds
	s_mov_b32 m0, s38
	s_nop 0
	buffer_load_dwordx4 v234, s[12:15], s2 offen lds
	s_mov_b64 s[2:3], -1
	s_cbranch_vccz .LBB0_824
	s_waitcnt vmcnt(8)
	s_mov_b64 s[2:3], 0

.LBB0_826:
	s_waitcnt lgkmcnt(0)
	s_barrier
	s_waitcnt lgkmcnt(7)
	v_mfma_f32_16x16x32_bf16 v[10:13], v[190:193], v[202:205], 0
	v_mfma_f32_16x16x32_bf16 v[6:9], v[182:185], v[202:205], 0
	s_waitcnt lgkmcnt(6)
	v_mfma_f32_16x16x32_bf16 v[2:5], v[190:193], v[194:197], 0
	v_mfma_f32_16x16x32_bf16 v[18:21], v[182:185], v[194:197], 0
	s_waitcnt lgkmcnt(3)
	v_mfma_f32_16x16x32_bf16 v[14:17], v[190:193], v[154:157], 0
	v_mfma_f32_16x16x32_bf16 v[26:29], v[182:185], v[154:157], 0
	s_waitcnt lgkmcnt(2)
	v_mfma_f32_16x16x32_bf16 v[22:25], v[190:193], v[146:149], 0
	v_mfma_f32_16x16x32_bf16 v[38:41], v[182:185], v[146:149], 0
	v_mfma_f32_16x16x32_bf16 v[10:13], v[186:189], v[206:209], v[10:13]
	v_mfma_f32_16x16x32_bf16 v[6:9], v[178:181], v[206:209], v[6:9]
	v_mfma_f32_16x16x32_bf16 v[2:5], v[186:189], v[198:201], v[2:5]
	v_mfma_f32_16x16x32_bf16 v[18:21], v[178:181], v[198:201], v[18:21]
	s_waitcnt lgkmcnt(1)
	v_mfma_f32_16x16x32_bf16 v[14:17], v[186:189], v[158:161], v[14:17]
	v_mfma_f32_16x16x32_bf16 v[26:29], v[178:181], v[158:161], v[26:29]
	s_waitcnt lgkmcnt(0)
	v_mfma_f32_16x16x32_bf16 v[22:25], v[186:189], v[150:153], v[22:25]
	v_mfma_f32_16x16x32_bf16 v[38:41], v[178:181], v[150:153], v[38:41]
	v_mfma_f32_16x16x32_bf16 v[34:37], v[174:177], v[202:205], 0
	v_mfma_f32_16x16x32_bf16 v[30:33], v[142:145], v[202:205], 0
	v_mfma_f32_16x16x32_bf16 v[42:45], v[174:177], v[194:197], 0
	v_mfma_f32_16x16x32_bf16 v[46:49], v[142:145], v[194:197], 0
	v_mfma_f32_16x16x32_bf16 v[50:53], v[174:177], v[154:157], 0
	v_mfma_f32_16x16x32_bf16 v[54:57], v[142:145], v[154:157], 0
	v_mfma_f32_16x16x32_bf16 v[58:61], v[174:177], v[146:149], 0
	v_mfma_f32_16x16x32_bf16 v[62:65], v[142:145], v[146:149], 0
	s_nop 0
	v_mfma_f32_16x16x32_bf16 v[34:37], v[170:173], v[206:209], v[34:37]
	v_mfma_f32_16x16x32_bf16 v[30:33], v[134:137], v[206:209], v[30:33]
	v_mfma_f32_16x16x32_bf16 v[42:45], v[170:173], v[198:201], v[42:45]
	v_mfma_f32_16x16x32_bf16 v[46:49], v[134:137], v[198:201], v[46:49]
	v_mfma_f32_16x16x32_bf16 v[50:53], v[170:173], v[158:161], v[50:53]
	v_mfma_f32_16x16x32_bf16 v[54:57], v[134:137], v[158:161], v[54:57]
	v_mfma_f32_16x16x32_bf16 v[58:61], v[170:173], v[150:153], v[58:61]
	v_mfma_f32_16x16x32_bf16 v[62:65], v[134:137], v[150:153], v[62:65]
	s_barrier
	v_add_u32_e32 v194, s58, v238
	v_add_u32_e32 v196, s56, v238
	v_add_u32_e32 v198, s59, v238
	v_add_u32_e32 v200, s57, v238
	v_add_u32_e32 v195, s58, v239
	ds_read_b128 v[146:149], v194
	ds_read_b128 v[150:153], v195
	v_add_u32_e32 v197, s56, v239
	ds_read_b128 v[154:157], v196
	ds_read_b128 v[158:161], v197
	v_add_u32_e32 v199, s59, v239
	ds_read_b128 v[130:133], v198
	ds_read_b128 v[134:137], v199
	v_add_u32_e32 v201, s57, v239
	ds_read_b128 v[138:141], v200
	ds_read_b128 v[142:145], v201
	s_mov_b32 m0, s39
	s_add_i32 s2, s42, 0x40100
	s_mov_b32 s8, s70
	ds_read_b128 v[186:189], v248 offset:32768
	ds_read_b128 v[174:177], v248 offset:34816
	ds_read_b128 v[190:193], v249 offset:32768
	ds_read_b128 v[178:181], v249 offset:34816
	ds_read_b128 v[170:173], v248 offset:36864
	ds_read_b128 v[162:165], v248 offset:38912
	ds_read_b128 v[182:185], v249 offset:36864
	ds_read_b128 v[166:169], v249 offset:38912
	buffer_load_dwordx4 v1, s[8:11], s2 offen lds
	s_mov_b32 m0, s41
	s_and_b64 vcc, exec, s[0:1]
	buffer_load_dwordx4 v234, s[8:11], s2 offen lds
	s_mov_b64 s[2:3], -1
	s_cbranch_vccz .LBB0_828
	s_waitcnt vmcnt(8)
	s_mov_b64 s[2:3], 0

.LBB0_830:
	s_waitcnt lgkmcnt(0)
	s_add_i32 s2, s42, 0x180
	s_add_i32 s3, s34, 0x180
	s_barrier
	s_waitcnt lgkmcnt(7)
	v_mfma_f32_16x16x32_bf16 v[74:77], v[146:149], v[186:189], v[74:77]
	v_mfma_f32_16x16x32_bf16 v[70:73], v[154:157], v[186:189], v[70:73]
	s_waitcnt lgkmcnt(6)
	v_mfma_f32_16x16x32_bf16 v[66:69], v[146:149], v[174:177], v[66:69]
	v_mfma_f32_16x16x32_bf16 v[82:85], v[154:157], v[174:177], v[82:85]
	s_waitcnt lgkmcnt(3)
	v_mfma_f32_16x16x32_bf16 v[78:81], v[146:149], v[170:173], v[78:81]
	v_mfma_f32_16x16x32_bf16 v[90:93], v[154:157], v[170:173], v[90:93]
	s_waitcnt lgkmcnt(2)
	v_mfma_f32_16x16x32_bf16 v[86:89], v[146:149], v[162:165], v[86:89]
	v_mfma_f32_16x16x32_bf16 v[102:105], v[154:157], v[162:165], v[102:105]
	v_mfma_f32_16x16x32_bf16 v[74:77], v[150:153], v[190:193], v[74:77]
	v_mfma_f32_16x16x32_bf16 v[70:73], v[158:161], v[190:193], v[70:73]
	v_mfma_f32_16x16x32_bf16 v[66:69], v[150:153], v[178:181], v[66:69]
	v_mfma_f32_16x16x32_bf16 v[82:85], v[158:161], v[178:181], v[82:85]
	s_waitcnt lgkmcnt(1)
	v_mfma_f32_16x16x32_bf16 v[78:81], v[150:153], v[182:185], v[78:81]
	v_mfma_f32_16x16x32_bf16 v[90:93], v[158:161], v[182:185], v[90:93]
	s_waitcnt lgkmcnt(0)
	v_mfma_f32_16x16x32_bf16 v[86:89], v[150:153], v[166:169], v[86:89]
	v_mfma_f32_16x16x32_bf16 v[102:105], v[158:161], v[166:169], v[102:105]
	v_mfma_f32_16x16x32_bf16 v[98:101], v[130:133], v[186:189], v[98:101]
	v_mfma_f32_16x16x32_bf16 v[94:97], v[138:141], v[186:189], v[94:97]
	v_mfma_f32_16x16x32_bf16 v[106:109], v[130:133], v[174:177], v[106:109]
	v_mfma_f32_16x16x32_bf16 v[110:113], v[138:141], v[174:177], v[110:113]
	v_mfma_f32_16x16x32_bf16 v[114:117], v[130:133], v[170:173], v[114:117]
	v_mfma_f32_16x16x32_bf16 v[118:121], v[138:141], v[170:173], v[118:121]
	v_mfma_f32_16x16x32_bf16 v[122:125], v[130:133], v[162:165], v[122:125]
	v_mfma_f32_16x16x32_bf16 v[126:129], v[138:141], v[162:165], v[126:129]
	v_mfma_f32_16x16x32_bf16 v[98:101], v[134:137], v[190:193], v[98:101]
	v_mfma_f32_16x16x32_bf16 v[94:97], v[142:145], v[190:193], v[94:97]
	v_mfma_f32_16x16x32_bf16 v[106:109], v[134:137], v[178:181], v[106:109]
	v_mfma_f32_16x16x32_bf16 v[110:113], v[142:145], v[178:181], v[110:113]
	v_mfma_f32_16x16x32_bf16 v[114:117], v[134:137], v[182:185], v[114:117]
	v_mfma_f32_16x16x32_bf16 v[118:121], v[142:145], v[182:185], v[118:121]
	v_mfma_f32_16x16x32_bf16 v[122:125], v[134:137], v[166:169], v[122:125]
	v_mfma_f32_16x16x32_bf16 v[126:129], v[142:145], v[166:169], v[126:129]
	s_barrier
	s_mov_b32 m0, s44
	s_mov_b32 s8, s70
	ds_read_b128 v[186:189], v248 offset:49152
	ds_read_b128 v[174:177], v248 offset:51200
	ds_read_b128 v[190:193], v249 offset:49152
	ds_read_b128 v[178:181], v249 offset:51200
	ds_read_b128 v[170:173], v248 offset:53248
	ds_read_b128 v[162:165], v248 offset:55296
	ds_read_b128 v[182:185], v249 offset:53248
	ds_read_b128 v[166:169], v249 offset:55296
	buffer_load_dwordx4 v233, s[8:11], s3 offen lds
	s_mov_b32 m0, s45
	s_and_b64 vcc, exec, s[0:1]
	buffer_load_dwordx4 v235, s[8:11], s3 offen lds
	s_add_i32 s3, s34, 0x40180
	s_mov_b32 m0, s48
	s_nop 0
	buffer_load_dwordx4 v233, s[8:11], s3 offen lds
	s_mov_b32 m0, s49
	s_nop 0
	buffer_load_dwordx4 v235, s[8:11], s3 offen lds
	s_mov_b32 m0, s46
	s_nop 0
	buffer_load_dwordx4 v1, s[8:11], s2 offen lds
	s_mov_b32 m0, s47
	s_nop 0
	buffer_load_dwordx4 v234, s[8:11], s2 offen lds
	s_mov_b64 s[2:3], -1
	s_cbranch_vccz .LBB0_832
	s_waitcnt vmcnt(8)
	s_mov_b64 s[2:3], 0

.LBB0_834:
	s_waitcnt lgkmcnt(0)
	s_barrier
	s_waitcnt lgkmcnt(7)
	v_mfma_f32_16x16x32_bf16 v[10:13], v[146:149], v[186:189], v[10:13]
	v_mfma_f32_16x16x32_bf16 v[6:9], v[154:157], v[186:189], v[6:9]
	s_waitcnt lgkmcnt(6)
	v_mfma_f32_16x16x32_bf16 v[2:5], v[146:149], v[174:177], v[2:5]
	v_mfma_f32_16x16x32_bf16 v[18:21], v[154:157], v[174:177], v[18:21]
	s_waitcnt lgkmcnt(3)
	v_mfma_f32_16x16x32_bf16 v[14:17], v[146:149], v[170:173], v[14:17]
	v_mfma_f32_16x16x32_bf16 v[26:29], v[154:157], v[170:173], v[26:29]
	s_waitcnt lgkmcnt(2)
	v_mfma_f32_16x16x32_bf16 v[22:25], v[146:149], v[162:165], v[22:25]
	v_mfma_f32_16x16x32_bf16 v[38:41], v[154:157], v[162:165], v[38:41]
	v_mfma_f32_16x16x32_bf16 v[10:13], v[150:153], v[190:193], v[10:13]
	v_mfma_f32_16x16x32_bf16 v[6:9], v[158:161], v[190:193], v[6:9]
	v_mfma_f32_16x16x32_bf16 v[2:5], v[150:153], v[178:181], v[2:5]
	v_mfma_f32_16x16x32_bf16 v[18:21], v[158:161], v[178:181], v[18:21]
	s_waitcnt lgkmcnt(1)
	v_mfma_f32_16x16x32_bf16 v[14:17], v[150:153], v[182:185], v[14:17]
	v_mfma_f32_16x16x32_bf16 v[26:29], v[158:161], v[182:185], v[26:29]
	s_waitcnt lgkmcnt(0)
	v_mfma_f32_16x16x32_bf16 v[22:25], v[150:153], v[166:169], v[22:25]
	v_mfma_f32_16x16x32_bf16 v[38:41], v[158:161], v[166:169], v[38:41]
	v_mfma_f32_16x16x32_bf16 v[34:37], v[130:133], v[186:189], v[34:37]
	v_mfma_f32_16x16x32_bf16 v[30:33], v[138:141], v[186:189], v[30:33]
	v_mfma_f32_16x16x32_bf16 v[42:45], v[130:133], v[174:177], v[42:45]
	v_mfma_f32_16x16x32_bf16 v[46:49], v[138:141], v[174:177], v[46:49]
	v_mfma_f32_16x16x32_bf16 v[50:53], v[130:133], v[170:173], v[50:53]
	v_mfma_f32_16x16x32_bf16 v[54:57], v[138:141], v[170:173], v[54:57]
	v_mfma_f32_16x16x32_bf16 v[58:61], v[130:133], v[162:165], v[58:61]
	v_mfma_f32_16x16x32_bf16 v[62:65], v[138:141], v[162:165], v[62:65]
	v_mfma_f32_16x16x32_bf16 v[34:37], v[134:137], v[190:193], v[34:37]
	v_mfma_f32_16x16x32_bf16 v[30:33], v[142:145], v[190:193], v[30:33]
	v_mfma_f32_16x16x32_bf16 v[42:45], v[134:137], v[178:181], v[42:45]
	v_mfma_f32_16x16x32_bf16 v[46:49], v[142:145], v[178:181], v[46:49]
	v_mfma_f32_16x16x32_bf16 v[50:53], v[134:137], v[182:185], v[50:53]
	v_mfma_f32_16x16x32_bf16 v[54:57], v[142:145], v[182:185], v[54:57]
	v_mfma_f32_16x16x32_bf16 v[58:61], v[134:137], v[166:169], v[58:61]
	v_mfma_f32_16x16x32_bf16 v[62:65], v[142:145], v[166:169], v[62:65]
	s_barrier
	s_add_i32 s62, s43, 1
	s_mul_i32 s0, s62, s94
	s_mul_hi_i32 s1, s62, s94
	s_add_u32 s0, s0, s95
	s_addc_u32 s1, s1, s40
	v_cmp_gt_i64_e64 s[2:3], s[0:1], v[226:227]
	s_and_b64 vcc, exec, s[2:3]
	s_cbranch_vccnz .LBB0_840
	s_ashr_i32 s4, s0, 31
	s_lshr_b32 s4, s4, 29
	s_add_i32 s8, s0, s4
	s_and_b32 s4, s8, -8
	s_sub_i32 s18, s0, s4
	s_cmp_gt_i32 s18, -1
	s_mov_b64 s[4:5], -1
	s_cbranch_scc0 .LBB0_837
	s_lshl_b32 s19, s18, 7
	s_mov_b64 s[4:5], 0

.LBB0_841:
	ds_read_b128 v[130:133], v240
	ds_read_b128 v[134:137], v241
	ds_read_b128 v[138:141], v242
	ds_read_b128 v[142:145], v243
	ds_read_b128 v[146:149], v244
	ds_read_b128 v[150:153], v245
	ds_read_b128 v[154:157], v246
	ds_read_b128 v[158:161], v247
	s_add_i32 s8, s42, s5
	s_add_i32 s19, s34, s5
	s_add_i32 s18, s8, 0x800
	s_addk_i32 s19, 0x800
	s_cmp_eq_u32 s5, 0
	s_cselect_b32 s20, s0, s18
	s_cselect_b32 s19, s1, s19
	s_add_i32 s18, s20, 0x80
	s_add_i32 s21, s8, 0x40780
	s_mov_b32 s8, s70
	s_mov_b32 m0, s52
	ds_read_b128 v[162:165], v248
	ds_read_b128 v[166:169], v248 offset:2048
	ds_read_b128 v[170:173], v249
	ds_read_b128 v[174:177], v249 offset:2048
	ds_read_b128 v[178:181], v248 offset:4096
	ds_read_b128 v[182:185], v248 offset:6144
	ds_read_b128 v[186:189], v249 offset:4096
	ds_read_b128 v[190:193], v249 offset:6144
	buffer_load_dwordx4 v1, s[8:11], s21 offen lds
	s_mov_b32 m0, s53
	s_nop 0
	buffer_load_dwordx4 v234, s[8:11], s21 offen lds
	s_waitcnt vmcnt(8)
	s_waitcnt lgkmcnt(0)
	s_barrier
	s_waitcnt lgkmcnt(7)
	v_mfma_f32_16x16x32_bf16 v[74:77], v[130:133], v[162:165], v[74:77]
	v_mfma_f32_16x16x32_bf16 v[70:73], v[138:141], v[162:165], v[70:73]
	s_waitcnt lgkmcnt(6)
	v_mfma_f32_16x16x32_bf16 v[66:69], v[130:133], v[166:169], v[66:69]
	v_mfma_f32_16x16x32_bf16 v[82:85], v[138:141], v[166:169], v[82:85]
	s_waitcnt lgkmcnt(3)
	v_mfma_f32_16x16x32_bf16 v[78:81], v[130:133], v[178:181], v[78:81]
	v_mfma_f32_16x16x32_bf16 v[90:93], v[138:141], v[178:181], v[90:93]
	s_waitcnt lgkmcnt(2)
	v_mfma_f32_16x16x32_bf16 v[86:89], v[130:133], v[182:185], v[86:89]
	v_mfma_f32_16x16x32_bf16 v[102:105], v[138:141], v[182:185], v[102:105]
	v_mfma_f32_16x16x32_bf16 v[74:77], v[134:137], v[170:173], v[74:77]
	v_mfma_f32_16x16x32_bf16 v[70:73], v[142:145], v[170:173], v[70:73]
	v_mfma_f32_16x16x32_bf16 v[66:69], v[134:137], v[174:177], v[66:69]
	v_mfma_f32_16x16x32_bf16 v[82:85], v[142:145], v[174:177], v[82:85]
	s_waitcnt lgkmcnt(1)
	v_mfma_f32_16x16x32_bf16 v[78:81], v[134:137], v[186:189], v[78:81]
	v_mfma_f32_16x16x32_bf16 v[90:93], v[142:145], v[186:189], v[90:93]
	s_waitcnt lgkmcnt(0)
	v_mfma_f32_16x16x32_bf16 v[86:89], v[134:137], v[190:193], v[86:89]
	v_mfma_f32_16x16x32_bf16 v[102:105], v[142:145], v[190:193], v[102:105]
	v_mfma_f32_16x16x32_bf16 v[98:101], v[146:149], v[162:165], v[98:101]
	v_mfma_f32_16x16x32_bf16 v[94:97], v[154:157], v[162:165], v[94:97]
	v_mfma_f32_16x16x32_bf16 v[106:109], v[146:149], v[166:169], v[106:109]
	v_mfma_f32_16x16x32_bf16 v[110:113], v[154:157], v[166:169], v[110:113]
	v_mfma_f32_16x16x32_bf16 v[114:117], v[146:149], v[178:181], v[114:117]
	v_mfma_f32_16x16x32_bf16 v[118:121], v[154:157], v[178:181], v[118:121]
	v_mfma_f32_16x16x32_bf16 v[122:125], v[146:149], v[182:185], v[122:125]
	v_mfma_f32_16x16x32_bf16 v[126:129], v[154:157], v[182:185], v[126:129]
	v_mfma_f32_16x16x32_bf16 v[98:101], v[150:153], v[170:173], v[98:101]
	v_mfma_f32_16x16x32_bf16 v[94:97], v[158:161], v[170:173], v[94:97]
	v_mfma_f32_16x16x32_bf16 v[106:109], v[150:153], v[174:177], v[106:109]
	v_mfma_f32_16x16x32_bf16 v[110:113], v[158:161], v[174:177], v[110:113]
	v_mfma_f32_16x16x32_bf16 v[114:117], v[150:153], v[186:189], v[114:117]
	v_mfma_f32_16x16x32_bf16 v[118:121], v[158:161], v[186:189], v[118:121]
	v_mfma_f32_16x16x32_bf16 v[122:125], v[150:153], v[190:193], v[122:125]
	v_mfma_f32_16x16x32_bf16 v[126:129], v[158:161], v[190:193], v[126:129]
	s_barrier
	s_mov_b32 m0, s29
	ds_read_b128 v[162:165], v248 offset:16384
	ds_read_b128 v[166:169], v248 offset:18432
	ds_read_b128 v[170:173], v249 offset:16384
	ds_read_b128 v[174:177], v249 offset:18432
	ds_read_b128 v[178:181], v248 offset:20480
	ds_read_b128 v[182:185], v248 offset:22528
	ds_read_b128 v[186:189], v249 offset:20480
	ds_read_b128 v[190:193], v249 offset:22528
	buffer_load_dwordx4 v233, s[8:11], s19 offen lds
	s_mov_b32 m0, s30
	s_add_i32 s21, s19, 0x40000
	buffer_load_dwordx4 v235, s[8:11], s19 offen lds
	s_mov_b32 m0, s31
	s_nop 0
	buffer_load_dwordx4 v233, s[8:11], s21 offen lds
	s_mov_b32 m0, s35
	s_nop 0
	buffer_load_dwordx4 v235, s[8:11], s21 offen lds
	s_mov_b32 m0, s28
	s_nop 0
	buffer_load_dwordx4 v1, s[8:11], s20 offen lds
	s_mov_b32 m0, s38
	s_nop 0
	buffer_load_dwordx4 v234, s[8:11], s20 offen lds
	s_waitcnt vmcnt(8)
	s_waitcnt lgkmcnt(0)
	s_barrier
	s_waitcnt lgkmcnt(7)
	v_mfma_f32_16x16x32_bf16 v[10:13], v[130:133], v[162:165], v[10:13]
	v_mfma_f32_16x16x32_bf16 v[6:9], v[138:141], v[162:165], v[6:9]
	s_waitcnt lgkmcnt(6)
	v_mfma_f32_16x16x32_bf16 v[2:5], v[130:133], v[166:169], v[2:5]
	v_mfma_f32_16x16x32_bf16 v[18:21], v[138:141], v[166:169], v[18:21]
	s_waitcnt lgkmcnt(3)
	v_mfma_f32_16x16x32_bf16 v[14:17], v[130:133], v[178:181], v[14:17]
	v_mfma_f32_16x16x32_bf16 v[26:29], v[138:141], v[178:181], v[26:29]
	s_waitcnt lgkmcnt(2)
	v_mfma_f32_16x16x32_bf16 v[22:25], v[130:133], v[182:185], v[22:25]
	v_mfma_f32_16x16x32_bf16 v[38:41], v[138:141], v[182:185], v[38:41]
	v_mfma_f32_16x16x32_bf16 v[10:13], v[134:137], v[170:173], v[10:13]
	v_mfma_f32_16x16x32_bf16 v[6:9], v[142:145], v[170:173], v[6:9]
	v_mfma_f32_16x16x32_bf16 v[2:5], v[134:137], v[174:177], v[2:5]
	v_mfma_f32_16x16x32_bf16 v[18:21], v[142:145], v[174:177], v[18:21]
	s_waitcnt lgkmcnt(1)
	v_mfma_f32_16x16x32_bf16 v[14:17], v[134:137], v[186:189], v[14:17]
	v_mfma_f32_16x16x32_bf16 v[26:29], v[142:145], v[186:189], v[26:29]
	s_waitcnt lgkmcnt(0)
	v_mfma_f32_16x16x32_bf16 v[22:25], v[134:137], v[190:193], v[22:25]
	v_mfma_f32_16x16x32_bf16 v[38:41], v[142:145], v[190:193], v[38:41]
	v_mfma_f32_16x16x32_bf16 v[34:37], v[146:149], v[162:165], v[34:37]
	v_mfma_f32_16x16x32_bf16 v[30:33], v[154:157], v[162:165], v[30:33]
	v_mfma_f32_16x16x32_bf16 v[42:45], v[146:149], v[166:169], v[42:45]
	v_mfma_f32_16x16x32_bf16 v[46:49], v[154:157], v[166:169], v[46:49]
	v_mfma_f32_16x16x32_bf16 v[50:53], v[146:149], v[178:181], v[50:53]
	v_mfma_f32_16x16x32_bf16 v[54:57], v[154:157], v[178:181], v[54:57]
	v_mfma_f32_16x16x32_bf16 v[58:61], v[146:149], v[182:185], v[58:61]
	v_mfma_f32_16x16x32_bf16 v[62:65], v[154:157], v[182:185], v[62:65]
	v_mfma_f32_16x16x32_bf16 v[34:37], v[150:153], v[170:173], v[34:37]
	v_mfma_f32_16x16x32_bf16 v[30:33], v[158:161], v[170:173], v[30:33]
	v_mfma_f32_16x16x32_bf16 v[42:45], v[150:153], v[174:177], v[42:45]
	v_mfma_f32_16x16x32_bf16 v[46:49], v[158:161], v[174:177], v[46:49]
	v_mfma_f32_16x16x32_bf16 v[50:53], v[150:153], v[186:189], v[50:53]
	v_mfma_f32_16x16x32_bf16 v[54:57], v[158:161], v[186:189], v[54:57]
	v_mfma_f32_16x16x32_bf16 v[58:61], v[150:153], v[190:193], v[58:61]
	v_mfma_f32_16x16x32_bf16 v[62:65], v[158:161], v[190:193], v[62:65]
	s_barrier
	ds_read_b128 v[130:133], v194
	ds_read_b128 v[134:137], v195
	ds_read_b128 v[138:141], v196
	ds_read_b128 v[142:145], v197
	ds_read_b128 v[146:149], v198
	ds_read_b128 v[150:153], v199
	ds_read_b128 v[154:157], v200
	ds_read_b128 v[158:161], v201
	s_add_i32 s20, s20, 0x40000
	s_mov_b32 m0, s39
	ds_read_b128 v[162:165], v248 offset:32768
	ds_read_b128 v[166:169], v248 offset:34816
	ds_read_b128 v[170:173], v249 offset:32768
	ds_read_b128 v[174:177], v249 offset:34816
	ds_read_b128 v[178:181], v248 offset:36864
	ds_read_b128 v[182:185], v248 offset:38912
	ds_read_b128 v[186:189], v249 offset:36864
	ds_read_b128 v[190:193], v249 offset:38912
	buffer_load_dwordx4 v1, s[8:11], s20 offen lds
	s_mov_b32 m0, s41
	s_nop 0
	buffer_load_dwordx4 v234, s[8:11], s20 offen lds
	s_waitcnt vmcnt(8)
	s_waitcnt lgkmcnt(0)
	s_barrier
	s_waitcnt lgkmcnt(7)
	v_mfma_f32_16x16x32_bf16 v[74:77], v[130:133], v[162:165], v[74:77]
	v_mfma_f32_16x16x32_bf16 v[70:73], v[138:141], v[162:165], v[70:73]
	s_waitcnt lgkmcnt(6)
	v_mfma_f32_16x16x32_bf16 v[66:69], v[130:133], v[166:169], v[66:69]
	v_mfma_f32_16x16x32_bf16 v[82:85], v[138:141], v[166:169], v[82:85]
	s_waitcnt lgkmcnt(3)
	v_mfma_f32_16x16x32_bf16 v[78:81], v[130:133], v[178:181], v[78:81]
	v_mfma_f32_16x16x32_bf16 v[90:93], v[138:141], v[178:181], v[90:93]
	s_waitcnt lgkmcnt(2)
	v_mfma_f32_16x16x32_bf16 v[86:89], v[130:133], v[182:185], v[86:89]
	v_mfma_f32_16x16x32_bf16 v[102:105], v[138:141], v[182:185], v[102:105]
	v_mfma_f32_16x16x32_bf16 v[74:77], v[134:137], v[170:173], v[74:77]
	v_mfma_f32_16x16x32_bf16 v[70:73], v[142:145], v[170:173], v[70:73]
	v_mfma_f32_16x16x32_bf16 v[66:69], v[134:137], v[174:177], v[66:69]
	v_mfma_f32_16x16x32_bf16 v[82:85], v[142:145], v[174:177], v[82:85]
	s_waitcnt lgkmcnt(1)
	v_mfma_f32_16x16x32_bf16 v[78:81], v[134:137], v[186:189], v[78:81]
	v_mfma_f32_16x16x32_bf16 v[90:93], v[142:145], v[186:189], v[90:93]
	s_waitcnt lgkmcnt(0)
	v_mfma_f32_16x16x32_bf16 v[86:89], v[134:137], v[190:193], v[86:89]
	v_mfma_f32_16x16x32_bf16 v[102:105], v[142:145], v[190:193], v[102:105]
	v_mfma_f32_16x16x32_bf16 v[98:101], v[146:149], v[162:165], v[98:101]
	v_mfma_f32_16x16x32_bf16 v[94:97], v[154:157], v[162:165], v[94:97]
	v_mfma_f32_16x16x32_bf16 v[106:109], v[146:149], v[166:169], v[106:109]
	v_mfma_f32_16x16x32_bf16 v[110:113], v[154:157], v[166:169], v[110:113]
	v_mfma_f32_16x16x32_bf16 v[114:117], v[146:149], v[178:181], v[114:117]
	v_mfma_f32_16x16x32_bf16 v[118:121], v[154:157], v[178:181], v[118:121]
	v_mfma_f32_16x16x32_bf16 v[122:125], v[146:149], v[182:185], v[122:125]
	v_mfma_f32_16x16x32_bf16 v[126:129], v[154:157], v[182:185], v[126:129]
	v_mfma_f32_16x16x32_bf16 v[98:101], v[150:153], v[170:173], v[98:101]
	v_mfma_f32_16x16x32_bf16 v[94:97], v[158:161], v[170:173], v[94:97]
	v_mfma_f32_16x16x32_bf16 v[106:109], v[150:153], v[174:177], v[106:109]
	v_mfma_f32_16x16x32_bf16 v[110:113], v[158:161], v[174:177], v[110:113]
	v_mfma_f32_16x16x32_bf16 v[114:117], v[150:153], v[186:189], v[114:117]
	v_mfma_f32_16x16x32_bf16 v[118:121], v[158:161], v[186:189], v[118:121]
	v_mfma_f32_16x16x32_bf16 v[122:125], v[150:153], v[190:193], v[122:125]
	v_mfma_f32_16x16x32_bf16 v[126:129], v[158:161], v[190:193], v[126:129]
	s_barrier
	s_mov_b32 m0, s44
	s_add_i32 s20, s19, 0x80
	ds_read_b128 v[162:165], v248 offset:49152
	ds_read_b128 v[166:169], v248 offset:51200
	ds_read_b128 v[170:173], v249 offset:49152
	ds_read_b128 v[174:177], v249 offset:51200
	ds_read_b128 v[178:181], v248 offset:53248
	ds_read_b128 v[182:185], v248 offset:55296
	ds_read_b128 v[186:189], v249 offset:53248
	ds_read_b128 v[190:193], v249 offset:55296
	buffer_load_dwordx4 v233, s[8:11], s20 offen lds
	s_mov_b32 m0, s45
	s_add_i32 s19, s19, 0x40080
	buffer_load_dwordx4 v235, s[8:11], s20 offen lds
	s_mov_b32 m0, s48
	s_nop 0
	buffer_load_dwordx4 v233, s[8:11], s19 offen lds
	s_mov_b32 m0, s49
	s_nop 0
	buffer_load_dwordx4 v235, s[8:11], s19 offen lds
	s_mov_b32 m0, s46
	s_nop 0
	buffer_load_dwordx4 v1, s[8:11], s18 offen lds
	s_mov_b32 m0, s47
	s_nop 0
	buffer_load_dwordx4 v234, s[8:11], s18 offen lds
	s_waitcnt vmcnt(8)
	s_waitcnt lgkmcnt(0)
	s_barrier
	s_waitcnt lgkmcnt(7)
	v_mfma_f32_16x16x32_bf16 v[10:13], v[130:133], v[162:165], v[10:13]
	v_mfma_f32_16x16x32_bf16 v[6:9], v[138:141], v[162:165], v[6:9]
	s_waitcnt lgkmcnt(6)
	v_mfma_f32_16x16x32_bf16 v[2:5], v[130:133], v[166:169], v[2:5]
	v_mfma_f32_16x16x32_bf16 v[18:21], v[138:141], v[166:169], v[18:21]
	s_waitcnt lgkmcnt(3)
	v_mfma_f32_16x16x32_bf16 v[14:17], v[130:133], v[178:181], v[14:17]
	v_mfma_f32_16x16x32_bf16 v[26:29], v[138:141], v[178:181], v[26:29]
	s_waitcnt lgkmcnt(2)
	v_mfma_f32_16x16x32_bf16 v[22:25], v[130:133], v[182:185], v[22:25]
	v_mfma_f32_16x16x32_bf16 v[38:41], v[138:141], v[182:185], v[38:41]
	v_mfma_f32_16x16x32_bf16 v[10:13], v[134:137], v[170:173], v[10:13]
	v_mfma_f32_16x16x32_bf16 v[6:9], v[142:145], v[170:173], v[6:9]
	v_mfma_f32_16x16x32_bf16 v[2:5], v[134:137], v[174:177], v[2:5]
	v_mfma_f32_16x16x32_bf16 v[18:21], v[142:145], v[174:177], v[18:21]
	s_waitcnt lgkmcnt(1)
	v_mfma_f32_16x16x32_bf16 v[14:17], v[134:137], v[186:189], v[14:17]
	v_mfma_f32_16x16x32_bf16 v[26:29], v[142:145], v[186:189], v[26:29]
	s_waitcnt lgkmcnt(0)
	v_mfma_f32_16x16x32_bf16 v[22:25], v[134:137], v[190:193], v[22:25]
	v_mfma_f32_16x16x32_bf16 v[38:41], v[142:145], v[190:193], v[38:41]
	v_mfma_f32_16x16x32_bf16 v[34:37], v[146:149], v[162:165], v[34:37]
	v_mfma_f32_16x16x32_bf16 v[30:33], v[154:157], v[162:165], v[30:33]
	v_mfma_f32_16x16x32_bf16 v[42:45], v[146:149], v[166:169], v[42:45]
	v_mfma_f32_16x16x32_bf16 v[46:49], v[154:157], v[166:169], v[46:49]
	v_mfma_f32_16x16x32_bf16 v[50:53], v[146:149], v[178:181], v[50:53]
	v_mfma_f32_16x16x32_bf16 v[54:57], v[154:157], v[178:181], v[54:57]
	v_mfma_f32_16x16x32_bf16 v[58:61], v[146:149], v[182:185], v[58:61]
	v_mfma_f32_16x16x32_bf16 v[62:65], v[154:157], v[182:185], v[62:65]
	v_mfma_f32_16x16x32_bf16 v[34:37], v[150:153], v[170:173], v[34:37]
	v_mfma_f32_16x16x32_bf16 v[30:33], v[158:161], v[170:173], v[30:33]
	v_mfma_f32_16x16x32_bf16 v[42:45], v[150:153], v[174:177], v[42:45]
	v_mfma_f32_16x16x32_bf16 v[46:49], v[158:161], v[174:177], v[46:49]
	v_mfma_f32_16x16x32_bf16 v[50:53], v[150:153], v[186:189], v[50:53]
	v_mfma_f32_16x16x32_bf16 v[54:57], v[158:161], v[186:189], v[54:57]
	v_mfma_f32_16x16x32_bf16 v[58:61], v[150:153], v[190:193], v[58:61]
	v_mfma_f32_16x16x32_bf16 v[62:65], v[158:161], v[190:193], v[62:65]
	s_barrier
	s_add_i32 s4, s4, 2
	s_addk_i32 s5, 0x100
	s_cmp_gt_u32 s4, 13
	s_cbranch_scc0 .LBB0_841
	s_and_b64 vcc, exec, s[16:17]
	s_cbranch_vccz .LBB0_844
	s_barrier

.LBB0_1103:
	s_waitcnt lgkmcnt(0)
	s_add_i32 s4, s31, 0x100
	s_add_i32 s5, s26, 0x100
	s_barrier
	s_waitcnt lgkmcnt(7)
	v_mfma_f32_16x16x32_bf16 v[126:129], v[190:193], v[218:221], 0
	v_mfma_f32_16x16x32_bf16 v[122:125], v[182:185], v[218:221], 0
	s_waitcnt lgkmcnt(6)
	v_mfma_f32_16x16x32_bf16 v[118:121], v[190:193], v[210:213], 0
	v_mfma_f32_16x16x32_bf16 v[114:117], v[182:185], v[210:213], 0
	s_waitcnt lgkmcnt(3)
	v_mfma_f32_16x16x32_bf16 v[110:113], v[190:193], v[202:205], 0
	v_mfma_f32_16x16x32_bf16 v[106:109], v[182:185], v[202:205], 0
	s_waitcnt lgkmcnt(2)
	v_mfma_f32_16x16x32_bf16 v[102:105], v[190:193], v[194:197], 0
	v_mfma_f32_16x16x32_bf16 v[98:101], v[182:185], v[194:197], 0
	v_mfma_f32_16x16x32_bf16 v[126:129], v[186:189], v[222:225], v[126:129]
	v_mfma_f32_16x16x32_bf16 v[122:125], v[178:181], v[222:225], v[122:125]
	v_mfma_f32_16x16x32_bf16 v[118:121], v[186:189], v[214:217], v[118:121]
	v_mfma_f32_16x16x32_bf16 v[114:117], v[178:181], v[214:217], v[114:117]
	s_waitcnt lgkmcnt(1)
	v_mfma_f32_16x16x32_bf16 v[110:113], v[186:189], v[206:209], v[110:113]
	v_mfma_f32_16x16x32_bf16 v[106:109], v[178:181], v[206:209], v[106:109]
	s_waitcnt lgkmcnt(0)
	v_mfma_f32_16x16x32_bf16 v[102:105], v[186:189], v[198:201], v[102:105]
	v_mfma_f32_16x16x32_bf16 v[98:101], v[178:181], v[198:201], v[98:101]
	v_mfma_f32_16x16x32_bf16 v[94:97], v[174:177], v[218:221], 0
	v_mfma_f32_16x16x32_bf16 v[90:93], v[166:169], v[218:221], 0
	v_mfma_f32_16x16x32_bf16 v[86:89], v[174:177], v[210:213], 0
	v_mfma_f32_16x16x32_bf16 v[82:85], v[166:169], v[210:213], 0
	v_mfma_f32_16x16x32_bf16 v[78:81], v[174:177], v[202:205], 0
	v_mfma_f32_16x16x32_bf16 v[74:77], v[166:169], v[202:205], 0
	v_mfma_f32_16x16x32_bf16 v[70:73], v[174:177], v[194:197], 0
	v_mfma_f32_16x16x32_bf16 v[66:69], v[166:169], v[194:197], 0
	s_nop 0
	v_mfma_f32_16x16x32_bf16 v[94:97], v[170:173], v[222:225], v[94:97]
	v_mfma_f32_16x16x32_bf16 v[90:93], v[162:165], v[222:225], v[90:93]
	v_mfma_f32_16x16x32_bf16 v[86:89], v[170:173], v[214:217], v[86:89]
	v_mfma_f32_16x16x32_bf16 v[82:85], v[162:165], v[214:217], v[82:85]
	v_mfma_f32_16x16x32_bf16 v[78:81], v[170:173], v[206:209], v[78:81]
	v_mfma_f32_16x16x32_bf16 v[74:77], v[162:165], v[206:209], v[74:77]
	v_mfma_f32_16x16x32_bf16 v[70:73], v[170:173], v[198:201], v[70:73]
	v_mfma_f32_16x16x32_bf16 v[66:69], v[162:165], v[198:201], v[66:69]
	s_barrier
	s_mov_b32 m0, s23
	ds_read_b128 v[202:205], v248 offset:16384
	ds_read_b128 v[194:197], v248 offset:18432
	ds_read_b128 v[206:209], v249 offset:16384
	ds_read_b128 v[198:201], v249 offset:18432
	ds_read_b128 v[146:149], v248 offset:20480
	ds_read_b128 v[130:133], v248 offset:22528
	ds_read_b128 v[154:157], v249 offset:20480
	ds_read_b128 v[138:141], v249 offset:22528
	buffer_load_dwordx4 v233, s[12:15], s5 offen lds
	s_mov_b32 m0, s24
	s_and_b64 vcc, exec, s[2:3]
	buffer_load_dwordx4 v235, s[12:15], s5 offen lds
	s_add_i32 s5, s26, 0x40100
	s_mov_b32 m0, s25
	s_nop 0
	buffer_load_dwordx4 v233, s[12:15], s5 offen lds
	s_mov_b32 m0, s27
	s_nop 0
	buffer_load_dwordx4 v235, s[12:15], s5 offen lds
	s_mov_b32 m0, s22
	s_nop 0
	buffer_load_dwordx4 v1, s[12:15], s4 offen lds
	s_mov_b32 m0, s28
	s_nop 0
	buffer_load_dwordx4 v234, s[12:15], s4 offen lds
	s_mov_b64 s[4:5], -1
	s_cbranch_vccz .LBB0_1105
	s_waitcnt vmcnt(8)
	s_mov_b64 s[4:5], 0

.LBB0_1107:
	s_waitcnt lgkmcnt(0)
	s_barrier
	s_waitcnt lgkmcnt(7)
	v_mfma_f32_16x16x32_bf16 v[62:65], v[190:193], v[202:205], 0
	v_mfma_f32_16x16x32_bf16 v[58:61], v[182:185], v[202:205], 0
	s_waitcnt lgkmcnt(6)
	v_mfma_f32_16x16x32_bf16 v[54:57], v[190:193], v[194:197], 0
	v_mfma_f32_16x16x32_bf16 v[50:53], v[182:185], v[194:197], 0
	s_waitcnt lgkmcnt(3)
	v_mfma_f32_16x16x32_bf16 v[46:49], v[190:193], v[146:149], 0
	v_mfma_f32_16x16x32_bf16 v[42:45], v[182:185], v[146:149], 0
	s_waitcnt lgkmcnt(2)
	v_mfma_f32_16x16x32_bf16 v[38:41], v[190:193], v[130:133], 0
	v_mfma_f32_16x16x32_bf16 v[34:37], v[182:185], v[130:133], 0
	v_mfma_f32_16x16x32_bf16 v[62:65], v[186:189], v[206:209], v[62:65]
	v_mfma_f32_16x16x32_bf16 v[58:61], v[178:181], v[206:209], v[58:61]
	v_mfma_f32_16x16x32_bf16 v[54:57], v[186:189], v[198:201], v[54:57]
	v_mfma_f32_16x16x32_bf16 v[50:53], v[178:181], v[198:201], v[50:53]
	s_waitcnt lgkmcnt(1)
	v_mfma_f32_16x16x32_bf16 v[46:49], v[186:189], v[154:157], v[46:49]
	v_mfma_f32_16x16x32_bf16 v[42:45], v[178:181], v[154:157], v[42:45]
	s_waitcnt lgkmcnt(0)
	v_mfma_f32_16x16x32_bf16 v[38:41], v[186:189], v[138:141], v[38:41]
	v_mfma_f32_16x16x32_bf16 v[34:37], v[178:181], v[138:141], v[34:37]
	v_mfma_f32_16x16x32_bf16 v[30:33], v[174:177], v[202:205], 0
	v_mfma_f32_16x16x32_bf16 v[26:29], v[166:169], v[202:205], 0
	v_mfma_f32_16x16x32_bf16 v[22:25], v[174:177], v[194:197], 0
	v_mfma_f32_16x16x32_bf16 v[18:21], v[166:169], v[194:197], 0
	v_mfma_f32_16x16x32_bf16 v[14:17], v[174:177], v[146:149], 0
	v_mfma_f32_16x16x32_bf16 v[10:13], v[166:169], v[146:149], 0
	v_mfma_f32_16x16x32_bf16 v[6:9], v[174:177], v[130:133], 0
	v_mfma_f32_16x16x32_bf16 v[2:5], v[166:169], v[130:133], 0
	s_nop 0
	v_mfma_f32_16x16x32_bf16 v[30:33], v[170:173], v[206:209], v[30:33]
	v_mfma_f32_16x16x32_bf16 v[26:29], v[162:165], v[206:209], v[26:29]
	v_mfma_f32_16x16x32_bf16 v[22:25], v[170:173], v[198:201], v[22:25]
	v_mfma_f32_16x16x32_bf16 v[18:21], v[162:165], v[198:201], v[18:21]
	v_mfma_f32_16x16x32_bf16 v[14:17], v[170:173], v[154:157], v[14:17]
	v_mfma_f32_16x16x32_bf16 v[10:13], v[162:165], v[154:157], v[10:13]
	v_mfma_f32_16x16x32_bf16 v[6:9], v[170:173], v[138:141], v[6:9]
	v_mfma_f32_16x16x32_bf16 v[2:5], v[162:165], v[138:141], v[2:5]
	s_barrier
	v_add_u32_e32 v194, s46, v238
	v_add_u32_e32 v196, s47, v238
	v_add_u32_e32 v198, s48, v238
	v_add_u32_e32 v200, s49, v238
	v_add_u32_e32 v195, s46, v239
	ds_read_b128 v[146:149], v194
	ds_read_b128 v[150:153], v195
	v_add_u32_e32 v197, s47, v239
	ds_read_b128 v[154:157], v196
	ds_read_b128 v[158:161], v197
	v_add_u32_e32 v199, s48, v239
	ds_read_b128 v[130:133], v198
	ds_read_b128 v[134:137], v199
	v_add_u32_e32 v201, s49, v239
	ds_read_b128 v[138:141], v200
	ds_read_b128 v[142:145], v201
	s_mov_b32 m0, s29
	s_add_i32 s4, s31, 0x40100
	ds_read_b128 v[186:189], v248 offset:32768
	ds_read_b128 v[174:177], v248 offset:34816
	ds_read_b128 v[190:193], v249 offset:32768
	ds_read_b128 v[178:181], v249 offset:34816
	ds_read_b128 v[170:173], v248 offset:36864
	ds_read_b128 v[162:165], v248 offset:38912
	ds_read_b128 v[182:185], v249 offset:36864
	ds_read_b128 v[166:169], v249 offset:38912
	buffer_load_dwordx4 v1, s[12:15], s4 offen lds
	s_mov_b32 m0, s30
	s_and_b64 vcc, exec, s[2:3]
	buffer_load_dwordx4 v234, s[12:15], s4 offen lds
	s_mov_b64 s[4:5], -1
	s_cbranch_vccz .LBB0_1109
	s_waitcnt vmcnt(8)
	s_mov_b64 s[4:5], 0

.LBB0_1111:
	s_waitcnt lgkmcnt(0)
	s_add_i32 s4, s31, 0x180
	s_add_i32 s5, s26, 0x180
	s_barrier
	s_waitcnt lgkmcnt(7)
	v_mfma_f32_16x16x32_bf16 v[126:129], v[146:149], v[186:189], v[126:129]
	v_mfma_f32_16x16x32_bf16 v[122:125], v[154:157], v[186:189], v[122:125]
	s_waitcnt lgkmcnt(6)
	v_mfma_f32_16x16x32_bf16 v[118:121], v[146:149], v[174:177], v[118:121]
	v_mfma_f32_16x16x32_bf16 v[114:117], v[154:157], v[174:177], v[114:117]
	s_waitcnt lgkmcnt(3)
	v_mfma_f32_16x16x32_bf16 v[110:113], v[146:149], v[170:173], v[110:113]
	v_mfma_f32_16x16x32_bf16 v[106:109], v[154:157], v[170:173], v[106:109]
	s_waitcnt lgkmcnt(2)
	v_mfma_f32_16x16x32_bf16 v[102:105], v[146:149], v[162:165], v[102:105]
	v_mfma_f32_16x16x32_bf16 v[98:101], v[154:157], v[162:165], v[98:101]
	v_mfma_f32_16x16x32_bf16 v[126:129], v[150:153], v[190:193], v[126:129]
	v_mfma_f32_16x16x32_bf16 v[122:125], v[158:161], v[190:193], v[122:125]
	v_mfma_f32_16x16x32_bf16 v[118:121], v[150:153], v[178:181], v[118:121]
	v_mfma_f32_16x16x32_bf16 v[114:117], v[158:161], v[178:181], v[114:117]
	s_waitcnt lgkmcnt(1)
	v_mfma_f32_16x16x32_bf16 v[110:113], v[150:153], v[182:185], v[110:113]
	v_mfma_f32_16x16x32_bf16 v[106:109], v[158:161], v[182:185], v[106:109]
	s_waitcnt lgkmcnt(0)
	v_mfma_f32_16x16x32_bf16 v[102:105], v[150:153], v[166:169], v[102:105]
	v_mfma_f32_16x16x32_bf16 v[98:101], v[158:161], v[166:169], v[98:101]
	v_mfma_f32_16x16x32_bf16 v[94:97], v[130:133], v[186:189], v[94:97]
	v_mfma_f32_16x16x32_bf16 v[90:93], v[138:141], v[186:189], v[90:93]
	v_mfma_f32_16x16x32_bf16 v[86:89], v[130:133], v[174:177], v[86:89]
	v_mfma_f32_16x16x32_bf16 v[82:85], v[138:141], v[174:177], v[82:85]
	v_mfma_f32_16x16x32_bf16 v[78:81], v[130:133], v[170:173], v[78:81]
	v_mfma_f32_16x16x32_bf16 v[74:77], v[138:141], v[170:173], v[74:77]
	v_mfma_f32_16x16x32_bf16 v[70:73], v[130:133], v[162:165], v[70:73]
	v_mfma_f32_16x16x32_bf16 v[66:69], v[138:141], v[162:165], v[66:69]
	v_mfma_f32_16x16x32_bf16 v[94:97], v[134:137], v[190:193], v[94:97]
	v_mfma_f32_16x16x32_bf16 v[90:93], v[142:145], v[190:193], v[90:93]
	v_mfma_f32_16x16x32_bf16 v[86:89], v[134:137], v[178:181], v[86:89]
	v_mfma_f32_16x16x32_bf16 v[82:85], v[142:145], v[178:181], v[82:85]
	v_mfma_f32_16x16x32_bf16 v[78:81], v[134:137], v[182:185], v[78:81]
	v_mfma_f32_16x16x32_bf16 v[74:77], v[142:145], v[182:185], v[74:77]
	v_mfma_f32_16x16x32_bf16 v[70:73], v[134:137], v[166:169], v[70:73]
	v_mfma_f32_16x16x32_bf16 v[66:69], v[142:145], v[166:169], v[66:69]
	s_barrier
	s_mov_b32 m0, s35
	ds_read_b128 v[186:189], v248 offset:49152
	ds_read_b128 v[174:177], v248 offset:51200
	ds_read_b128 v[190:193], v249 offset:49152
	ds_read_b128 v[178:181], v249 offset:51200
	ds_read_b128 v[170:173], v248 offset:53248
	ds_read_b128 v[162:165], v248 offset:55296
	ds_read_b128 v[182:185], v249 offset:53248
	ds_read_b128 v[166:169], v249 offset:55296
	buffer_load_dwordx4 v233, s[12:15], s5 offen lds
	s_mov_b32 m0, s36
	s_and_b64 vcc, exec, s[2:3]
	buffer_load_dwordx4 v235, s[12:15], s5 offen lds
	s_add_i32 s5, s26, 0x40180
	s_mov_b32 m0, s39
	s_nop 0
	buffer_load_dwordx4 v233, s[12:15], s5 offen lds
	s_mov_b32 m0, s41
	s_nop 0
	buffer_load_dwordx4 v235, s[12:15], s5 offen lds
	s_mov_b32 m0, s37
	s_nop 0
	buffer_load_dwordx4 v1, s[12:15], s4 offen lds
	s_mov_b32 m0, s38
	s_nop 0
	buffer_load_dwordx4 v234, s[12:15], s4 offen lds
	s_mov_b64 s[4:5], -1
	s_cbranch_vccz .LBB0_1113
	s_waitcnt vmcnt(8)
	s_mov_b64 s[4:5], 0

.LBB0_1115:
	s_waitcnt lgkmcnt(0)
	s_barrier
	s_waitcnt lgkmcnt(7)
	v_mfma_f32_16x16x32_bf16 v[62:65], v[146:149], v[186:189], v[62:65]
	v_mfma_f32_16x16x32_bf16 v[58:61], v[154:157], v[186:189], v[58:61]
	s_waitcnt lgkmcnt(6)
	v_mfma_f32_16x16x32_bf16 v[54:57], v[146:149], v[174:177], v[54:57]
	v_mfma_f32_16x16x32_bf16 v[50:53], v[154:157], v[174:177], v[50:53]
	s_waitcnt lgkmcnt(3)
	v_mfma_f32_16x16x32_bf16 v[46:49], v[146:149], v[170:173], v[46:49]
	v_mfma_f32_16x16x32_bf16 v[42:45], v[154:157], v[170:173], v[42:45]
	s_waitcnt lgkmcnt(2)
	v_mfma_f32_16x16x32_bf16 v[38:41], v[146:149], v[162:165], v[38:41]
	v_mfma_f32_16x16x32_bf16 v[34:37], v[154:157], v[162:165], v[34:37]
	v_mfma_f32_16x16x32_bf16 v[62:65], v[150:153], v[190:193], v[62:65]
	v_mfma_f32_16x16x32_bf16 v[58:61], v[158:161], v[190:193], v[58:61]
	v_mfma_f32_16x16x32_bf16 v[54:57], v[150:153], v[178:181], v[54:57]
	v_mfma_f32_16x16x32_bf16 v[50:53], v[158:161], v[178:181], v[50:53]
	s_waitcnt lgkmcnt(1)
	v_mfma_f32_16x16x32_bf16 v[46:49], v[150:153], v[182:185], v[46:49]
	v_mfma_f32_16x16x32_bf16 v[42:45], v[158:161], v[182:185], v[42:45]
	s_waitcnt lgkmcnt(0)
	v_mfma_f32_16x16x32_bf16 v[38:41], v[150:153], v[166:169], v[38:41]
	v_mfma_f32_16x16x32_bf16 v[34:37], v[158:161], v[166:169], v[34:37]
	v_mfma_f32_16x16x32_bf16 v[30:33], v[130:133], v[186:189], v[30:33]
	v_mfma_f32_16x16x32_bf16 v[26:29], v[138:141], v[186:189], v[26:29]
	v_mfma_f32_16x16x32_bf16 v[22:25], v[130:133], v[174:177], v[22:25]
	v_mfma_f32_16x16x32_bf16 v[18:21], v[138:141], v[174:177], v[18:21]
	v_mfma_f32_16x16x32_bf16 v[14:17], v[130:133], v[170:173], v[14:17]
	v_mfma_f32_16x16x32_bf16 v[10:13], v[138:141], v[170:173], v[10:13]
	v_mfma_f32_16x16x32_bf16 v[6:9], v[130:133], v[162:165], v[6:9]
	v_mfma_f32_16x16x32_bf16 v[2:5], v[138:141], v[162:165], v[2:5]
	v_mfma_f32_16x16x32_bf16 v[30:33], v[134:137], v[190:193], v[30:33]
	v_mfma_f32_16x16x32_bf16 v[26:29], v[142:145], v[190:193], v[26:29]
	v_mfma_f32_16x16x32_bf16 v[22:25], v[134:137], v[178:181], v[22:25]
	v_mfma_f32_16x16x32_bf16 v[18:21], v[142:145], v[178:181], v[18:21]
	v_mfma_f32_16x16x32_bf16 v[14:17], v[134:137], v[182:185], v[14:17]
	v_mfma_f32_16x16x32_bf16 v[10:13], v[142:145], v[182:185], v[10:13]
	v_mfma_f32_16x16x32_bf16 v[6:9], v[134:137], v[166:169], v[6:9]
	v_mfma_f32_16x16x32_bf16 v[2:5], v[142:145], v[166:169], v[2:5]
	s_barrier
	s_add_i32 s50, s34, 1
	s_mul_i32 s3, s50, s94
	s_mul_hi_i32 s2, s50, s94
	s_add_u32 s4, s3, s95
	s_addc_u32 s5, s2, s40
	v_cmp_gt_i64_e64 s[2:3], s[4:5], v[226:227]
	s_and_b64 vcc, exec, s[2:3]
	s_cbranch_vccnz .LBB0_1121
	s_ashr_i32 s8, s4, 31
	s_lshr_b32 s8, s8, 29
	s_add_i32 s8, s4, s8
	s_and_b32 s18, s8, -8
	s_sub_i32 s33, s4, s18
	s_cmp_gt_i32 s33, -1
	s_mov_b64 s[18:19], -1
	s_cbranch_scc0 .LBB0_1118
	s_lshl_b32 s51, s33, 9
	s_mov_b64 s[18:19], 0

.LBB0_1122:
	ds_read_b128 v[130:133], v240
	ds_read_b128 v[134:137], v241
	ds_read_b128 v[138:141], v242
	ds_read_b128 v[142:145], v243
	ds_read_b128 v[146:149], v244
	ds_read_b128 v[150:153], v245
	ds_read_b128 v[154:157], v246
	ds_read_b128 v[158:161], v247
	s_add_i32 s8, s31, s53
	s_add_i32 s55, s26, s53
	s_add_i32 s54, s8, 0x800
	s_addk_i32 s55, 0x800
	s_cmp_eq_u32 s53, 0
	s_cselect_b32 s56, s4, s54
	s_cselect_b32 s55, s5, s55
	s_add_i32 s54, s56, 0x80
	s_add_i32 s57, s8, 0x40780
	s_mov_b32 s8, s70
	s_mov_b32 m0, s44
	ds_read_b128 v[162:165], v248
	ds_read_b128 v[166:169], v248 offset:2048
	ds_read_b128 v[170:173], v249
	ds_read_b128 v[174:177], v249 offset:2048
	ds_read_b128 v[178:181], v248 offset:4096
	ds_read_b128 v[182:185], v248 offset:6144
	ds_read_b128 v[186:189], v249 offset:4096
	ds_read_b128 v[190:193], v249 offset:6144
	buffer_load_dwordx4 v1, s[8:11], s57 offen lds
	s_mov_b32 m0, s45
	s_nop 0
	buffer_load_dwordx4 v234, s[8:11], s57 offen lds
	s_waitcnt vmcnt(8)
	s_waitcnt lgkmcnt(0)
	s_barrier
	s_waitcnt lgkmcnt(7)
	v_mfma_f32_16x16x32_bf16 v[126:129], v[130:133], v[162:165], v[126:129]
	v_mfma_f32_16x16x32_bf16 v[122:125], v[138:141], v[162:165], v[122:125]
	s_waitcnt lgkmcnt(6)
	v_mfma_f32_16x16x32_bf16 v[118:121], v[130:133], v[166:169], v[118:121]
	v_mfma_f32_16x16x32_bf16 v[114:117], v[138:141], v[166:169], v[114:117]
	s_waitcnt lgkmcnt(3)
	v_mfma_f32_16x16x32_bf16 v[110:113], v[130:133], v[178:181], v[110:113]
	v_mfma_f32_16x16x32_bf16 v[106:109], v[138:141], v[178:181], v[106:109]
	s_waitcnt lgkmcnt(2)
	v_mfma_f32_16x16x32_bf16 v[102:105], v[130:133], v[182:185], v[102:105]
	v_mfma_f32_16x16x32_bf16 v[98:101], v[138:141], v[182:185], v[98:101]
	v_mfma_f32_16x16x32_bf16 v[126:129], v[134:137], v[170:173], v[126:129]
	v_mfma_f32_16x16x32_bf16 v[122:125], v[142:145], v[170:173], v[122:125]
	v_mfma_f32_16x16x32_bf16 v[118:121], v[134:137], v[174:177], v[118:121]
	v_mfma_f32_16x16x32_bf16 v[114:117], v[142:145], v[174:177], v[114:117]
	s_waitcnt lgkmcnt(1)
	v_mfma_f32_16x16x32_bf16 v[110:113], v[134:137], v[186:189], v[110:113]
	v_mfma_f32_16x16x32_bf16 v[106:109], v[142:145], v[186:189], v[106:109]
	s_waitcnt lgkmcnt(0)
	v_mfma_f32_16x16x32_bf16 v[102:105], v[134:137], v[190:193], v[102:105]
	v_mfma_f32_16x16x32_bf16 v[98:101], v[142:145], v[190:193], v[98:101]
	v_mfma_f32_16x16x32_bf16 v[94:97], v[146:149], v[162:165], v[94:97]
	v_mfma_f32_16x16x32_bf16 v[90:93], v[154:157], v[162:165], v[90:93]
	v_mfma_f32_16x16x32_bf16 v[86:89], v[146:149], v[166:169], v[86:89]
	v_mfma_f32_16x16x32_bf16 v[82:85], v[154:157], v[166:169], v[82:85]
	v_mfma_f32_16x16x32_bf16 v[78:81], v[146:149], v[178:181], v[78:81]
	v_mfma_f32_16x16x32_bf16 v[74:77], v[154:157], v[178:181], v[74:77]
	v_mfma_f32_16x16x32_bf16 v[70:73], v[146:149], v[182:185], v[70:73]
	v_mfma_f32_16x16x32_bf16 v[66:69], v[154:157], v[182:185], v[66:69]
	v_mfma_f32_16x16x32_bf16 v[94:97], v[150:153], v[170:173], v[94:97]
	v_mfma_f32_16x16x32_bf16 v[90:93], v[158:161], v[170:173], v[90:93]
	v_mfma_f32_16x16x32_bf16 v[86:89], v[150:153], v[174:177], v[86:89]
	v_mfma_f32_16x16x32_bf16 v[82:85], v[158:161], v[174:177], v[82:85]
	v_mfma_f32_16x16x32_bf16 v[78:81], v[150:153], v[186:189], v[78:81]
	v_mfma_f32_16x16x32_bf16 v[74:77], v[158:161], v[186:189], v[74:77]
	v_mfma_f32_16x16x32_bf16 v[70:73], v[150:153], v[190:193], v[70:73]
	v_mfma_f32_16x16x32_bf16 v[66:69], v[158:161], v[190:193], v[66:69]
	s_barrier
	s_mov_b32 m0, s23
	ds_read_b128 v[162:165], v248 offset:16384
	ds_read_b128 v[166:169], v248 offset:18432
	ds_read_b128 v[170:173], v249 offset:16384
	ds_read_b128 v[174:177], v249 offset:18432
	ds_read_b128 v[178:181], v248 offset:20480
	ds_read_b128 v[182:185], v248 offset:22528
	ds_read_b128 v[186:189], v249 offset:20480
	ds_read_b128 v[190:193], v249 offset:22528
	buffer_load_dwordx4 v233, s[8:11], s55 offen lds
	s_mov_b32 m0, s24
	s_add_i32 s57, s55, 0x40000
	buffer_load_dwordx4 v235, s[8:11], s55 offen lds
	s_mov_b32 m0, s25
	s_nop 0
	buffer_load_dwordx4 v233, s[8:11], s57 offen lds
	s_mov_b32 m0, s27
	s_nop 0
	buffer_load_dwordx4 v235, s[8:11], s57 offen lds
	s_mov_b32 m0, s22
	s_nop 0
	buffer_load_dwordx4 v1, s[8:11], s56 offen lds
	s_mov_b32 m0, s28
	s_nop 0
	buffer_load_dwordx4 v234, s[8:11], s56 offen lds
	s_waitcnt vmcnt(8)
	s_waitcnt lgkmcnt(0)
	s_barrier
	s_waitcnt lgkmcnt(7)
	v_mfma_f32_16x16x32_bf16 v[62:65], v[130:133], v[162:165], v[62:65]
	v_mfma_f32_16x16x32_bf16 v[58:61], v[138:141], v[162:165], v[58:61]
	s_waitcnt lgkmcnt(6)
	v_mfma_f32_16x16x32_bf16 v[54:57], v[130:133], v[166:169], v[54:57]
	v_mfma_f32_16x16x32_bf16 v[50:53], v[138:141], v[166:169], v[50:53]
	s_waitcnt lgkmcnt(3)
	v_mfma_f32_16x16x32_bf16 v[46:49], v[130:133], v[178:181], v[46:49]
	v_mfma_f32_16x16x32_bf16 v[42:45], v[138:141], v[178:181], v[42:45]
	s_waitcnt lgkmcnt(2)
	v_mfma_f32_16x16x32_bf16 v[38:41], v[130:133], v[182:185], v[38:41]
	v_mfma_f32_16x16x32_bf16 v[34:37], v[138:141], v[182:185], v[34:37]
	v_mfma_f32_16x16x32_bf16 v[62:65], v[134:137], v[170:173], v[62:65]
	v_mfma_f32_16x16x32_bf16 v[58:61], v[142:145], v[170:173], v[58:61]
	v_mfma_f32_16x16x32_bf16 v[54:57], v[134:137], v[174:177], v[54:57]
	v_mfma_f32_16x16x32_bf16 v[50:53], v[142:145], v[174:177], v[50:53]
	s_waitcnt lgkmcnt(1)
	v_mfma_f32_16x16x32_bf16 v[46:49], v[134:137], v[186:189], v[46:49]
	v_mfma_f32_16x16x32_bf16 v[42:45], v[142:145], v[186:189], v[42:45]
	s_waitcnt lgkmcnt(0)
	v_mfma_f32_16x16x32_bf16 v[38:41], v[134:137], v[190:193], v[38:41]
	v_mfma_f32_16x16x32_bf16 v[34:37], v[142:145], v[190:193], v[34:37]
	v_mfma_f32_16x16x32_bf16 v[30:33], v[146:149], v[162:165], v[30:33]
	v_mfma_f32_16x16x32_bf16 v[26:29], v[154:157], v[162:165], v[26:29]
	v_mfma_f32_16x16x32_bf16 v[22:25], v[146:149], v[166:169], v[22:25]
	v_mfma_f32_16x16x32_bf16 v[18:21], v[154:157], v[166:169], v[18:21]
	v_mfma_f32_16x16x32_bf16 v[14:17], v[146:149], v[178:181], v[14:17]
	v_mfma_f32_16x16x32_bf16 v[10:13], v[154:157], v[178:181], v[10:13]
	v_mfma_f32_16x16x32_bf16 v[6:9], v[146:149], v[182:185], v[6:9]
	v_mfma_f32_16x16x32_bf16 v[2:5], v[154:157], v[182:185], v[2:5]
	v_mfma_f32_16x16x32_bf16 v[30:33], v[150:153], v[170:173], v[30:33]
	v_mfma_f32_16x16x32_bf16 v[26:29], v[158:161], v[170:173], v[26:29]
	v_mfma_f32_16x16x32_bf16 v[22:25], v[150:153], v[174:177], v[22:25]
	v_mfma_f32_16x16x32_bf16 v[18:21], v[158:161], v[174:177], v[18:21]
	v_mfma_f32_16x16x32_bf16 v[14:17], v[150:153], v[186:189], v[14:17]
	v_mfma_f32_16x16x32_bf16 v[10:13], v[158:161], v[186:189], v[10:13]
	v_mfma_f32_16x16x32_bf16 v[6:9], v[150:153], v[190:193], v[6:9]
	v_mfma_f32_16x16x32_bf16 v[2:5], v[158:161], v[190:193], v[2:5]
	s_barrier
	ds_read_b128 v[130:133], v194
	ds_read_b128 v[134:137], v195
	ds_read_b128 v[138:141], v196
	ds_read_b128 v[142:145], v197
	ds_read_b128 v[146:149], v198
	ds_read_b128 v[150:153], v199
	ds_read_b128 v[154:157], v200
	ds_read_b128 v[158:161], v201
	s_add_i32 s56, s56, 0x40000
	s_mov_b32 m0, s29
	ds_read_b128 v[162:165], v248 offset:32768
	ds_read_b128 v[166:169], v248 offset:34816
	ds_read_b128 v[170:173], v249 offset:32768
	ds_read_b128 v[174:177], v249 offset:34816
	ds_read_b128 v[178:181], v248 offset:36864
	ds_read_b128 v[182:185], v248 offset:38912
	ds_read_b128 v[186:189], v249 offset:36864
	ds_read_b128 v[190:193], v249 offset:38912
	buffer_load_dwordx4 v1, s[8:11], s56 offen lds
	s_mov_b32 m0, s30
	s_nop 0
	buffer_load_dwordx4 v234, s[8:11], s56 offen lds
	s_waitcnt vmcnt(8)
	s_waitcnt lgkmcnt(0)
	s_barrier
	s_waitcnt lgkmcnt(7)
	v_mfma_f32_16x16x32_bf16 v[126:129], v[130:133], v[162:165], v[126:129]
	v_mfma_f32_16x16x32_bf16 v[122:125], v[138:141], v[162:165], v[122:125]
	s_waitcnt lgkmcnt(6)
	v_mfma_f32_16x16x32_bf16 v[118:121], v[130:133], v[166:169], v[118:121]
	v_mfma_f32_16x16x32_bf16 v[114:117], v[138:141], v[166:169], v[114:117]
	s_waitcnt lgkmcnt(3)
	v_mfma_f32_16x16x32_bf16 v[110:113], v[130:133], v[178:181], v[110:113]
	v_mfma_f32_16x16x32_bf16 v[106:109], v[138:141], v[178:181], v[106:109]
	s_waitcnt lgkmcnt(2)
	v_mfma_f32_16x16x32_bf16 v[102:105], v[130:133], v[182:185], v[102:105]
	v_mfma_f32_16x16x32_bf16 v[98:101], v[138:141], v[182:185], v[98:101]
	v_mfma_f32_16x16x32_bf16 v[126:129], v[134:137], v[170:173], v[126:129]
	v_mfma_f32_16x16x32_bf16 v[122:125], v[142:145], v[170:173], v[122:125]
	v_mfma_f32_16x16x32_bf16 v[118:121], v[134:137], v[174:177], v[118:121]
	v_mfma_f32_16x16x32_bf16 v[114:117], v[142:145], v[174:177], v[114:117]
	s_waitcnt lgkmcnt(1)
	v_mfma_f32_16x16x32_bf16 v[110:113], v[134:137], v[186:189], v[110:113]
	v_mfma_f32_16x16x32_bf16 v[106:109], v[142:145], v[186:189], v[106:109]
	s_waitcnt lgkmcnt(0)
	v_mfma_f32_16x16x32_bf16 v[102:105], v[134:137], v[190:193], v[102:105]
	v_mfma_f32_16x16x32_bf16 v[98:101], v[142:145], v[190:193], v[98:101]
	v_mfma_f32_16x16x32_bf16 v[94:97], v[146:149], v[162:165], v[94:97]
	v_mfma_f32_16x16x32_bf16 v[90:93], v[154:157], v[162:165], v[90:93]
	v_mfma_f32_16x16x32_bf16 v[86:89], v[146:149], v[166:169], v[86:89]
	v_mfma_f32_16x16x32_bf16 v[82:85], v[154:157], v[166:169], v[82:85]
	v_mfma_f32_16x16x32_bf16 v[78:81], v[146:149], v[178:181], v[78:81]
	v_mfma_f32_16x16x32_bf16 v[74:77], v[154:157], v[178:181], v[74:77]
	v_mfma_f32_16x16x32_bf16 v[70:73], v[146:149], v[182:185], v[70:73]
	v_mfma_f32_16x16x32_bf16 v[66:69], v[154:157], v[182:185], v[66:69]
	v_mfma_f32_16x16x32_bf16 v[94:97], v[150:153], v[170:173], v[94:97]
	v_mfma_f32_16x16x32_bf16 v[90:93], v[158:161], v[170:173], v[90:93]
	v_mfma_f32_16x16x32_bf16 v[86:89], v[150:153], v[174:177], v[86:89]
	v_mfma_f32_16x16x32_bf16 v[82:85], v[158:161], v[174:177], v[82:85]
	v_mfma_f32_16x16x32_bf16 v[78:81], v[150:153], v[186:189], v[78:81]
	v_mfma_f32_16x16x32_bf16 v[74:77], v[158:161], v[186:189], v[74:77]
	v_mfma_f32_16x16x32_bf16 v[70:73], v[150:153], v[190:193], v[70:73]
	v_mfma_f32_16x16x32_bf16 v[66:69], v[158:161], v[190:193], v[66:69]
	s_barrier
	s_mov_b32 m0, s35
	s_add_i32 s56, s55, 0x80
	ds_read_b128 v[162:165], v248 offset:49152
	ds_read_b128 v[166:169], v248 offset:51200
	ds_read_b128 v[170:173], v249 offset:49152
	ds_read_b128 v[174:177], v249 offset:51200
	ds_read_b128 v[178:181], v248 offset:53248
	ds_read_b128 v[182:185], v248 offset:55296
	ds_read_b128 v[186:189], v249 offset:53248
	ds_read_b128 v[190:193], v249 offset:55296
	buffer_load_dwordx4 v233, s[8:11], s56 offen lds
	s_mov_b32 m0, s36
	s_add_i32 s55, s55, 0x40080
	buffer_load_dwordx4 v235, s[8:11], s56 offen lds
	s_mov_b32 m0, s39
	s_nop 0
	buffer_load_dwordx4 v233, s[8:11], s55 offen lds
	s_mov_b32 m0, s41
	s_nop 0
	buffer_load_dwordx4 v235, s[8:11], s55 offen lds
	s_mov_b32 m0, s37
	s_nop 0
	buffer_load_dwordx4 v1, s[8:11], s54 offen lds
	s_mov_b32 m0, s38
	s_nop 0
	buffer_load_dwordx4 v234, s[8:11], s54 offen lds
	s_waitcnt vmcnt(8)
	s_waitcnt lgkmcnt(0)
	s_barrier
	s_waitcnt lgkmcnt(7)
	v_mfma_f32_16x16x32_bf16 v[62:65], v[130:133], v[162:165], v[62:65]
	v_mfma_f32_16x16x32_bf16 v[58:61], v[138:141], v[162:165], v[58:61]
	s_waitcnt lgkmcnt(6)
	v_mfma_f32_16x16x32_bf16 v[54:57], v[130:133], v[166:169], v[54:57]
	v_mfma_f32_16x16x32_bf16 v[50:53], v[138:141], v[166:169], v[50:53]
	s_waitcnt lgkmcnt(3)
	v_mfma_f32_16x16x32_bf16 v[46:49], v[130:133], v[178:181], v[46:49]
	v_mfma_f32_16x16x32_bf16 v[42:45], v[138:141], v[178:181], v[42:45]
	s_waitcnt lgkmcnt(2)
	v_mfma_f32_16x16x32_bf16 v[38:41], v[130:133], v[182:185], v[38:41]
	v_mfma_f32_16x16x32_bf16 v[34:37], v[138:141], v[182:185], v[34:37]
	v_mfma_f32_16x16x32_bf16 v[62:65], v[134:137], v[170:173], v[62:65]
	v_mfma_f32_16x16x32_bf16 v[58:61], v[142:145], v[170:173], v[58:61]
	v_mfma_f32_16x16x32_bf16 v[54:57], v[134:137], v[174:177], v[54:57]
	v_mfma_f32_16x16x32_bf16 v[50:53], v[142:145], v[174:177], v[50:53]
	s_waitcnt lgkmcnt(1)
	v_mfma_f32_16x16x32_bf16 v[46:49], v[134:137], v[186:189], v[46:49]
	v_mfma_f32_16x16x32_bf16 v[42:45], v[142:145], v[186:189], v[42:45]
	s_waitcnt lgkmcnt(0)
	v_mfma_f32_16x16x32_bf16 v[38:41], v[134:137], v[190:193], v[38:41]
	v_mfma_f32_16x16x32_bf16 v[34:37], v[142:145], v[190:193], v[34:37]
	v_mfma_f32_16x16x32_bf16 v[30:33], v[146:149], v[162:165], v[30:33]
	v_mfma_f32_16x16x32_bf16 v[26:29], v[154:157], v[162:165], v[26:29]
	v_mfma_f32_16x16x32_bf16 v[22:25], v[146:149], v[166:169], v[22:25]
	v_mfma_f32_16x16x32_bf16 v[18:21], v[154:157], v[166:169], v[18:21]
	v_mfma_f32_16x16x32_bf16 v[14:17], v[146:149], v[178:181], v[14:17]
	v_mfma_f32_16x16x32_bf16 v[10:13], v[154:157], v[178:181], v[10:13]
	v_mfma_f32_16x16x32_bf16 v[6:9], v[146:149], v[182:185], v[6:9]
	v_mfma_f32_16x16x32_bf16 v[2:5], v[154:157], v[182:185], v[2:5]
	v_mfma_f32_16x16x32_bf16 v[30:33], v[150:153], v[170:173], v[30:33]
	v_mfma_f32_16x16x32_bf16 v[26:29], v[158:161], v[170:173], v[26:29]
	v_mfma_f32_16x16x32_bf16 v[22:25], v[150:153], v[174:177], v[22:25]
	v_mfma_f32_16x16x32_bf16 v[18:21], v[158:161], v[174:177], v[18:21]
	v_mfma_f32_16x16x32_bf16 v[14:17], v[150:153], v[186:189], v[14:17]
	v_mfma_f32_16x16x32_bf16 v[10:13], v[158:161], v[186:189], v[10:13]
	v_mfma_f32_16x16x32_bf16 v[6:9], v[150:153], v[190:193], v[6:9]
	v_mfma_f32_16x16x32_bf16 v[2:5], v[158:161], v[190:193], v[2:5]
	s_barrier
	s_add_i32 s33, s33, 2
	s_addk_i32 s53, 0x100
	s_cmp_gt_u32 s33, 13
	s_cbranch_scc0 .LBB0_1122
	s_and_b64 vcc, exec, s[16:17]
	s_cbranch_vccz .LBB0_1125
	s_barrier

.LBB0_1232:
	s_waitcnt lgkmcnt(0)
	s_add_i32 s2, s51, 0x100
	s_add_i32 s3, s46, 0x100
	s_barrier
	s_waitcnt lgkmcnt(7)
	v_mfma_f32_16x16x32_bf16 v[74:77], v[190:193], v[218:221], 0
	v_mfma_f32_16x16x32_bf16 v[70:73], v[182:185], v[218:221], 0
	s_waitcnt lgkmcnt(6)
	v_mfma_f32_16x16x32_bf16 v[66:69], v[190:193], v[210:213], 0
	v_mfma_f32_16x16x32_bf16 v[82:85], v[182:185], v[210:213], 0
	s_waitcnt lgkmcnt(3)
	v_mfma_f32_16x16x32_bf16 v[78:81], v[190:193], v[202:205], 0
	v_mfma_f32_16x16x32_bf16 v[90:93], v[182:185], v[202:205], 0
	s_waitcnt lgkmcnt(2)
	v_mfma_f32_16x16x32_bf16 v[86:89], v[190:193], v[194:197], 0
	v_mfma_f32_16x16x32_bf16 v[102:105], v[182:185], v[194:197], 0
	v_mfma_f32_16x16x32_bf16 v[74:77], v[186:189], v[222:225], v[74:77]
	v_mfma_f32_16x16x32_bf16 v[70:73], v[178:181], v[222:225], v[70:73]
	v_mfma_f32_16x16x32_bf16 v[66:69], v[186:189], v[214:217], v[66:69]
	v_mfma_f32_16x16x32_bf16 v[82:85], v[178:181], v[214:217], v[82:85]
	s_waitcnt lgkmcnt(1)
	v_mfma_f32_16x16x32_bf16 v[78:81], v[186:189], v[206:209], v[78:81]
	v_mfma_f32_16x16x32_bf16 v[90:93], v[178:181], v[206:209], v[90:93]
	s_waitcnt lgkmcnt(0)
	v_mfma_f32_16x16x32_bf16 v[86:89], v[186:189], v[198:201], v[86:89]
	v_mfma_f32_16x16x32_bf16 v[102:105], v[178:181], v[198:201], v[102:105]
	v_mfma_f32_16x16x32_bf16 v[98:101], v[174:177], v[218:221], 0
	v_mfma_f32_16x16x32_bf16 v[94:97], v[166:169], v[218:221], 0
	v_mfma_f32_16x16x32_bf16 v[106:109], v[174:177], v[210:213], 0
	v_mfma_f32_16x16x32_bf16 v[110:113], v[166:169], v[210:213], 0
	v_mfma_f32_16x16x32_bf16 v[114:117], v[174:177], v[202:205], 0
	v_mfma_f32_16x16x32_bf16 v[118:121], v[166:169], v[202:205], 0
	v_mfma_f32_16x16x32_bf16 v[122:125], v[174:177], v[194:197], 0
	v_mfma_f32_16x16x32_bf16 v[126:129], v[166:169], v[194:197], 0
	s_nop 0
	v_mfma_f32_16x16x32_bf16 v[98:101], v[170:173], v[222:225], v[98:101]
	v_mfma_f32_16x16x32_bf16 v[94:97], v[162:165], v[222:225], v[94:97]
	v_mfma_f32_16x16x32_bf16 v[106:109], v[170:173], v[214:217], v[106:109]
	v_mfma_f32_16x16x32_bf16 v[110:113], v[162:165], v[214:217], v[110:113]
	v_mfma_f32_16x16x32_bf16 v[114:117], v[170:173], v[206:209], v[114:117]
	v_mfma_f32_16x16x32_bf16 v[118:121], v[162:165], v[206:209], v[118:121]
	v_mfma_f32_16x16x32_bf16 v[122:125], v[170:173], v[198:201], v[122:125]
	v_mfma_f32_16x16x32_bf16 v[126:129], v[162:165], v[198:201], v[126:129]
	s_barrier
	s_mov_b32 m0, s43
	s_mov_b32 s8, s70
	ds_read_b128 v[202:205], v247 offset:16384
	ds_read_b128 v[194:197], v247 offset:18432
	ds_read_b128 v[206:209], v248 offset:16384
	ds_read_b128 v[198:201], v248 offset:18432
	ds_read_b128 v[138:141], v247 offset:20480
	ds_read_b128 v[130:133], v247 offset:22528
	ds_read_b128 v[142:145], v248 offset:20480
	ds_read_b128 v[134:137], v248 offset:22528
	buffer_load_dwordx4 v231, s[8:11], s3 offen lds
	s_mov_b32 m0, s44
	s_and_b64 vcc, exec, s[0:1]
	buffer_load_dwordx4 v234, s[8:11], s3 offen lds
	s_add_i32 s3, s46, 0x100100
	s_mov_b32 m0, s45
	s_nop 0
	buffer_load_dwordx4 v231, s[8:11], s3 offen lds
	s_mov_b32 m0, s47
	s_nop 0
	buffer_load_dwordx4 v234, s[8:11], s3 offen lds
	s_mov_b32 m0, s42
	s_nop 0
	buffer_load_dwordx4 v230, s[8:11], s2 offen lds
	s_mov_b32 m0, s48
	s_nop 0
	buffer_load_dwordx4 v233, s[8:11], s2 offen lds
	s_mov_b64 s[2:3], -1
	s_cbranch_vccz .LBB0_1234
	s_waitcnt vmcnt(8)
	s_mov_b64 s[2:3], 0

.LBB0_1236:
	s_waitcnt lgkmcnt(0)
	s_barrier
	s_waitcnt lgkmcnt(7)
	v_mfma_f32_16x16x32_bf16 v[10:13], v[190:193], v[202:205], 0
	v_mfma_f32_16x16x32_bf16 v[6:9], v[182:185], v[202:205], 0
	s_waitcnt lgkmcnt(6)
	v_mfma_f32_16x16x32_bf16 v[2:5], v[190:193], v[194:197], 0
	v_mfma_f32_16x16x32_bf16 v[18:21], v[182:185], v[194:197], 0
	s_waitcnt lgkmcnt(3)
	v_mfma_f32_16x16x32_bf16 v[14:17], v[190:193], v[138:141], 0
	v_mfma_f32_16x16x32_bf16 v[26:29], v[182:185], v[138:141], 0
	s_waitcnt lgkmcnt(2)
	v_mfma_f32_16x16x32_bf16 v[22:25], v[190:193], v[130:133], 0
	v_mfma_f32_16x16x32_bf16 v[38:41], v[182:185], v[130:133], 0
	v_mfma_f32_16x16x32_bf16 v[10:13], v[186:189], v[206:209], v[10:13]
	v_mfma_f32_16x16x32_bf16 v[6:9], v[178:181], v[206:209], v[6:9]
	v_mfma_f32_16x16x32_bf16 v[0:3], v[186:189], v[198:201], v[2:5]
	v_mfma_f32_16x16x32_bf16 v[18:21], v[178:181], v[198:201], v[18:21]
	s_waitcnt lgkmcnt(1)
	v_mfma_f32_16x16x32_bf16 v[14:17], v[186:189], v[142:145], v[14:17]
	v_mfma_f32_16x16x32_bf16 v[26:29], v[178:181], v[142:145], v[26:29]
	s_waitcnt lgkmcnt(0)
	v_mfma_f32_16x16x32_bf16 v[22:25], v[186:189], v[134:137], v[22:25]
	v_mfma_f32_16x16x32_bf16 v[38:41], v[178:181], v[134:137], v[38:41]
	v_mfma_f32_16x16x32_bf16 v[34:37], v[174:177], v[202:205], 0
	v_mfma_f32_16x16x32_bf16 v[30:33], v[166:169], v[202:205], 0
	v_mfma_f32_16x16x32_bf16 v[42:45], v[174:177], v[194:197], 0
	v_mfma_f32_16x16x32_bf16 v[46:49], v[166:169], v[194:197], 0
	v_mfma_f32_16x16x32_bf16 v[50:53], v[174:177], v[138:141], 0
	v_mfma_f32_16x16x32_bf16 v[54:57], v[166:169], v[138:141], 0
	v_mfma_f32_16x16x32_bf16 v[58:61], v[174:177], v[130:133], 0
	v_mfma_f32_16x16x32_bf16 v[62:65], v[166:169], v[130:133], 0
	s_nop 0
	v_mfma_f32_16x16x32_bf16 v[34:37], v[170:173], v[206:209], v[34:37]
	v_mfma_f32_16x16x32_bf16 v[30:33], v[162:165], v[206:209], v[30:33]
	v_mfma_f32_16x16x32_bf16 v[42:45], v[170:173], v[198:201], v[42:45]
	v_mfma_f32_16x16x32_bf16 v[46:49], v[162:165], v[198:201], v[46:49]
	v_mfma_f32_16x16x32_bf16 v[50:53], v[170:173], v[142:145], v[50:53]
	v_mfma_f32_16x16x32_bf16 v[54:57], v[162:165], v[142:145], v[54:57]
	v_mfma_f32_16x16x32_bf16 v[58:61], v[170:173], v[134:137], v[58:61]
	v_mfma_f32_16x16x32_bf16 v[62:65], v[162:165], v[134:137], v[62:65]
	s_barrier
	s_add_i32 s2, 0, 0x18000
	v_add_u32_e32 v194, s2, v237
	v_add_u32_e32 v195, s2, v238
	s_add_i32 s2, 0, 0x1c000
	v_add_u32_e32 v196, s72, v237
	v_add_u32_e32 v198, s2, v237
	v_add_u32_e32 v200, s73, v237
	ds_read_b128 v[146:149], v194
	ds_read_b128 v[150:153], v195
	v_add_u32_e32 v197, s72, v238
	ds_read_b128 v[154:157], v196
	ds_read_b128 v[158:161], v197
	v_add_u32_e32 v199, s2, v238
	ds_read_b128 v[130:133], v198
	ds_read_b128 v[134:137], v199
	v_add_u32_e32 v201, s73, v238
	ds_read_b128 v[138:141], v200
	ds_read_b128 v[142:145], v201
	s_mov_b32 m0, s49
	s_add_i32 s2, s51, 0x100100
	s_mov_b32 s8, s70
	ds_read_b128 v[186:189], v247 offset:32768
	ds_read_b128 v[174:177], v247 offset:34816
	ds_read_b128 v[190:193], v248 offset:32768
	ds_read_b128 v[178:181], v248 offset:34816
	ds_read_b128 v[170:173], v247 offset:36864
	ds_read_b128 v[162:165], v247 offset:38912
	ds_read_b128 v[182:185], v248 offset:36864
	ds_read_b128 v[166:169], v248 offset:38912
	buffer_load_dwordx4 v230, s[8:11], s2 offen lds
	s_mov_b32 m0, s50
	s_and_b64 vcc, exec, s[0:1]
	buffer_load_dwordx4 v233, s[8:11], s2 offen lds
	s_mov_b64 s[2:3], -1
	s_cbranch_vccz .LBB0_1238
	s_waitcnt vmcnt(8)
	s_mov_b64 s[2:3], 0

.LBB0_1240:
	s_waitcnt lgkmcnt(0)
	s_add_i32 s2, s51, 0x180
	s_add_i32 s3, s46, 0x180
	s_barrier
	s_waitcnt lgkmcnt(7)
	v_mfma_f32_16x16x32_bf16 v[74:77], v[146:149], v[186:189], v[74:77]
	v_mfma_f32_16x16x32_bf16 v[70:73], v[154:157], v[186:189], v[70:73]
	s_waitcnt lgkmcnt(6)
	v_mfma_f32_16x16x32_bf16 v[66:69], v[146:149], v[174:177], v[66:69]
	v_mfma_f32_16x16x32_bf16 v[82:85], v[154:157], v[174:177], v[82:85]
	s_waitcnt lgkmcnt(3)
	v_mfma_f32_16x16x32_bf16 v[78:81], v[146:149], v[170:173], v[78:81]
	v_mfma_f32_16x16x32_bf16 v[90:93], v[154:157], v[170:173], v[90:93]
	s_waitcnt lgkmcnt(2)
	v_mfma_f32_16x16x32_bf16 v[86:89], v[146:149], v[162:165], v[86:89]
	v_mfma_f32_16x16x32_bf16 v[102:105], v[154:157], v[162:165], v[102:105]
	v_mfma_f32_16x16x32_bf16 v[74:77], v[150:153], v[190:193], v[74:77]
	v_mfma_f32_16x16x32_bf16 v[70:73], v[158:161], v[190:193], v[70:73]
	v_mfma_f32_16x16x32_bf16 v[66:69], v[150:153], v[178:181], v[66:69]
	v_mfma_f32_16x16x32_bf16 v[82:85], v[158:161], v[178:181], v[82:85]
	s_waitcnt lgkmcnt(1)
	v_mfma_f32_16x16x32_bf16 v[78:81], v[150:153], v[182:185], v[78:81]
	v_mfma_f32_16x16x32_bf16 v[90:93], v[158:161], v[182:185], v[90:93]
	s_waitcnt lgkmcnt(0)
	v_mfma_f32_16x16x32_bf16 v[86:89], v[150:153], v[166:169], v[86:89]
	v_mfma_f32_16x16x32_bf16 v[102:105], v[158:161], v[166:169], v[102:105]
	v_mfma_f32_16x16x32_bf16 v[98:101], v[130:133], v[186:189], v[98:101]
	v_mfma_f32_16x16x32_bf16 v[94:97], v[138:141], v[186:189], v[94:97]
	v_mfma_f32_16x16x32_bf16 v[106:109], v[130:133], v[174:177], v[106:109]
	v_mfma_f32_16x16x32_bf16 v[110:113], v[138:141], v[174:177], v[110:113]
	v_mfma_f32_16x16x32_bf16 v[114:117], v[130:133], v[170:173], v[114:117]
	v_mfma_f32_16x16x32_bf16 v[118:121], v[138:141], v[170:173], v[118:121]
	v_mfma_f32_16x16x32_bf16 v[122:125], v[130:133], v[162:165], v[122:125]
	v_mfma_f32_16x16x32_bf16 v[126:129], v[138:141], v[162:165], v[126:129]
	v_mfma_f32_16x16x32_bf16 v[98:101], v[134:137], v[190:193], v[98:101]
	v_mfma_f32_16x16x32_bf16 v[94:97], v[142:145], v[190:193], v[94:97]
	v_mfma_f32_16x16x32_bf16 v[106:109], v[134:137], v[178:181], v[106:109]
	v_mfma_f32_16x16x32_bf16 v[110:113], v[142:145], v[178:181], v[110:113]
	v_mfma_f32_16x16x32_bf16 v[114:117], v[134:137], v[182:185], v[114:117]
	v_mfma_f32_16x16x32_bf16 v[118:121], v[142:145], v[182:185], v[118:121]
	v_mfma_f32_16x16x32_bf16 v[122:125], v[134:137], v[166:169], v[122:125]
	v_mfma_f32_16x16x32_bf16 v[126:129], v[142:145], v[166:169], v[126:129]
	s_barrier
	s_mov_b32 m0, s53
	s_mov_b32 s8, s70
	ds_read_b128 v[186:189], v247 offset:49152
	ds_read_b128 v[174:177], v247 offset:51200
	ds_read_b128 v[190:193], v248 offset:49152
	ds_read_b128 v[178:181], v248 offset:51200
	ds_read_b128 v[170:173], v247 offset:53248
	ds_read_b128 v[162:165], v247 offset:55296
	ds_read_b128 v[182:185], v248 offset:53248
	ds_read_b128 v[166:169], v248 offset:55296
	buffer_load_dwordx4 v231, s[8:11], s3 offen lds
	s_mov_b32 m0, s54
	s_and_b64 vcc, exec, s[0:1]
	buffer_load_dwordx4 v234, s[8:11], s3 offen lds
	s_add_i32 s3, s46, 0x100180
	s_mov_b32 m0, s57
	s_nop 0
	buffer_load_dwordx4 v231, s[8:11], s3 offen lds
	s_mov_b32 m0, s58
	s_nop 0
	buffer_load_dwordx4 v234, s[8:11], s3 offen lds
	s_mov_b32 m0, s55
	s_nop 0
	buffer_load_dwordx4 v230, s[8:11], s2 offen lds
	s_mov_b32 m0, s56
	s_nop 0
	buffer_load_dwordx4 v233, s[8:11], s2 offen lds
	s_mov_b64 s[2:3], -1
	s_cbranch_vccz .LBB0_1242
	s_waitcnt vmcnt(8)
	s_mov_b64 s[2:3], 0

.LBB0_1244:
	s_waitcnt lgkmcnt(0)
	s_barrier
	s_waitcnt lgkmcnt(7)
	v_mfma_f32_16x16x32_bf16 v[10:13], v[146:149], v[186:189], v[10:13]
	v_mfma_f32_16x16x32_bf16 v[4:7], v[154:157], v[186:189], v[6:9]
	s_waitcnt lgkmcnt(6)
	v_mfma_f32_16x16x32_bf16 v[0:3], v[146:149], v[174:177], v[0:3]
	v_mfma_f32_16x16x32_bf16 v[18:21], v[154:157], v[174:177], v[18:21]
	s_waitcnt lgkmcnt(3)
	v_mfma_f32_16x16x32_bf16 v[14:17], v[146:149], v[170:173], v[14:17]
	v_mfma_f32_16x16x32_bf16 v[26:29], v[154:157], v[170:173], v[26:29]
	s_waitcnt lgkmcnt(2)
	v_mfma_f32_16x16x32_bf16 v[22:25], v[146:149], v[162:165], v[22:25]
	v_mfma_f32_16x16x32_bf16 v[38:41], v[154:157], v[162:165], v[38:41]
	v_mfma_f32_16x16x32_bf16 v[10:13], v[150:153], v[190:193], v[10:13]
	v_mfma_f32_16x16x32_bf16 v[6:9], v[158:161], v[190:193], v[4:7]
	v_mfma_f32_16x16x32_bf16 v[2:5], v[150:153], v[178:181], v[0:3]
	v_mfma_f32_16x16x32_bf16 v[18:21], v[158:161], v[178:181], v[18:21]
	s_waitcnt lgkmcnt(1)
	v_mfma_f32_16x16x32_bf16 v[14:17], v[150:153], v[182:185], v[14:17]
	v_mfma_f32_16x16x32_bf16 v[26:29], v[158:161], v[182:185], v[26:29]
	s_waitcnt lgkmcnt(0)
	v_mfma_f32_16x16x32_bf16 v[22:25], v[150:153], v[166:169], v[22:25]
	v_mfma_f32_16x16x32_bf16 v[38:41], v[158:161], v[166:169], v[38:41]
	v_mfma_f32_16x16x32_bf16 v[34:37], v[130:133], v[186:189], v[34:37]
	v_mfma_f32_16x16x32_bf16 v[30:33], v[138:141], v[186:189], v[30:33]
	v_mfma_f32_16x16x32_bf16 v[42:45], v[130:133], v[174:177], v[42:45]
	v_mfma_f32_16x16x32_bf16 v[46:49], v[138:141], v[174:177], v[46:49]
	v_mfma_f32_16x16x32_bf16 v[50:53], v[130:133], v[170:173], v[50:53]
	v_mfma_f32_16x16x32_bf16 v[54:57], v[138:141], v[170:173], v[54:57]
	v_mfma_f32_16x16x32_bf16 v[58:61], v[130:133], v[162:165], v[58:61]
	v_mfma_f32_16x16x32_bf16 v[62:65], v[138:141], v[162:165], v[62:65]
	v_mfma_f32_16x16x32_bf16 v[34:37], v[134:137], v[190:193], v[34:37]
	v_mfma_f32_16x16x32_bf16 v[30:33], v[142:145], v[190:193], v[30:33]
	v_mfma_f32_16x16x32_bf16 v[42:45], v[134:137], v[178:181], v[42:45]
	v_mfma_f32_16x16x32_bf16 v[46:49], v[142:145], v[178:181], v[46:49]
	v_mfma_f32_16x16x32_bf16 v[50:53], v[134:137], v[182:185], v[50:53]
	v_mfma_f32_16x16x32_bf16 v[54:57], v[142:145], v[182:185], v[54:57]
	v_mfma_f32_16x16x32_bf16 v[58:61], v[134:137], v[166:169], v[58:61]
	v_mfma_f32_16x16x32_bf16 v[62:65], v[142:145], v[166:169], v[62:65]
	s_barrier
	s_add_i32 s82, s52, 1
	s_mul_i32 s0, s82, s94
	s_mul_hi_i32 s1, s82, s94
	s_add_u32 s0, s0, s95
	s_addc_u32 s1, s1, s65
	v_cmp_gt_i64_e64 s[2:3], s[0:1], v[226:227]
	s_and_b64 vcc, exec, s[2:3]
	s_cbranch_vccnz .LBB0_1250
	s_ashr_i32 s4, s0, 31
	s_lshr_b32 s4, s4, 29
	s_add_i32 s8, s0, s4
	s_and_b32 s4, s8, -8
	s_sub_i32 s30, s0, s4
	s_cmp_gt_i32 s30, -1
	s_mov_b64 s[4:5], -1
	s_cbranch_scc0 .LBB0_1247
	s_lshl_b32 s31, s30, 7
	s_mov_b64 s[4:5], 0

.LBB0_1251:
	ds_read_b128 v[130:133], v239
	ds_read_b128 v[134:137], v240
	ds_read_b128 v[138:141], v241
	ds_read_b128 v[142:145], v242
	ds_read_b128 v[146:149], v243
	ds_read_b128 v[150:153], v244
	ds_read_b128 v[154:157], v245
	ds_read_b128 v[158:161], v246
	s_add_i32 s8, s51, s5
	s_add_i32 s31, s46, s5
	s_add_i32 s30, s8, 0x2000
	s_addk_i32 s31, 0x2000
	s_cmp_eq_u32 s5, 0
	s_cselect_b32 s33, s0, s30
	s_cselect_b32 s31, s1, s31
	s_add_i32 s30, s33, 0x80
	s_add_i32 s34, s8, 0x101f80
	s_mov_b32 s8, s70
	s_mov_b32 m0, s61
	ds_read_b128 v[162:165], v247
	ds_read_b128 v[166:169], v247 offset:2048
	ds_read_b128 v[170:173], v248
	ds_read_b128 v[174:177], v248 offset:2048
	ds_read_b128 v[178:181], v247 offset:4096
	ds_read_b128 v[182:185], v247 offset:6144
	ds_read_b128 v[186:189], v248 offset:4096
	ds_read_b128 v[190:193], v248 offset:6144
	buffer_load_dwordx4 v230, s[8:11], s34 offen lds
	s_mov_b32 m0, s64
	s_nop 0
	buffer_load_dwordx4 v233, s[8:11], s34 offen lds
	s_waitcnt vmcnt(8)
	s_waitcnt lgkmcnt(0)
	s_barrier
	s_waitcnt lgkmcnt(7)
	v_mfma_f32_16x16x32_bf16 v[74:77], v[130:133], v[162:165], v[74:77]
	v_mfma_f32_16x16x32_bf16 v[70:73], v[138:141], v[162:165], v[70:73]
	s_waitcnt lgkmcnt(6)
	v_mfma_f32_16x16x32_bf16 v[66:69], v[130:133], v[166:169], v[66:69]
	v_mfma_f32_16x16x32_bf16 v[82:85], v[138:141], v[166:169], v[82:85]
	s_waitcnt lgkmcnt(3)
	v_mfma_f32_16x16x32_bf16 v[78:81], v[130:133], v[178:181], v[78:81]
	v_mfma_f32_16x16x32_bf16 v[90:93], v[138:141], v[178:181], v[90:93]
	s_waitcnt lgkmcnt(2)
	v_mfma_f32_16x16x32_bf16 v[86:89], v[130:133], v[182:185], v[86:89]
	v_mfma_f32_16x16x32_bf16 v[102:105], v[138:141], v[182:185], v[102:105]
	v_mfma_f32_16x16x32_bf16 v[74:77], v[134:137], v[170:173], v[74:77]
	v_mfma_f32_16x16x32_bf16 v[70:73], v[142:145], v[170:173], v[70:73]
	v_mfma_f32_16x16x32_bf16 v[66:69], v[134:137], v[174:177], v[66:69]
	v_mfma_f32_16x16x32_bf16 v[82:85], v[142:145], v[174:177], v[82:85]
	s_waitcnt lgkmcnt(1)
	v_mfma_f32_16x16x32_bf16 v[78:81], v[134:137], v[186:189], v[78:81]
	v_mfma_f32_16x16x32_bf16 v[90:93], v[142:145], v[186:189], v[90:93]
	s_waitcnt lgkmcnt(0)
	v_mfma_f32_16x16x32_bf16 v[86:89], v[134:137], v[190:193], v[86:89]
	v_mfma_f32_16x16x32_bf16 v[102:105], v[142:145], v[190:193], v[102:105]
	v_mfma_f32_16x16x32_bf16 v[98:101], v[146:149], v[162:165], v[98:101]
	v_mfma_f32_16x16x32_bf16 v[94:97], v[154:157], v[162:165], v[94:97]
	v_mfma_f32_16x16x32_bf16 v[106:109], v[146:149], v[166:169], v[106:109]
	v_mfma_f32_16x16x32_bf16 v[110:113], v[154:157], v[166:169], v[110:113]
	v_mfma_f32_16x16x32_bf16 v[114:117], v[146:149], v[178:181], v[114:117]
	v_mfma_f32_16x16x32_bf16 v[118:121], v[154:157], v[178:181], v[118:121]
	v_mfma_f32_16x16x32_bf16 v[122:125], v[146:149], v[182:185], v[122:125]
	v_mfma_f32_16x16x32_bf16 v[126:129], v[154:157], v[182:185], v[126:129]
	v_mfma_f32_16x16x32_bf16 v[98:101], v[150:153], v[170:173], v[98:101]
	v_mfma_f32_16x16x32_bf16 v[94:97], v[158:161], v[170:173], v[94:97]
	v_mfma_f32_16x16x32_bf16 v[106:109], v[150:153], v[174:177], v[106:109]
	v_mfma_f32_16x16x32_bf16 v[110:113], v[158:161], v[174:177], v[110:113]
	v_mfma_f32_16x16x32_bf16 v[114:117], v[150:153], v[186:189], v[114:117]
	v_mfma_f32_16x16x32_bf16 v[118:121], v[158:161], v[186:189], v[118:121]
	v_mfma_f32_16x16x32_bf16 v[122:125], v[150:153], v[190:193], v[122:125]
	v_mfma_f32_16x16x32_bf16 v[126:129], v[158:161], v[190:193], v[126:129]
	s_barrier
	s_mov_b32 m0, s43
	ds_read_b128 v[162:165], v247 offset:16384
	ds_read_b128 v[166:169], v247 offset:18432
	ds_read_b128 v[170:173], v248 offset:16384
	ds_read_b128 v[174:177], v248 offset:18432
	ds_read_b128 v[178:181], v247 offset:20480
	ds_read_b128 v[182:185], v247 offset:22528
	ds_read_b128 v[186:189], v248 offset:20480
	ds_read_b128 v[190:193], v248 offset:22528
	buffer_load_dwordx4 v231, s[8:11], s31 offen lds
	s_mov_b32 m0, s44
	s_add_i32 s34, s31, 0x100000
	buffer_load_dwordx4 v234, s[8:11], s31 offen lds
	s_mov_b32 m0, s45
	s_nop 0
	buffer_load_dwordx4 v231, s[8:11], s34 offen lds
	s_mov_b32 m0, s47
	s_nop 0
	buffer_load_dwordx4 v234, s[8:11], s34 offen lds
	s_mov_b32 m0, s42
	s_nop 0
	buffer_load_dwordx4 v230, s[8:11], s33 offen lds
	s_mov_b32 m0, s48
	s_nop 0
	buffer_load_dwordx4 v233, s[8:11], s33 offen lds
	s_waitcnt vmcnt(8)
	s_waitcnt lgkmcnt(0)
	s_barrier
	s_waitcnt lgkmcnt(7)
	v_mfma_f32_16x16x32_bf16 v[10:13], v[130:133], v[162:165], v[10:13]
	v_mfma_f32_16x16x32_bf16 v[6:9], v[138:141], v[162:165], v[6:9]
	s_waitcnt lgkmcnt(6)
	v_mfma_f32_16x16x32_bf16 v[0:3], v[130:133], v[166:169], v[2:5]
	v_mfma_f32_16x16x32_bf16 v[18:21], v[138:141], v[166:169], v[18:21]
	s_waitcnt lgkmcnt(3)
	v_mfma_f32_16x16x32_bf16 v[14:17], v[130:133], v[178:181], v[14:17]
	v_mfma_f32_16x16x32_bf16 v[26:29], v[138:141], v[178:181], v[26:29]
	s_waitcnt lgkmcnt(2)
	v_mfma_f32_16x16x32_bf16 v[22:25], v[130:133], v[182:185], v[22:25]
	v_mfma_f32_16x16x32_bf16 v[38:41], v[138:141], v[182:185], v[38:41]
	v_mfma_f32_16x16x32_bf16 v[10:13], v[134:137], v[170:173], v[10:13]
	v_mfma_f32_16x16x32_bf16 v[6:9], v[142:145], v[170:173], v[6:9]
	v_mfma_f32_16x16x32_bf16 v[0:3], v[134:137], v[174:177], v[0:3]
	v_mfma_f32_16x16x32_bf16 v[18:21], v[142:145], v[174:177], v[18:21]
	s_waitcnt lgkmcnt(1)
	v_mfma_f32_16x16x32_bf16 v[14:17], v[134:137], v[186:189], v[14:17]
	v_mfma_f32_16x16x32_bf16 v[26:29], v[142:145], v[186:189], v[26:29]
	s_waitcnt lgkmcnt(0)
	v_mfma_f32_16x16x32_bf16 v[22:25], v[134:137], v[190:193], v[22:25]
	v_mfma_f32_16x16x32_bf16 v[38:41], v[142:145], v[190:193], v[38:41]
	v_mfma_f32_16x16x32_bf16 v[34:37], v[146:149], v[162:165], v[34:37]
	v_mfma_f32_16x16x32_bf16 v[30:33], v[154:157], v[162:165], v[30:33]
	v_mfma_f32_16x16x32_bf16 v[42:45], v[146:149], v[166:169], v[42:45]
	v_mfma_f32_16x16x32_bf16 v[46:49], v[154:157], v[166:169], v[46:49]
	v_mfma_f32_16x16x32_bf16 v[50:53], v[146:149], v[178:181], v[50:53]
	v_mfma_f32_16x16x32_bf16 v[54:57], v[154:157], v[178:181], v[54:57]
	v_mfma_f32_16x16x32_bf16 v[58:61], v[146:149], v[182:185], v[58:61]
	v_mfma_f32_16x16x32_bf16 v[62:65], v[154:157], v[182:185], v[62:65]
	v_mfma_f32_16x16x32_bf16 v[34:37], v[150:153], v[170:173], v[34:37]
	v_mfma_f32_16x16x32_bf16 v[30:33], v[158:161], v[170:173], v[30:33]
	v_mfma_f32_16x16x32_bf16 v[42:45], v[150:153], v[174:177], v[42:45]
	v_mfma_f32_16x16x32_bf16 v[46:49], v[158:161], v[174:177], v[46:49]
	v_mfma_f32_16x16x32_bf16 v[50:53], v[150:153], v[186:189], v[50:53]
	v_mfma_f32_16x16x32_bf16 v[54:57], v[158:161], v[186:189], v[54:57]
	v_mfma_f32_16x16x32_bf16 v[58:61], v[150:153], v[190:193], v[58:61]
	v_mfma_f32_16x16x32_bf16 v[62:65], v[158:161], v[190:193], v[62:65]
	s_barrier
	ds_read_b128 v[130:133], v194
	ds_read_b128 v[134:137], v195
	ds_read_b128 v[138:141], v196
	ds_read_b128 v[142:145], v197
	ds_read_b128 v[146:149], v198
	ds_read_b128 v[150:153], v199
	ds_read_b128 v[154:157], v200
	ds_read_b128 v[158:161], v201
	s_add_i32 s33, s33, 0x100000
	s_mov_b32 m0, s49
	ds_read_b128 v[162:165], v247 offset:32768
	ds_read_b128 v[166:169], v247 offset:34816
	ds_read_b128 v[170:173], v248 offset:32768
	ds_read_b128 v[174:177], v248 offset:34816
	ds_read_b128 v[178:181], v247 offset:36864
	ds_read_b128 v[182:185], v247 offset:38912
	ds_read_b128 v[186:189], v248 offset:36864
	ds_read_b128 v[190:193], v248 offset:38912
	buffer_load_dwordx4 v230, s[8:11], s33 offen lds
	s_mov_b32 m0, s50
	s_nop 0
	buffer_load_dwordx4 v233, s[8:11], s33 offen lds
	s_waitcnt vmcnt(8)
	s_waitcnt lgkmcnt(0)
	s_barrier
	s_waitcnt lgkmcnt(7)
	v_mfma_f32_16x16x32_bf16 v[74:77], v[130:133], v[162:165], v[74:77]
	v_mfma_f32_16x16x32_bf16 v[70:73], v[138:141], v[162:165], v[70:73]
	s_waitcnt lgkmcnt(6)
	v_mfma_f32_16x16x32_bf16 v[66:69], v[130:133], v[166:169], v[66:69]
	v_mfma_f32_16x16x32_bf16 v[82:85], v[138:141], v[166:169], v[82:85]
	s_waitcnt lgkmcnt(3)
	v_mfma_f32_16x16x32_bf16 v[78:81], v[130:133], v[178:181], v[78:81]
	v_mfma_f32_16x16x32_bf16 v[90:93], v[138:141], v[178:181], v[90:93]
	s_waitcnt lgkmcnt(2)
	v_mfma_f32_16x16x32_bf16 v[86:89], v[130:133], v[182:185], v[86:89]
	v_mfma_f32_16x16x32_bf16 v[102:105], v[138:141], v[182:185], v[102:105]
	v_mfma_f32_16x16x32_bf16 v[74:77], v[134:137], v[170:173], v[74:77]
	v_mfma_f32_16x16x32_bf16 v[70:73], v[142:145], v[170:173], v[70:73]
	v_mfma_f32_16x16x32_bf16 v[66:69], v[134:137], v[174:177], v[66:69]
	v_mfma_f32_16x16x32_bf16 v[82:85], v[142:145], v[174:177], v[82:85]
	s_waitcnt lgkmcnt(1)
	v_mfma_f32_16x16x32_bf16 v[78:81], v[134:137], v[186:189], v[78:81]
	v_mfma_f32_16x16x32_bf16 v[90:93], v[142:145], v[186:189], v[90:93]
	s_waitcnt lgkmcnt(0)
	v_mfma_f32_16x16x32_bf16 v[86:89], v[134:137], v[190:193], v[86:89]
	v_mfma_f32_16x16x32_bf16 v[102:105], v[142:145], v[190:193], v[102:105]
	v_mfma_f32_16x16x32_bf16 v[98:101], v[146:149], v[162:165], v[98:101]
	v_mfma_f32_16x16x32_bf16 v[94:97], v[154:157], v[162:165], v[94:97]
	v_mfma_f32_16x16x32_bf16 v[106:109], v[146:149], v[166:169], v[106:109]
	v_mfma_f32_16x16x32_bf16 v[110:113], v[154:157], v[166:169], v[110:113]
	v_mfma_f32_16x16x32_bf16 v[114:117], v[146:149], v[178:181], v[114:117]
	v_mfma_f32_16x16x32_bf16 v[118:121], v[154:157], v[178:181], v[118:121]
	v_mfma_f32_16x16x32_bf16 v[122:125], v[146:149], v[182:185], v[122:125]
	v_mfma_f32_16x16x32_bf16 v[126:129], v[154:157], v[182:185], v[126:129]
	v_mfma_f32_16x16x32_bf16 v[98:101], v[150:153], v[170:173], v[98:101]
	v_mfma_f32_16x16x32_bf16 v[94:97], v[158:161], v[170:173], v[94:97]
	v_mfma_f32_16x16x32_bf16 v[106:109], v[150:153], v[174:177], v[106:109]
	v_mfma_f32_16x16x32_bf16 v[110:113], v[158:161], v[174:177], v[110:113]
	v_mfma_f32_16x16x32_bf16 v[114:117], v[150:153], v[186:189], v[114:117]
	v_mfma_f32_16x16x32_bf16 v[118:121], v[158:161], v[186:189], v[118:121]
	v_mfma_f32_16x16x32_bf16 v[122:125], v[150:153], v[190:193], v[122:125]
	v_mfma_f32_16x16x32_bf16 v[126:129], v[158:161], v[190:193], v[126:129]
	s_barrier
	s_mov_b32 m0, s53
	s_add_i32 s33, s31, 0x80
	ds_read_b128 v[162:165], v247 offset:49152
	ds_read_b128 v[166:169], v247 offset:51200
	ds_read_b128 v[170:173], v248 offset:49152
	ds_read_b128 v[174:177], v248 offset:51200
	ds_read_b128 v[178:181], v247 offset:53248
	ds_read_b128 v[182:185], v247 offset:55296
	ds_read_b128 v[186:189], v248 offset:53248
	ds_read_b128 v[190:193], v248 offset:55296
	buffer_load_dwordx4 v231, s[8:11], s33 offen lds
	s_mov_b32 m0, s54
	s_add_i32 s31, s31, 0x100080
	buffer_load_dwordx4 v234, s[8:11], s33 offen lds
	s_mov_b32 m0, s57
	s_nop 0
	buffer_load_dwordx4 v231, s[8:11], s31 offen lds
	s_mov_b32 m0, s58
	s_nop 0
	buffer_load_dwordx4 v234, s[8:11], s31 offen lds
	s_mov_b32 m0, s55
	s_nop 0
	buffer_load_dwordx4 v230, s[8:11], s30 offen lds
	s_mov_b32 m0, s56
	s_nop 0
	buffer_load_dwordx4 v233, s[8:11], s30 offen lds
	s_waitcnt vmcnt(8)
	s_waitcnt lgkmcnt(0)
	s_barrier
	s_waitcnt lgkmcnt(7)
	v_mfma_f32_16x16x32_bf16 v[10:13], v[130:133], v[162:165], v[10:13]
	v_mfma_f32_16x16x32_bf16 v[4:7], v[138:141], v[162:165], v[6:9]
	s_waitcnt lgkmcnt(6)
	v_mfma_f32_16x16x32_bf16 v[0:3], v[130:133], v[166:169], v[0:3]
	v_mfma_f32_16x16x32_bf16 v[18:21], v[138:141], v[166:169], v[18:21]
	s_waitcnt lgkmcnt(3)
	v_mfma_f32_16x16x32_bf16 v[14:17], v[130:133], v[178:181], v[14:17]
	v_mfma_f32_16x16x32_bf16 v[26:29], v[138:141], v[178:181], v[26:29]
	s_waitcnt lgkmcnt(2)
	v_mfma_f32_16x16x32_bf16 v[22:25], v[130:133], v[182:185], v[22:25]
	v_mfma_f32_16x16x32_bf16 v[38:41], v[138:141], v[182:185], v[38:41]
	v_mfma_f32_16x16x32_bf16 v[10:13], v[134:137], v[170:173], v[10:13]
	v_mfma_f32_16x16x32_bf16 v[6:9], v[142:145], v[170:173], v[4:7]
	v_mfma_f32_16x16x32_bf16 v[2:5], v[134:137], v[174:177], v[0:3]
	v_mfma_f32_16x16x32_bf16 v[18:21], v[142:145], v[174:177], v[18:21]
	s_waitcnt lgkmcnt(1)
	v_mfma_f32_16x16x32_bf16 v[14:17], v[134:137], v[186:189], v[14:17]
	v_mfma_f32_16x16x32_bf16 v[26:29], v[142:145], v[186:189], v[26:29]
	s_waitcnt lgkmcnt(0)
	v_mfma_f32_16x16x32_bf16 v[22:25], v[134:137], v[190:193], v[22:25]
	v_mfma_f32_16x16x32_bf16 v[38:41], v[142:145], v[190:193], v[38:41]
	v_mfma_f32_16x16x32_bf16 v[34:37], v[146:149], v[162:165], v[34:37]
	v_mfma_f32_16x16x32_bf16 v[30:33], v[154:157], v[162:165], v[30:33]
	v_mfma_f32_16x16x32_bf16 v[42:45], v[146:149], v[166:169], v[42:45]
	v_mfma_f32_16x16x32_bf16 v[46:49], v[154:157], v[166:169], v[46:49]
	v_mfma_f32_16x16x32_bf16 v[50:53], v[146:149], v[178:181], v[50:53]
	v_mfma_f32_16x16x32_bf16 v[54:57], v[154:157], v[178:181], v[54:57]
	v_mfma_f32_16x16x32_bf16 v[58:61], v[146:149], v[182:185], v[58:61]
	v_mfma_f32_16x16x32_bf16 v[62:65], v[154:157], v[182:185], v[62:65]
	v_mfma_f32_16x16x32_bf16 v[34:37], v[150:153], v[170:173], v[34:37]
	v_mfma_f32_16x16x32_bf16 v[30:33], v[158:161], v[170:173], v[30:33]
	v_mfma_f32_16x16x32_bf16 v[42:45], v[150:153], v[174:177], v[42:45]
	v_mfma_f32_16x16x32_bf16 v[46:49], v[158:161], v[174:177], v[46:49]
	v_mfma_f32_16x16x32_bf16 v[50:53], v[150:153], v[186:189], v[50:53]
	v_mfma_f32_16x16x32_bf16 v[54:57], v[158:161], v[186:189], v[54:57]
	v_mfma_f32_16x16x32_bf16 v[58:61], v[150:153], v[190:193], v[58:61]
	v_mfma_f32_16x16x32_bf16 v[62:65], v[158:161], v[190:193], v[62:65]
	s_barrier
	s_add_i32 s4, s4, 2
	s_addk_i32 s5, 0x100
	s_cmp_gt_u32 s4, 61
	s_cbranch_scc0 .LBB0_1251
	s_and_b64 vcc, exec, s[18:19]
	s_cbranch_vccz .LBB0_1254
	s_barrier
